# packed f32 VALU ops (v_pk_mul/v_pk_fma) of every GEMM epilogue split into scalar v_mul/v_fma pairs
# baseline (speedup 1.0000x reference)
;     __device__ __forceinline__ void operator()(const f32x4 (&acc)[2][2][4][2], const pg8::Unit& u, int wr, int wc, int fr, int fq) const {
;         const bool lat = u.pm < 128; const int ms = lat ? (u.pm >> 5) : 4;
;         const size_t toff = (size_t)(lat ? u.pm : u.pm - 128) * 256 * DM;
;         const float* base = (lat ? bl : bc) + toff; float* out = (lat ? ol : oc) + toff;
;         const float* g = gate + ms * NMOD; const int col0 = u.pn * 256 + wc * 32 + 4 * fq;
; #pragma unroll
;         for (int bj = 0; bj < 2; ++bj)
; #pragma unroll
;             for (int n = 0; n < 2; ++n) {
;                 const f32x4 gv = *(const f32x4*)(g + col0 + bj * 128 + n * 16) * gs;
;                 f32x4 b[8];
; #pragma unroll
;                 for (int i = 0; i < 8; ++i) b[i] = *(const f32x4*)(base + (size_t)((i >> 2) * 128 + wr * 64 + (i & 3) * 16 + fr) * DM + col0 + bj * 128 + n * 16);
; #pragma unroll
;                 for (int i = 0; i < 8; ++i) *(f32x4*)(out + (size_t)((i >> 2) * 128 + wr * 64 + (i & 3) * 16 + fr) * DM + col0 + bj * 128 + n * 16) = b[i] + gv * acc[i >> 2][bj][i & 3][n];
;                 asm volatile("" ::: "memory");
;             }
.LBB0_483:
	s_cmpk_lt_i32 s72, 0x80
	s_cselect_b32 s19, s61, s57
	s_cselect_b32 s18, s60, s56
	s_cselect_b32 s48, s85, s87
	s_cselect_b32 s49, s84, s86
	s_add_i32 s4, s72, 0xffffff80
	s_cmpk_lt_i32 s72, 0x80
	s_cselect_b32 s4, s72, s4
	s_lshr_b32 s5, s72, 5
	s_cmpk_lt_i32 s72, 0x80
	s_mulk_i32 s5, 0x2400
	s_cselect_b32 s6, s5, 0x9000
	s_ashr_i32 s5, s4, 31
	s_ashr_i32 s7, s6, 31
	s_lshl_b64 s[4:5], s[4:5], 20
	s_add_u32 s18, s18, s4
	s_addc_u32 s19, s19, s5
	s_add_u32 s4, s49, s4
	s_addc_u32 s5, s48, s5
	s_lshl_b64 s[6:7], s[6:7], 2
	v_lshl_or_b32 v154, s64, 8, v172
	s_add_u32 s6, s24, s6
	v_ashrrev_i32_e32 v155, 31, v154
	s_addc_u32 s7, s25, s7
	v_lshlrev_b64 v[156:157], 2, v[154:155]
	v_lshl_add_u64 v[154:155], s[6:7], 0, v[156:157]
	v_lshl_add_u64 v[170:171], s[18:19], 0, v[156:157]
	v_lshl_add_u64 v[212:213], s[4:5], 0, v[156:157]
	global_load_dwordx4 v[174:177], v[154:155], off
	v_lshl_add_u64 v[156:157], v[170:171], 0, v[134:135]
	global_load_dwordx4 v[178:181], v[156:157], off
	v_lshl_add_u64 v[158:159], v[170:171], 0, v[136:137]
	global_load_dwordx4 v[182:185], v[158:159], off
	v_lshl_add_u64 v[160:161], v[170:171], 0, v[138:139]
	global_load_dwordx4 v[186:189], v[160:161], off
	v_lshl_add_u64 v[162:163], v[170:171], 0, v[140:141]
	global_load_dwordx4 v[194:197], v[162:163], off
	v_lshl_add_u64 v[164:165], v[170:171], 0, v[142:143]
	global_load_dwordx4 v[198:201], v[164:165], off
	v_lshl_add_u64 v[166:167], v[170:171], 0, v[144:145]
	global_load_dwordx4 v[202:205], v[166:167], off
	v_lshl_add_u64 v[168:169], v[170:171], 0, v[146:147]
	global_load_dwordx4 v[220:223], v[168:169], off
	v_lshl_add_u64 v[170:171], v[170:171], 0, v[148:149]
	global_load_dwordx4 v[224:227], v[170:171], off
	s_mov_b64 s[4:5], -1
	s_and_b64 vcc, exec, s[38:39]
	s_waitcnt vmcnt(0)
	v_mul_f32_e32 v214, 0.5, v176
	v_mul_f32_e32 v215, 0.5, v177
	v_mul_f32_e32 v228, 0.5, v174
	v_mul_f32_e32 v229, 0.5, v175
	v_fma_f32 v176, v128, v214, v180
	v_fma_f32 v177, v129, v215, v181
	v_fma_f32 v174, v126, v228, v178
	v_fma_f32 v175, v127, v229, v179
	v_lshl_add_u64 v[126:127], v[212:213], 0, v[134:135]
	global_store_dwordx4 v[126:127], v[174:177], off
	s_nop 1
	v_fma_f32 v176, v124, v214, v184
	v_fma_f32 v177, v125, v215, v185
	v_fma_f32 v174, v122, v228, v182
	v_fma_f32 v175, v123, v229, v183
	v_lshl_add_u64 v[122:123], v[212:213], 0, v[136:137]
	global_store_dwordx4 v[122:123], v[174:177], off
	s_nop 1
	v_fma_f32 v176, v120, v214, v188
	v_fma_f32 v177, v121, v215, v189
	v_fma_f32 v174, v118, v228, v186
	v_fma_f32 v175, v119, v229, v187
	v_lshl_add_u64 v[118:119], v[212:213], 0, v[138:139]
	global_store_dwordx4 v[118:119], v[174:177], off
	s_nop 1
	v_fma_f32 v176, v116, v214, v196
	v_fma_f32 v177, v117, v215, v197
	v_fma_f32 v174, v114, v228, v194
	v_fma_f32 v175, v115, v229, v195
	v_lshl_add_u64 v[114:115], v[212:213], 0, v[140:141]
	global_store_dwordx4 v[114:115], v[174:177], off
	s_nop 1
	v_fma_f32 v176, v112, v214, v200
	v_fma_f32 v177, v113, v215, v201
	v_fma_f32 v174, v110, v228, v198
	v_fma_f32 v175, v111, v229, v199
	v_lshl_add_u64 v[110:111], v[212:213], 0, v[142:143]
	global_store_dwordx4 v[110:111], v[174:177], off
	s_nop 1
	v_fma_f32 v176, v108, v214, v204
	v_fma_f32 v177, v109, v215, v205
	v_fma_f32 v174, v106, v228, v202
	v_fma_f32 v175, v107, v229, v203
	v_lshl_add_u64 v[106:107], v[212:213], 0, v[144:145]
	global_store_dwordx4 v[106:107], v[174:177], off
	s_nop 1
	v_fma_f32 v176, v104, v214, v222
	v_fma_f32 v177, v105, v215, v223
	v_fma_f32 v174, v102, v228, v220
	v_fma_f32 v175, v103, v229, v221
	v_lshl_add_u64 v[102:103], v[212:213], 0, v[146:147]
	global_store_dwordx4 v[102:103], v[174:177], off
	s_nop 1
	v_fma_f32 v176, v100, v214, v226
	v_fma_f32 v177, v101, v215, v227
	v_fma_f32 v174, v98, v228, v224
	v_fma_f32 v175, v99, v229, v225
	v_lshl_add_u64 v[98:99], v[212:213], 0, v[148:149]
	global_store_dwordx4 v[98:99], v[174:177], off
	global_load_dwordx4 v[174:177], v[154:155], off offset:64
	global_load_dwordx4 v[178:181], v[156:157], off offset:64
	global_load_dwordx4 v[182:185], v[158:159], off offset:64
	global_load_dwordx4 v[186:189], v[160:161], off offset:64
	global_load_dwordx4 v[194:197], v[162:163], off offset:64
	global_load_dwordx4 v[198:201], v[164:165], off offset:64
	global_load_dwordx4 v[202:205], v[166:167], off offset:64
	global_load_dwordx4 v[220:223], v[168:169], off offset:64
	global_load_dwordx4 v[224:227], v[170:171], off offset:64
	s_waitcnt vmcnt(8)
	v_mul_f32_e32 v100, 0.5, v176
	v_mul_f32_e32 v101, 0.5, v177
	v_mul_f32_e32 v104, 0.5, v174
	v_mul_f32_e32 v105, 0.5, v175
	s_waitcnt vmcnt(7)
	v_fma_f32 v96, v96, v100, v180
	v_fma_f32 v97, v97, v101, v181
	v_fma_f32 v94, v94, v104, v178
	v_fma_f32 v95, v95, v105, v179
	s_waitcnt vmcnt(6)
	v_fma_f32 v92, v92, v100, v184
	v_fma_f32 v93, v93, v101, v185
	v_fma_f32 v90, v90, v104, v182
	v_fma_f32 v91, v91, v105, v183
	s_waitcnt vmcnt(5)
	v_fma_f32 v88, v88, v100, v188
	v_fma_f32 v89, v89, v101, v189
	v_fma_f32 v86, v86, v104, v186
	v_fma_f32 v87, v87, v105, v187
	s_waitcnt vmcnt(4)
	v_fma_f32 v84, v84, v100, v196
	v_fma_f32 v85, v85, v101, v197
	v_fma_f32 v82, v82, v104, v194
	v_fma_f32 v83, v83, v105, v195
	s_waitcnt vmcnt(3)
	v_fma_f32 v80, v80, v100, v200
	v_fma_f32 v81, v81, v101, v201
	v_fma_f32 v78, v78, v104, v198
	v_fma_f32 v79, v79, v105, v199
	s_waitcnt vmcnt(2)
	v_fma_f32 v76, v76, v100, v204
	v_fma_f32 v77, v77, v101, v205
	v_fma_f32 v74, v74, v104, v202
	v_fma_f32 v75, v75, v105, v203
	s_waitcnt vmcnt(1)
;     __device__ __forceinline__ void operator()(const f32x4 (&acc)[2][2][4][2], const pg8::Unit& u, int wr, int wc, int fr, int fq) const {
;     ...
;         for (int bj = 0; bj < 2; ++bj)
; #pragma unroll
;             for (int n = 0; n < 2; ++n) {
;                 const f32x4 gv = *(const f32x4*)(g + col0 + bj * 128 + n * 16) * gs;
;                 f32x4 b[8];
; #pragma unroll
;                 for (int i = 0; i < 8; ++i) b[i] = *(const f32x4*)(base + (size_t)((i >> 2) * 128 + wr * 64 + (i & 3) * 16 + fr) * DM + col0 + bj * 128 + n * 16);
; #pragma unroll
;                 for (int i = 0; i < 8; ++i) *(f32x4*)(out + (size_t)((i >> 2) * 128 + wr * 64 + (i & 3) * 16 + fr) * DM + col0 + bj * 128 + n * 16) = b[i] + gv * acc[i >> 2][bj][i & 3][n];
;                 asm volatile("" ::: "memory");
;             }
	v_fma_f32 v72, v72, v100, v222
	v_fma_f32 v73, v73, v101, v223
	v_fma_f32 v70, v70, v104, v220
	v_fma_f32 v71, v71, v105, v221
	s_waitcnt vmcnt(0)
	v_fma_f32 v64, v64, v100, v226
	v_fma_f32 v65, v65, v101, v227
	v_fma_f32 v62, v62, v104, v224
	v_fma_f32 v63, v63, v105, v225
	global_store_dwordx4 v[126:127], v[94:97], off offset:64
	global_store_dwordx4 v[122:123], v[90:93], off offset:64
	global_store_dwordx4 v[118:119], v[86:89], off offset:64
	global_store_dwordx4 v[114:115], v[82:85], off offset:64
	global_store_dwordx4 v[110:111], v[78:81], off offset:64
	global_store_dwordx4 v[106:107], v[74:77], off offset:64
	global_store_dwordx4 v[102:103], v[70:73], off offset:64
	global_store_dwordx4 v[98:99], v[62:65], off offset:64
	global_load_dwordx4 v[62:65], v[154:155], off offset:512
	global_load_dwordx4 v[70:73], v[156:157], off offset:512
	global_load_dwordx4 v[74:77], v[158:159], off offset:512
	global_load_dwordx4 v[78:81], v[160:161], off offset:512
	global_load_dwordx4 v[82:85], v[162:163], off offset:512
	global_load_dwordx4 v[86:89], v[164:165], off offset:512
	global_load_dwordx4 v[90:93], v[166:167], off offset:512
	global_load_dwordx4 v[94:97], v[168:169], off offset:512
	global_load_dwordx4 v[174:177], v[170:171], off offset:512
	s_waitcnt vmcnt(8)
	v_mul_f32_e32 v100, 0.5, v64
	v_mul_f32_e32 v101, 0.5, v65
	v_mul_f32_e32 v104, 0.5, v62
	v_mul_f32_e32 v105, 0.5, v63
	s_waitcnt vmcnt(7)
	v_fma_f32 v64, v68, v100, v72
	v_fma_f32 v65, v69, v101, v73
	v_fma_f32 v62, v66, v104, v70
	v_fma_f32 v63, v67, v105, v71
	s_waitcnt vmcnt(6)
	v_fma_f32 v60, v60, v100, v76
	v_fma_f32 v61, v61, v101, v77
	v_fma_f32 v58, v58, v104, v74
	v_fma_f32 v59, v59, v105, v75
	s_waitcnt vmcnt(5)
	v_fma_f32 v56, v56, v100, v80
	v_fma_f32 v57, v57, v101, v81
	v_fma_f32 v54, v54, v104, v78
	v_fma_f32 v55, v55, v105, v79
	s_waitcnt vmcnt(4)
	v_fma_f32 v52, v52, v100, v84
	v_fma_f32 v53, v53, v101, v85
	v_fma_f32 v50, v50, v104, v82
	v_fma_f32 v51, v51, v105, v83
	s_waitcnt vmcnt(3)
	v_fma_f32 v48, v48, v100, v88
	v_fma_f32 v49, v49, v101, v89
	v_fma_f32 v46, v46, v104, v86
	v_fma_f32 v47, v47, v105, v87
	s_waitcnt vmcnt(2)
	v_fma_f32 v44, v44, v100, v92
	v_fma_f32 v45, v45, v101, v93
	v_fma_f32 v42, v42, v104, v90
	v_fma_f32 v43, v43, v105, v91
	s_waitcnt vmcnt(1)
	v_fma_f32 v36, v36, v100, v96
	v_fma_f32 v37, v37, v101, v97
	v_fma_f32 v34, v34, v104, v94
	v_fma_f32 v35, v35, v105, v95
	s_waitcnt vmcnt(0)
	v_fma_f32 v28, v28, v100, v176
	v_fma_f32 v29, v29, v101, v177
	v_fma_f32 v26, v26, v104, v174
	v_fma_f32 v27, v27, v105, v175
	global_store_dwordx4 v[126:127], v[62:65], off offset:512
	global_store_dwordx4 v[122:123], v[58:61], off offset:512
	global_store_dwordx4 v[118:119], v[54:57], off offset:512
	global_store_dwordx4 v[114:115], v[50:53], off offset:512
	global_store_dwordx4 v[110:111], v[46:49], off offset:512
	global_store_dwordx4 v[106:107], v[42:45], off offset:512
	global_store_dwordx4 v[102:103], v[34:37], off offset:512
	global_store_dwordx4 v[98:99], v[26:29], off offset:512
	global_load_dwordx4 v[26:29], v[154:155], off offset:576
	global_load_dwordx4 v[34:37], v[156:157], off offset:576
	global_load_dwordx4 v[42:45], v[158:159], off offset:576
	global_load_dwordx4 v[46:49], v[160:161], off offset:576
	global_load_dwordx4 v[50:53], v[162:163], off offset:576
	global_load_dwordx4 v[54:57], v[164:165], off offset:576
	global_load_dwordx4 v[58:61], v[166:167], off offset:576
	global_load_dwordx4 v[62:65], v[168:169], off offset:576
	global_load_dwordx4 v[66:69], v[170:171], off offset:576
	s_waitcnt vmcnt(8)
	v_mul_f32_e32 v70, 0.5, v28
	v_mul_f32_e32 v71, 0.5, v29
	v_mul_f32_e32 v72, 0.5, v26
	v_mul_f32_e32 v73, 0.5, v27
	s_waitcnt vmcnt(7)
	v_fma_f32 v28, v40, v70, v36
	v_fma_f32 v29, v41, v71, v37
	v_fma_f32 v26, v38, v72, v34
	v_fma_f32 v27, v39, v73, v35
	global_store_dwordx4 v[126:127], v[26:29], off offset:576
	s_waitcnt vmcnt(6)
	v_fma_f32 v24, v24, v70, v48
	v_fma_f32 v25, v25, v71, v49
	v_fma_f32 v22, v22, v72, v46
	v_fma_f32 v23, v23, v73, v47
	v_fma_f32 v28, v32, v70, v44
	v_fma_f32 v29, v33, v71, v45
	v_fma_f32 v26, v30, v72, v42
	v_fma_f32 v27, v31, v73, v43
	s_waitcnt vmcnt(5)
	v_fma_f32 v20, v20, v70, v52
	v_fma_f32 v21, v21, v71, v53
	v_fma_f32 v18, v18, v72, v50
	v_fma_f32 v19, v19, v73, v51
	s_waitcnt vmcnt(4)
	v_fma_f32 v16, v16, v70, v56
	v_fma_f32 v17, v17, v71, v57
	v_fma_f32 v14, v14, v72, v54
	v_fma_f32 v15, v15, v73, v55
	s_waitcnt vmcnt(3)
	v_fma_f32 v12, v12, v70, v60
	v_fma_f32 v13, v13, v71, v61
	v_fma_f32 v10, v10, v72, v58
	v_fma_f32 v11, v11, v73, v59
	s_waitcnt vmcnt(2)
	v_fma_f32 v8, v8, v70, v64
	v_fma_f32 v9, v9, v71, v65
	v_fma_f32 v6, v6, v72, v62
	v_fma_f32 v7, v7, v73, v63
	s_waitcnt vmcnt(1)
	v_fma_f32 v4, v4, v70, v68
	v_fma_f32 v5, v5, v71, v69
	v_fma_f32 v2, v2, v72, v66
	v_fma_f32 v3, v3, v73, v67
	global_store_dwordx4 v[122:123], v[26:29], off offset:576
	global_store_dwordx4 v[118:119], v[22:25], off offset:576
	global_store_dwordx4 v[114:115], v[18:21], off offset:576
	global_store_dwordx4 v[110:111], v[14:17], off offset:576
	global_store_dwordx4 v[106:107], v[10:13], off offset:576
	global_store_dwordx4 v[102:103], v[6:9], off offset:576
	global_store_dwordx4 v[98:99], v[2:5], off offset:576
	s_cbranch_vccnz .LBB0_468
	s_andn2_b64 vcc, exec, s[36:37]
	s_cbranch_vccnz .LBB0_467
	s_barrier
	s_branch .LBB0_467

; __device__ __forceinline__ unsigned pk2(float lo, float hi) { f32x2_t v = {lo, hi}; bf16x2_t b = __builtin_convertvector(v, bf16x2_t); return __builtin_bit_cast(unsigned, b); }
;     __device__ __forceinline__ void operator()(const f32x4 (&acc)[2][2][4][2], const pg8::Unit& u, int wr, int wc, int fr, int fq) const {
;     ...
;             for (int m = 0; m < 4; ++m) {
;                 const int row = u.pm * 256 + ai * 128 + wr * 64 + m * 16 + fr;
;                 const bool lat = row < TL; const int t = row & (SEQ - 1), pr = t >> 6, pc = t & 63;
; #pragma unroll
;                 for (int bj = 0; bj < 2; ++bj) {
;                     const int cg = (u.pn * 256 + bj * 128 + wc * 32) >> 5;
;                     f32x4 v0 = acc[ai][bj][m][0], v1 = acc[ai][bj][m][1];
;                     bool r16 = false, r8 = false; float sc = 1.f;
;                     if (IS_UQ) { r8 = (cg % 3) == 2; sc = MLA_C2; }
;                     else { r16 = cg < 32; r8 = cg == 84; if (cg >= 16 && cg < 32) sc = 0.125f; }
;                     if (r16 && lat) {
;                         const int pos = (cg & 1) ? pc : pr;
;                         const f32x4 cs = *(const f32x4*)(rt16c + pos * 16 + 4 * fq), sn = *(const f32x4*)(rt16s + pos * 16 + 4 * fq);
;                         const f32x4 o0 = v0 * cs - v1 * sn, o1 = v1 * cs + v0 * sn; v0 = o0; v1 = o1;
;                     }
;                     if (r8 && lat) {
;                         const int pos = (fq >> 1) ? pc : pr;
;                         const f32x4 cs = *(const f32x4*)(rt8c + pos * 8 + 4 * (fq & 1)), sn = *(const f32x4*)(rt8s + pos * 8 + 4 * (fq & 1));
;                         const f32x4 o0 = v0 * cs - v1 * sn, o1 = v1 * cs + v0 * sn; v0 = o0; v1 = o1;
;                     }
;                     v0 = v0 * sc; v1 = v1 * sc;
;                     u32x4 w; w.x = pk2(v0[0], v0[1]); w.y = pk2(v0[2], v0[3]); w.z = pk2(v1[0], v1[1]); w.w = pk2(v1[2], v1[3]);
;                     *(u32x4*)(O + (size_t)row * LDC + cg * 32 + 8 * fq) = w;
.LBB0_623:
	s_lshl_b32 s6, s78, 8
	s_add_i32 s6, s6, s26
	s_lshl_b32 s4, s44, 8
	s_bfe_u32 s7, s6, 0x70006
	s_or_b32 s78, s4, s27
	v_mov_b32_e32 v152, s7
	v_or_b32_e32 v0, s6, v139
	v_cndmask_b32_e64 v152, v139, v152, s[38:39]
	s_cmpk_lt_i32 s78, 0x400
	v_cmp_gt_i32_e32 vcc, s91, v0
	v_lshlrev_b32_e32 v152, 4, v152
	s_cselect_b64 s[94:95], -1, 0
	s_and_b64 s[18:19], s[94:95], vcc
	v_lshlrev_b32_e32 v154, 2, v152
	s_and_saveexec_b64 s[4:5], s[18:19]
	s_mov_b32 s64, s11
	s_cbranch_execz .LBB0_625
	v_mov_b32_e32 v155, v1
	v_lshl_add_u64 v[152:153], v[142:143], 0, v[154:155]
	global_load_dwordx4 v[162:165], v[152:153], off
	v_lshl_add_u64 v[152:153], v[140:141], 0, v[154:155]
	global_load_dwordx4 v[166:169], v[152:153], off
	s_waitcnt vmcnt(0)
	v_mul_f32_e32 v152, v124, v164
	v_mul_f32_e32 v153, v125, v165
	v_mul_f32_e32 v170, v122, v162
	v_mul_f32_e32 v171, v123, v163
	v_mul_f32_e32 v164, v128, v164
	v_mul_f32_e32 v165, v129, v165
	v_mul_f32_e32 v162, v126, v162
	v_mul_f32_e32 v163, v127, v163
	v_fma_f32 v128, v128, v168, -v152
	v_fma_f32 v129, v129, v169, -v153
	v_fma_f32 v126, v126, v166, -v170
	v_fma_f32 v127, v127, v167, -v171
	v_fma_f32 v124, v124, v168, v164
	v_fma_f32 v125, v125, v169, v165
	v_fma_f32 v122, v122, v166, v162
	v_fma_f32 v123, v123, v167, v163
.LBB0_625:
	s_or_b64 exec, exec, s[4:5]
	s_and_b32 s4, s44, 0xfffffe
	s_cmp_eq_u32 s4, 2
	s_cselect_b64 s[44:45], -1, 0
	v_mov_b32_e32 v152, 0x3e000000
	v_cndmask_b32_e64 v152, 1.0, v152, s[44:45]
	v_mul_f32_e32 v126, v152, v126
	v_mul_f32_e32 v127, v152, v127
	v_mul_f32_e32 v122, v152, v122
	v_mul_f32_e32 v123, v152, v123
	v_mul_f32_e32 v162, v152, v124
	v_mul_f32_e32 v163, v152, v125
	v_cvt_pk_bf16_f32 v124, v126, v127
	v_cvt_pk_bf16_f32 v126, v122, v123
	v_mov_b64_e32 v[122:123], s[30:31]
	v_mad_i64_i32 v[122:123], s[4:5], v0, s16, v[122:123]
	s_ashr_i32 s79, s78, 31
	s_or_b32 s4, s78, 0x80
	s_cmpk_lt_i32 s4, 0x400
	v_mul_f32_e32 v128, v152, v128
	v_mul_f32_e32 v129, v152, v129
	v_lshl_add_u64 v[122:123], s[78:79], 1, v[122:123]
	v_lshlrev_b32_e32 v0, 1, v138
	s_cselect_b64 s[44:45], -1, 0
	v_cvt_pk_bf16_f32 v125, v128, v129
	v_cvt_pk_bf16_f32 v127, v162, v163
	v_lshl_add_u64 v[122:123], v[122:123], 0, v[0:1]
	s_and_b64 s[18:19], s[44:45], vcc
	global_store_dwordx4 v[122:123], v[124:127], off
	s_and_saveexec_b64 s[4:5], s[18:19]
	s_cbranch_execz .LBB0_627
	v_mov_b32_e32 v155, v1
	v_lshl_add_u64 v[124:125], v[142:143], 0, v[154:155]
	global_load_dwordx4 v[124:127], v[124:125], off
	v_lshl_add_u64 v[128:129], v[140:141], 0, v[154:155]
	global_load_dwordx4 v[162:165], v[128:129], off
	s_waitcnt vmcnt(0)
	v_mul_f32_e32 v128, v116, v126
	v_mul_f32_e32 v129, v117, v127
	v_mul_f32_e32 v154, v114, v124
	v_mul_f32_e32 v155, v115, v125
	v_mul_f32_e32 v126, v120, v126
	v_mul_f32_e32 v127, v121, v127
	v_mul_f32_e32 v124, v118, v124
	v_mul_f32_e32 v125, v119, v125
	v_fma_f32 v120, v120, v164, -v128
	v_fma_f32 v121, v121, v165, -v129
	v_fma_f32 v118, v118, v162, -v154
	v_fma_f32 v119, v119, v163, -v155
	v_fma_f32 v116, v116, v164, v126
	v_fma_f32 v117, v117, v165, v127
	v_fma_f32 v114, v114, v162, v124
	v_fma_f32 v115, v115, v163, v125
.LBB0_627:
	s_or_b64 exec, exec, s[4:5]
	s_cmpk_eq_i32 s78, 0xa00
	s_cselect_b64 s[48:49], -1, 0
	s_and_b64 s[18:19], s[48:49], vcc
	s_and_saveexec_b64 s[4:5], s[18:19]
	s_cbranch_execz .LBB0_629
	v_mov_b32_e32 v124, s7
	v_cndmask_b32_e64 v124, v139, v124, s[40:41]
	v_lshlrev_b32_e32 v128, 5, v124
	v_mov_b32_e32 v129, v1
	v_lshl_add_u64 v[124:125], v[146:147], 0, v[128:129]
	global_load_dwordx4 v[124:127], v[124:125], off
	v_lshl_add_u64 v[128:129], v[144:145], 0, v[128:129]
	global_load_dwordx4 v[162:165], v[128:129], off
	s_waitcnt vmcnt(0)
	v_mul_f32_e32 v128, v116, v126
	v_mul_f32_e32 v129, v117, v127
	v_mul_f32_e32 v154, v114, v124
	v_mul_f32_e32 v155, v115, v125
	v_mul_f32_e32 v126, v120, v126
	v_mul_f32_e32 v127, v121, v127
	v_mul_f32_e32 v124, v118, v124
	v_mul_f32_e32 v125, v119, v125
	v_fma_f32 v120, v120, v164, -v128
	v_fma_f32 v121, v121, v165, -v129
	v_fma_f32 v118, v118, v162, -v154
	v_fma_f32 v119, v119, v163, -v155
	v_fma_f32 v116, v116, v164, v126
	v_fma_f32 v117, v117, v165, v127
	v_fma_f32 v114, v114, v162, v124
	v_fma_f32 v115, v115, v163, v125
.LBB0_629:
	s_or_b64 exec, exec, s[4:5]
	v_mov_b32_e32 v153, v152
	v_mov_b32_e32 v124, v152
	v_mov_b32_e32 v125, v152
	v_mul_f32_e32 v120, v124, v120
	v_mul_f32_e32 v121, v125, v121
	v_mul_f32_e32 v118, v152, v118
	v_mul_f32_e32 v119, v153, v119
	v_mul_f32_e32 v126, v124, v116
	v_mul_f32_e32 v127, v125, v117
	v_mul_f32_e32 v116, v152, v114
	v_mul_f32_e32 v117, v153, v115
	v_cvt_pk_bf16_f32 v114, v118, v119
	v_cvt_pk_bf16_f32 v115, v120, v121
	v_cvt_pk_bf16_f32 v116, v116, v117
	v_cvt_pk_bf16_f32 v117, v126, v127
	global_store_dwordx4 v[122:123], v[114:117], off offset:256
	v_or_b32_e32 v118, s6, v157
	v_cmp_gt_i32_e32 vcc, s91, v118
	v_mov_b32_e32 v114, s7
	v_cndmask_b32_e64 v114, v157, v114, s[38:39]
	v_lshlrev_b32_e32 v114, 4, v114
	v_mov_b32_e32 v115, v1
	v_lshlrev_b64 v[116:117], 2, v[114:115]
	s_and_b64 s[18:19], s[94:95], vcc
	v_lshl_add_u64 v[114:115], v[140:141], 0, v[116:117]
	v_lshl_add_u64 v[116:117], v[142:143], 0, v[116:117]
	s_and_saveexec_b64 s[4:5], s[18:19]
	s_cbranch_execz .LBB0_631
	global_load_dwordx4 v[120:123], v[116:117], off
	global_load_dwordx4 v[126:129], v[114:115], off
	s_waitcnt vmcnt(0)
	v_mul_f32_e32 v154, v108, v122
	v_mul_f32_e32 v155, v109, v123
	v_mul_f32_e32 v162, v106, v120
	v_mul_f32_e32 v163, v107, v121
	v_mul_f32_e32 v122, v112, v122
	v_mul_f32_e32 v123, v113, v123
	v_mul_f32_e32 v120, v110, v120
	v_mul_f32_e32 v121, v111, v121
	v_fma_f32 v112, v112, v128, -v154
	v_fma_f32 v113, v113, v129, -v155
	v_fma_f32 v110, v110, v126, -v162
	v_fma_f32 v111, v111, v127, -v163
	v_fma_f32 v108, v108, v128, v122
	v_fma_f32 v109, v109, v129, v123
	v_fma_f32 v106, v106, v126, v120
	v_fma_f32 v107, v107, v127, v121
; __device__ __forceinline__ unsigned pk2(float lo, float hi) { f32x2_t v = {lo, hi}; bf16x2_t b = __builtin_convertvector(v, bf16x2_t); return __builtin_bit_cast(unsigned, b); }
;     __device__ __forceinline__ void operator()(const f32x4 (&acc)[2][2][4][2], const pg8::Unit& u, int wr, int wc, int fr, int fq) const {
;     ...
;                 for (int bj = 0; bj < 2; ++bj) {
;                     const int cg = (u.pn * 256 + bj * 128 + wc * 32) >> 5;
;                     f32x4 v0 = acc[ai][bj][m][0], v1 = acc[ai][bj][m][1];
;                     bool r16 = false, r8 = false; float sc = 1.f;
;                     if (IS_UQ) { r8 = (cg % 3) == 2; sc = MLA_C2; }
;                     else { r16 = cg < 32; r8 = cg == 84; if (cg >= 16 && cg < 32) sc = 0.125f; }
;                     if (r16 && lat) {
;                         const int pos = (cg & 1) ? pc : pr;
;                         const f32x4 cs = *(const f32x4*)(rt16c + pos * 16 + 4 * fq), sn = *(const f32x4*)(rt16s + pos * 16 + 4 * fq);
;                         const f32x4 o0 = v0 * cs - v1 * sn, o1 = v1 * cs + v0 * sn; v0 = o0; v1 = o1;
;                     }
;                     if (r8 && lat) {
;                         const int pos = (fq >> 1) ? pc : pr;
;                         const f32x4 cs = *(const f32x4*)(rt8c + pos * 8 + 4 * (fq & 1)), sn = *(const f32x4*)(rt8s + pos * 8 + 4 * (fq & 1));
;                         const f32x4 o0 = v0 * cs - v1 * sn, o1 = v1 * cs + v0 * sn; v0 = o0; v1 = o1;
;                     }
;                     v0 = v0 * sc; v1 = v1 * sc;
;                     u32x4 w; w.x = pk2(v0[0], v0[1]); w.y = pk2(v0[2], v0[3]); w.z = pk2(v1[0], v1[1]); w.w = pk2(v1[2], v1[3]);
;                     *(u32x4*)(O + (size_t)row * LDC + cg * 32 + 8 * fq) = w;
.LBB0_631:
	s_or_b64 exec, exec, s[4:5]
	v_mul_f32_e32 v110, v152, v110
	v_mul_f32_e32 v111, v153, v111
	v_mul_f32_e32 v106, v152, v106
	v_mul_f32_e32 v107, v153, v107
	v_mul_f32_e32 v120, v124, v108
	v_mul_f32_e32 v121, v125, v109
	v_cvt_pk_bf16_f32 v108, v110, v111
	v_cvt_pk_bf16_f32 v110, v106, v107
	v_mov_b64_e32 v[106:107], s[30:31]
	v_mad_i64_i32 v[106:107], s[4:5], v118, s16, v[106:107]
	v_mul_f32_e32 v112, v124, v112
	v_mul_f32_e32 v113, v125, v113
	v_lshl_add_u64 v[106:107], s[78:79], 1, v[106:107]
	v_cvt_pk_bf16_f32 v109, v112, v113
	v_cvt_pk_bf16_f32 v111, v120, v121
	v_lshl_add_u64 v[106:107], v[106:107], 0, v[0:1]
	s_and_b64 s[18:19], s[44:45], vcc
	global_store_dwordx4 v[106:107], v[108:111], off
	s_and_saveexec_b64 s[4:5], s[18:19]
	s_cbranch_execz .LBB0_633
	global_load_dwordx4 v[108:111], v[116:117], off
	s_nop 0
	global_load_dwordx4 v[112:115], v[114:115], off
	s_waitcnt vmcnt(0)
	v_mul_f32_e32 v116, v100, v110
	v_mul_f32_e32 v117, v101, v111
	v_mul_f32_e32 v118, v98, v108
	v_mul_f32_e32 v119, v99, v109
	v_mul_f32_e32 v110, v104, v110
	v_mul_f32_e32 v111, v105, v111
	v_mul_f32_e32 v108, v102, v108
	v_mul_f32_e32 v109, v103, v109
	v_fma_f32 v104, v104, v114, -v116
	v_fma_f32 v105, v105, v115, -v117
	v_fma_f32 v102, v102, v112, -v118
	v_fma_f32 v103, v103, v113, -v119
	v_fma_f32 v100, v100, v114, v110
	v_fma_f32 v101, v101, v115, v111
	v_fma_f32 v98, v98, v112, v108
	v_fma_f32 v99, v99, v113, v109
.LBB0_633:
	s_or_b64 exec, exec, s[4:5]
	s_and_b64 s[18:19], s[48:49], vcc
	s_and_saveexec_b64 s[4:5], s[18:19]
	s_cbranch_execz .LBB0_635
	v_mov_b32_e32 v108, s7
	v_cndmask_b32_e64 v108, v157, v108, s[40:41]
	v_lshlrev_b32_e32 v112, 5, v108
	v_mov_b32_e32 v113, v1
	v_lshl_add_u64 v[108:109], v[146:147], 0, v[112:113]
	global_load_dwordx4 v[108:111], v[108:109], off
	v_lshl_add_u64 v[112:113], v[144:145], 0, v[112:113]
	global_load_dwordx4 v[112:115], v[112:113], off
	s_waitcnt vmcnt(0)
	v_mul_f32_e32 v116, v100, v110
	v_mul_f32_e32 v117, v101, v111
	v_mul_f32_e32 v118, v98, v108
	v_mul_f32_e32 v119, v99, v109
	v_mul_f32_e32 v110, v104, v110
	v_mul_f32_e32 v111, v105, v111
	v_mul_f32_e32 v108, v102, v108
	v_mul_f32_e32 v109, v103, v109
	v_fma_f32 v104, v104, v114, -v116
	v_fma_f32 v105, v105, v115, -v117
	v_fma_f32 v102, v102, v112, -v118
	v_fma_f32 v103, v103, v113, -v119
	v_fma_f32 v100, v100, v114, v110
	v_fma_f32 v101, v101, v115, v111
	v_fma_f32 v98, v98, v112, v108
	v_fma_f32 v99, v99, v113, v109
.LBB0_635:
	s_or_b64 exec, exec, s[4:5]
	v_mov_b32_e32 v108, v152
	v_mov_b32_e32 v109, v152
	v_mul_f32_e32 v104, v108, v104
	v_mul_f32_e32 v105, v109, v105
	v_mul_f32_e32 v102, v152, v102
	v_mul_f32_e32 v103, v153, v103
	v_mul_f32_e32 v110, v108, v100
	v_mul_f32_e32 v111, v109, v101
	v_mul_f32_e32 v100, v152, v98
	v_mul_f32_e32 v101, v153, v99
	v_cvt_pk_bf16_f32 v98, v102, v103
	v_cvt_pk_bf16_f32 v99, v104, v105
	v_cvt_pk_bf16_f32 v100, v100, v101
	v_cvt_pk_bf16_f32 v101, v110, v111
	global_store_dwordx4 v[106:107], v[98:101], off offset:256
	v_or_b32_e32 v102, s6, v158
	v_cmp_gt_i32_e32 vcc, s91, v102
	v_mov_b32_e32 v98, s7
	v_cndmask_b32_e64 v98, v158, v98, s[38:39]
	v_lshlrev_b32_e32 v98, 4, v98
	v_mov_b32_e32 v99, v1
	v_lshlrev_b64 v[100:101], 2, v[98:99]
	s_and_b64 s[18:19], s[94:95], vcc
	v_lshl_add_u64 v[98:99], v[140:141], 0, v[100:101]
	v_lshl_add_u64 v[100:101], v[142:143], 0, v[100:101]
	s_and_saveexec_b64 s[4:5], s[18:19]
	s_cbranch_execz .LBB0_637
	global_load_dwordx4 v[104:107], v[100:101], off
	global_load_dwordx4 v[110:113], v[98:99], off
	s_waitcnt vmcnt(0)
	v_mul_f32_e32 v114, v92, v106
	v_mul_f32_e32 v115, v93, v107
	v_mul_f32_e32 v116, v90, v104
	v_mul_f32_e32 v117, v91, v105
	v_mul_f32_e32 v106, v96, v106
	v_mul_f32_e32 v107, v97, v107
	v_mul_f32_e32 v104, v94, v104
	v_mul_f32_e32 v105, v95, v105
	v_fma_f32 v96, v96, v112, -v114
	v_fma_f32 v97, v97, v113, -v115
	v_fma_f32 v94, v94, v110, -v116
	v_fma_f32 v95, v95, v111, -v117
	v_fma_f32 v92, v92, v112, v106
	v_fma_f32 v93, v93, v113, v107
	v_fma_f32 v90, v90, v110, v104
	v_fma_f32 v91, v91, v111, v105
.LBB0_637:
	s_or_b64 exec, exec, s[4:5]
	v_mul_f32_e32 v94, v152, v94
	v_mul_f32_e32 v95, v153, v95
	v_mul_f32_e32 v90, v152, v90
	v_mul_f32_e32 v91, v153, v91
	v_mul_f32_e32 v104, v108, v92
	v_mul_f32_e32 v105, v109, v93
	v_cvt_pk_bf16_f32 v92, v94, v95
	v_cvt_pk_bf16_f32 v94, v90, v91
	v_mov_b64_e32 v[90:91], s[30:31]
	v_mad_i64_i32 v[90:91], s[4:5], v102, s16, v[90:91]
	v_mul_f32_e32 v96, v108, v96
	v_mul_f32_e32 v97, v109, v97
	v_lshl_add_u64 v[90:91], s[78:79], 1, v[90:91]
	v_cvt_pk_bf16_f32 v93, v96, v97
	v_cvt_pk_bf16_f32 v95, v104, v105
	v_lshl_add_u64 v[90:91], v[90:91], 0, v[0:1]
	s_and_b64 s[18:19], s[44:45], vcc
	global_store_dwordx4 v[90:91], v[92:95], off
	s_and_saveexec_b64 s[4:5], s[18:19]
	s_cbranch_execz .LBB0_639
	global_load_dwordx4 v[92:95], v[100:101], off
	s_nop 0
	global_load_dwordx4 v[96:99], v[98:99], off
	s_waitcnt vmcnt(0)
	v_mul_f32_e32 v100, v84, v94
	v_mul_f32_e32 v101, v85, v95
	v_mul_f32_e32 v102, v82, v92
	v_mul_f32_e32 v103, v83, v93
	v_mul_f32_e32 v94, v88, v94
	v_mul_f32_e32 v95, v89, v95
	v_mul_f32_e32 v92, v86, v92
	v_mul_f32_e32 v93, v87, v93
	v_fma_f32 v88, v88, v98, -v100
	v_fma_f32 v89, v89, v99, -v101
	v_fma_f32 v86, v86, v96, -v102
	v_fma_f32 v87, v87, v97, -v103
	v_fma_f32 v84, v84, v98, v94
	v_fma_f32 v85, v85, v99, v95
	v_fma_f32 v82, v82, v96, v92
	v_fma_f32 v83, v83, v97, v93
; __device__ __forceinline__ unsigned pk2(float lo, float hi) { f32x2_t v = {lo, hi}; bf16x2_t b = __builtin_convertvector(v, bf16x2_t); return __builtin_bit_cast(unsigned, b); }
;     __device__ __forceinline__ void operator()(const f32x4 (&acc)[2][2][4][2], const pg8::Unit& u, int wr, int wc, int fr, int fq) const {
;     ...
;                 const int row = u.pm * 256 + ai * 128 + wr * 64 + m * 16 + fr;
;                 const bool lat = row < TL; const int t = row & (SEQ - 1), pr = t >> 6, pc = t & 63;
; #pragma unroll
;                 for (int bj = 0; bj < 2; ++bj) {
;                     const int cg = (u.pn * 256 + bj * 128 + wc * 32) >> 5;
;                     f32x4 v0 = acc[ai][bj][m][0], v1 = acc[ai][bj][m][1];
;                     bool r16 = false, r8 = false; float sc = 1.f;
;                     if (IS_UQ) { r8 = (cg % 3) == 2; sc = MLA_C2; }
;                     else { r16 = cg < 32; r8 = cg == 84; if (cg >= 16 && cg < 32) sc = 0.125f; }
;                     if (r16 && lat) {
;                         const int pos = (cg & 1) ? pc : pr;
;                         const f32x4 cs = *(const f32x4*)(rt16c + pos * 16 + 4 * fq), sn = *(const f32x4*)(rt16s + pos * 16 + 4 * fq);
;                         const f32x4 o0 = v0 * cs - v1 * sn, o1 = v1 * cs + v0 * sn; v0 = o0; v1 = o1;
;                     }
;                     if (r8 && lat) {
;                         const int pos = (fq >> 1) ? pc : pr;
;                         const f32x4 cs = *(const f32x4*)(rt8c + pos * 8 + 4 * (fq & 1)), sn = *(const f32x4*)(rt8s + pos * 8 + 4 * (fq & 1));
;                         const f32x4 o0 = v0 * cs - v1 * sn, o1 = v1 * cs + v0 * sn; v0 = o0; v1 = o1;
;                     }
;                     v0 = v0 * sc; v1 = v1 * sc;
;                     u32x4 w; w.x = pk2(v0[0], v0[1]); w.y = pk2(v0[2], v0[3]); w.z = pk2(v1[0], v1[1]); w.w = pk2(v1[2], v1[3]);
;                     *(u32x4*)(O + (size_t)row * LDC + cg * 32 + 8 * fq) = w;
.LBB0_639:
	s_or_b64 exec, exec, s[4:5]
	s_and_b64 s[18:19], s[48:49], vcc
	s_and_saveexec_b64 s[4:5], s[18:19]
	s_cbranch_execz .LBB0_641
	v_mov_b32_e32 v92, s7
	v_cndmask_b32_e64 v92, v158, v92, s[40:41]
	v_lshlrev_b32_e32 v96, 5, v92
	v_mov_b32_e32 v97, v1
	v_lshl_add_u64 v[92:93], v[146:147], 0, v[96:97]
	global_load_dwordx4 v[92:95], v[92:93], off
	v_lshl_add_u64 v[96:97], v[144:145], 0, v[96:97]
	global_load_dwordx4 v[96:99], v[96:97], off
	s_waitcnt vmcnt(0)
	v_mul_f32_e32 v100, v84, v94
	v_mul_f32_e32 v101, v85, v95
	v_mul_f32_e32 v102, v82, v92
	v_mul_f32_e32 v103, v83, v93
	v_mul_f32_e32 v94, v88, v94
	v_mul_f32_e32 v95, v89, v95
	v_mul_f32_e32 v92, v86, v92
	v_mul_f32_e32 v93, v87, v93
	v_fma_f32 v88, v88, v98, -v100
	v_fma_f32 v89, v89, v99, -v101
	v_fma_f32 v86, v86, v96, -v102
	v_fma_f32 v87, v87, v97, -v103
	v_fma_f32 v84, v84, v98, v94
	v_fma_f32 v85, v85, v99, v95
	v_fma_f32 v82, v82, v96, v92
	v_fma_f32 v83, v83, v97, v93
.LBB0_641:
	s_or_b64 exec, exec, s[4:5]
	v_mov_b32_e32 v92, v152
	v_mov_b32_e32 v93, v152
	v_mul_f32_e32 v88, v92, v88
	v_mul_f32_e32 v89, v93, v89
	v_mul_f32_e32 v86, v152, v86
	v_mul_f32_e32 v87, v153, v87
	v_mul_f32_e32 v94, v92, v84
	v_mul_f32_e32 v95, v93, v85
	v_mul_f32_e32 v84, v152, v82
	v_mul_f32_e32 v85, v153, v83
	v_cvt_pk_bf16_f32 v82, v86, v87
	v_cvt_pk_bf16_f32 v83, v88, v89
	v_cvt_pk_bf16_f32 v84, v84, v85
	v_cvt_pk_bf16_f32 v85, v94, v95
	global_store_dwordx4 v[90:91], v[82:85], off offset:256
	v_or_b32_e32 v86, s6, v159
	v_cmp_gt_i32_e32 vcc, s91, v86
	v_mov_b32_e32 v82, s7
	v_cndmask_b32_e64 v82, v159, v82, s[38:39]
	v_lshlrev_b32_e32 v82, 4, v82
	v_mov_b32_e32 v83, v1
	v_lshlrev_b64 v[84:85], 2, v[82:83]
	s_and_b64 s[18:19], s[94:95], vcc
	v_lshl_add_u64 v[82:83], v[140:141], 0, v[84:85]
	v_lshl_add_u64 v[84:85], v[142:143], 0, v[84:85]
	s_and_saveexec_b64 s[4:5], s[18:19]
	s_cbranch_execz .LBB0_643
	global_load_dwordx4 v[88:91], v[84:85], off
	global_load_dwordx4 v[94:97], v[82:83], off
	s_waitcnt vmcnt(0)
	v_mul_f32_e32 v98, v76, v90
	v_mul_f32_e32 v99, v77, v91
	v_mul_f32_e32 v100, v74, v88
	v_mul_f32_e32 v101, v75, v89
	v_mul_f32_e32 v90, v80, v90
	v_mul_f32_e32 v91, v81, v91
	v_mul_f32_e32 v88, v78, v88
	v_mul_f32_e32 v89, v79, v89
	v_fma_f32 v80, v80, v96, -v98
	v_fma_f32 v81, v81, v97, -v99
	v_fma_f32 v78, v78, v94, -v100
	v_fma_f32 v79, v79, v95, -v101
	v_fma_f32 v76, v76, v96, v90
	v_fma_f32 v77, v77, v97, v91
	v_fma_f32 v74, v74, v94, v88
	v_fma_f32 v75, v75, v95, v89
.LBB0_643:
	s_or_b64 exec, exec, s[4:5]
	v_mul_f32_e32 v78, v152, v78
	v_mul_f32_e32 v79, v153, v79
	v_mul_f32_e32 v74, v152, v74
	v_mul_f32_e32 v75, v153, v75
	v_mul_f32_e32 v88, v92, v76
	v_mul_f32_e32 v89, v93, v77
	v_cvt_pk_bf16_f32 v76, v78, v79
	v_cvt_pk_bf16_f32 v78, v74, v75
	v_mov_b64_e32 v[74:75], s[30:31]
	v_mad_i64_i32 v[74:75], s[4:5], v86, s16, v[74:75]
	v_mul_f32_e32 v80, v92, v80
	v_mul_f32_e32 v81, v93, v81
	v_lshl_add_u64 v[74:75], s[78:79], 1, v[74:75]
	v_cvt_pk_bf16_f32 v77, v80, v81
	v_cvt_pk_bf16_f32 v79, v88, v89
	v_lshl_add_u64 v[74:75], v[74:75], 0, v[0:1]
	s_and_b64 s[18:19], s[44:45], vcc
	global_store_dwordx4 v[74:75], v[76:79], off
	s_and_saveexec_b64 s[4:5], s[18:19]
	s_cbranch_execz .LBB0_645
	global_load_dwordx4 v[76:79], v[84:85], off
	s_nop 0
	global_load_dwordx4 v[80:83], v[82:83], off
	s_waitcnt vmcnt(0)
	v_mul_f32_e32 v84, v68, v78
	v_mul_f32_e32 v85, v69, v79
	v_mul_f32_e32 v86, v66, v76
	v_mul_f32_e32 v87, v67, v77
	v_mul_f32_e32 v78, v72, v78
	v_mul_f32_e32 v79, v73, v79
	v_mul_f32_e32 v76, v70, v76
	v_mul_f32_e32 v77, v71, v77
	v_fma_f32 v72, v72, v82, -v84
	v_fma_f32 v73, v73, v83, -v85
	v_fma_f32 v70, v70, v80, -v86
	v_fma_f32 v71, v71, v81, -v87
	v_fma_f32 v68, v68, v82, v78
	v_fma_f32 v69, v69, v83, v79
	v_fma_f32 v66, v66, v80, v76
	v_fma_f32 v67, v67, v81, v77
.LBB0_645:
	s_or_b64 exec, exec, s[4:5]
	s_and_b64 s[18:19], s[48:49], vcc
	s_and_saveexec_b64 s[4:5], s[18:19]
	s_cbranch_execz .LBB0_647
	v_mov_b32_e32 v76, s7
	v_cndmask_b32_e64 v76, v159, v76, s[40:41]
	v_lshlrev_b32_e32 v80, 5, v76
	v_mov_b32_e32 v81, v1
	v_lshl_add_u64 v[76:77], v[146:147], 0, v[80:81]
	global_load_dwordx4 v[76:79], v[76:77], off
	v_lshl_add_u64 v[80:81], v[144:145], 0, v[80:81]
	global_load_dwordx4 v[80:83], v[80:81], off
	s_waitcnt vmcnt(0)
	v_mul_f32_e32 v84, v68, v78
	v_mul_f32_e32 v85, v69, v79
	v_mul_f32_e32 v86, v66, v76
	v_mul_f32_e32 v87, v67, v77
	v_mul_f32_e32 v78, v72, v78
	v_mul_f32_e32 v79, v73, v79
	v_mul_f32_e32 v76, v70, v76
	v_mul_f32_e32 v77, v71, v77
	v_fma_f32 v72, v72, v82, -v84
	v_fma_f32 v73, v73, v83, -v85
	v_fma_f32 v70, v70, v80, -v86
	v_fma_f32 v71, v71, v81, -v87
	v_fma_f32 v68, v68, v82, v78
	v_fma_f32 v69, v69, v83, v79
	v_fma_f32 v66, v66, v80, v76
	v_fma_f32 v67, v67, v81, v77
.LBB0_647:
	s_or_b64 exec, exec, s[4:5]
	v_mov_b32_e32 v76, v152
	v_mov_b32_e32 v77, v152
	v_mul_f32_e32 v72, v76, v72
	v_mul_f32_e32 v73, v77, v73
	v_mul_f32_e32 v70, v152, v70
	v_mul_f32_e32 v71, v153, v71
	v_mul_f32_e32 v78, v76, v68
	v_mul_f32_e32 v79, v77, v69
	v_mul_f32_e32 v68, v152, v66
	v_mul_f32_e32 v69, v153, v67
	s_add_i32 s7, s6, 0x80
	v_cvt_pk_bf16_f32 v66, v70, v71
	v_cvt_pk_bf16_f32 v67, v72, v73
	v_cvt_pk_bf16_f32 v68, v68, v69
	v_cvt_pk_bf16_f32 v69, v78, v79
	s_bfe_u32 s6, s7, 0x70006
	global_store_dwordx4 v[74:75], v[66:69], off offset:256
	v_or_b32_e32 v70, s7, v139
	v_cmp_gt_i32_e32 vcc, s91, v70
	v_mov_b32_e32 v66, s6
	v_cndmask_b32_e64 v66, v139, v66, s[38:39]
	v_lshlrev_b32_e32 v66, 4, v66
	v_mov_b32_e32 v67, v1
	v_lshlrev_b64 v[68:69], 2, v[66:67]
	s_and_b64 s[18:19], s[94:95], vcc
	v_lshl_add_u64 v[66:67], v[140:141], 0, v[68:69]
	v_lshl_add_u64 v[68:69], v[142:143], 0, v[68:69]
	s_and_saveexec_b64 s[4:5], s[18:19]
	s_cbranch_execz .LBB0_649
	global_load_dwordx4 v[72:75], v[68:69], off
	global_load_dwordx4 v[78:81], v[66:67], off
	s_waitcnt vmcnt(0)
	v_mul_f32_e32 v82, v60, v74
	v_mul_f32_e32 v83, v61, v75
	v_mul_f32_e32 v84, v58, v72
	v_mul_f32_e32 v85, v59, v73
	v_mul_f32_e32 v74, v64, v74
	v_mul_f32_e32 v75, v65, v75
	v_mul_f32_e32 v72, v62, v72
	v_mul_f32_e32 v73, v63, v73
	v_fma_f32 v64, v64, v80, -v82
	v_fma_f32 v65, v65, v81, -v83
	v_fma_f32 v62, v62, v78, -v84
	v_fma_f32 v63, v63, v79, -v85
	v_fma_f32 v60, v60, v80, v74
	v_fma_f32 v61, v61, v81, v75
	v_fma_f32 v58, v58, v78, v72
	v_fma_f32 v59, v59, v79, v73
; __device__ __forceinline__ unsigned pk2(float lo, float hi) { f32x2_t v = {lo, hi}; bf16x2_t b = __builtin_convertvector(v, bf16x2_t); return __builtin_bit_cast(unsigned, b); }
;     __device__ __forceinline__ void operator()(const f32x4 (&acc)[2][2][4][2], const pg8::Unit& u, int wr, int wc, int fr, int fq) const {
;     ...
;                 const int row = u.pm * 256 + ai * 128 + wr * 64 + m * 16 + fr;
;                 const bool lat = row < TL; const int t = row & (SEQ - 1), pr = t >> 6, pc = t & 63;
; #pragma unroll
;                 for (int bj = 0; bj < 2; ++bj) {
;                     const int cg = (u.pn * 256 + bj * 128 + wc * 32) >> 5;
;                     f32x4 v0 = acc[ai][bj][m][0], v1 = acc[ai][bj][m][1];
;                     bool r16 = false, r8 = false; float sc = 1.f;
;                     if (IS_UQ) { r8 = (cg % 3) == 2; sc = MLA_C2; }
;                     else { r16 = cg < 32; r8 = cg == 84; if (cg >= 16 && cg < 32) sc = 0.125f; }
;                     if (r16 && lat) {
;                         const int pos = (cg & 1) ? pc : pr;
;                         const f32x4 cs = *(const f32x4*)(rt16c + pos * 16 + 4 * fq), sn = *(const f32x4*)(rt16s + pos * 16 + 4 * fq);
;                         const f32x4 o0 = v0 * cs - v1 * sn, o1 = v1 * cs + v0 * sn; v0 = o0; v1 = o1;
;                     }
;                     if (r8 && lat) {
;                         const int pos = (fq >> 1) ? pc : pr;
;                         const f32x4 cs = *(const f32x4*)(rt8c + pos * 8 + 4 * (fq & 1)), sn = *(const f32x4*)(rt8s + pos * 8 + 4 * (fq & 1));
;                         const f32x4 o0 = v0 * cs - v1 * sn, o1 = v1 * cs + v0 * sn; v0 = o0; v1 = o1;
;                     }
;                     v0 = v0 * sc; v1 = v1 * sc;
;                     u32x4 w; w.x = pk2(v0[0], v0[1]); w.y = pk2(v0[2], v0[3]); w.z = pk2(v1[0], v1[1]); w.w = pk2(v1[2], v1[3]);
;                     *(u32x4*)(O + (size_t)row * LDC + cg * 32 + 8 * fq) = w;
.LBB0_649:
	s_or_b64 exec, exec, s[4:5]
	v_mul_f32_e32 v62, v152, v62
	v_mul_f32_e32 v63, v153, v63
	v_mul_f32_e32 v58, v152, v58
	v_mul_f32_e32 v59, v153, v59
	v_mul_f32_e32 v72, v76, v60
	v_mul_f32_e32 v73, v77, v61
	v_cvt_pk_bf16_f32 v60, v62, v63
	v_cvt_pk_bf16_f32 v62, v58, v59
	v_mov_b64_e32 v[58:59], s[30:31]
	v_mad_i64_i32 v[58:59], s[4:5], v70, s16, v[58:59]
	v_mul_f32_e32 v64, v76, v64
	v_mul_f32_e32 v65, v77, v65
	v_lshl_add_u64 v[58:59], s[78:79], 1, v[58:59]
	v_cvt_pk_bf16_f32 v61, v64, v65
	v_cvt_pk_bf16_f32 v63, v72, v73
	v_lshl_add_u64 v[58:59], v[58:59], 0, v[0:1]
	s_and_b64 s[18:19], s[44:45], vcc
	global_store_dwordx4 v[58:59], v[60:63], off
	s_and_saveexec_b64 s[4:5], s[18:19]
	s_cbranch_execz .LBB0_651
	global_load_dwordx4 v[60:63], v[68:69], off
	s_nop 0
	global_load_dwordx4 v[64:67], v[66:67], off
	s_waitcnt vmcnt(0)
	v_mul_f32_e32 v68, v52, v62
	v_mul_f32_e32 v69, v53, v63
	v_mul_f32_e32 v70, v50, v60
	v_mul_f32_e32 v71, v51, v61
	v_mul_f32_e32 v62, v56, v62
	v_mul_f32_e32 v63, v57, v63
	v_mul_f32_e32 v60, v54, v60
	v_mul_f32_e32 v61, v55, v61
	v_fma_f32 v56, v56, v66, -v68
	v_fma_f32 v57, v57, v67, -v69
	v_fma_f32 v54, v54, v64, -v70
	v_fma_f32 v55, v55, v65, -v71
	v_fma_f32 v52, v52, v66, v62
	v_fma_f32 v53, v53, v67, v63
	v_fma_f32 v50, v50, v64, v60
	v_fma_f32 v51, v51, v65, v61
.LBB0_651:
	s_or_b64 exec, exec, s[4:5]
	s_and_b64 s[18:19], s[48:49], vcc
	s_and_saveexec_b64 s[4:5], s[18:19]
	s_cbranch_execz .LBB0_653
	v_mov_b32_e32 v60, s6
	v_cndmask_b32_e64 v60, v139, v60, s[40:41]
	v_lshlrev_b32_e32 v64, 5, v60
	v_mov_b32_e32 v65, v1
	v_lshl_add_u64 v[60:61], v[146:147], 0, v[64:65]
	global_load_dwordx4 v[60:63], v[60:61], off
	v_lshl_add_u64 v[64:65], v[144:145], 0, v[64:65]
	global_load_dwordx4 v[64:67], v[64:65], off
	s_waitcnt vmcnt(0)
	v_mul_f32_e32 v68, v52, v62
	v_mul_f32_e32 v69, v53, v63
	v_mul_f32_e32 v70, v50, v60
	v_mul_f32_e32 v71, v51, v61
	v_mul_f32_e32 v62, v56, v62
	v_mul_f32_e32 v63, v57, v63
	v_mul_f32_e32 v60, v54, v60
	v_mul_f32_e32 v61, v55, v61
	v_fma_f32 v56, v56, v66, -v68
	v_fma_f32 v57, v57, v67, -v69
	v_fma_f32 v54, v54, v64, -v70
	v_fma_f32 v55, v55, v65, -v71
	v_fma_f32 v52, v52, v66, v62
	v_fma_f32 v53, v53, v67, v63
	v_fma_f32 v50, v50, v64, v60
	v_fma_f32 v51, v51, v65, v61
.LBB0_653:
	s_or_b64 exec, exec, s[4:5]
	v_mov_b32_e32 v60, v152
	v_mov_b32_e32 v61, v152
	v_mul_f32_e32 v56, v60, v56
	v_mul_f32_e32 v57, v61, v57
	v_mul_f32_e32 v54, v152, v54
	v_mul_f32_e32 v55, v153, v55
	v_mul_f32_e32 v62, v60, v52
	v_mul_f32_e32 v63, v61, v53
	v_mul_f32_e32 v52, v152, v50
	v_mul_f32_e32 v53, v153, v51
	v_cvt_pk_bf16_f32 v50, v54, v55
	v_cvt_pk_bf16_f32 v51, v56, v57
	v_cvt_pk_bf16_f32 v52, v52, v53
	v_cvt_pk_bf16_f32 v53, v62, v63
	global_store_dwordx4 v[58:59], v[50:53], off offset:256
	v_or_b32_e32 v54, s7, v157
	v_cmp_gt_i32_e32 vcc, s91, v54
	v_mov_b32_e32 v50, s6
	v_cndmask_b32_e64 v50, v157, v50, s[38:39]
	v_lshlrev_b32_e32 v50, 4, v50
	v_mov_b32_e32 v51, v1
	v_lshlrev_b64 v[52:53], 2, v[50:51]
	s_and_b64 s[18:19], s[94:95], vcc
	v_lshl_add_u64 v[50:51], v[140:141], 0, v[52:53]
	v_lshl_add_u64 v[52:53], v[142:143], 0, v[52:53]
	s_and_saveexec_b64 s[4:5], s[18:19]
	s_cbranch_execz .LBB0_655
	global_load_dwordx4 v[56:59], v[52:53], off
	global_load_dwordx4 v[62:65], v[50:51], off
	s_waitcnt vmcnt(0)
	v_mul_f32_e32 v66, v44, v58
	v_mul_f32_e32 v67, v45, v59
	v_mul_f32_e32 v68, v42, v56
	v_mul_f32_e32 v69, v43, v57
	v_mul_f32_e32 v58, v48, v58
	v_mul_f32_e32 v59, v49, v59
	v_mul_f32_e32 v56, v46, v56
	v_mul_f32_e32 v57, v47, v57
	v_fma_f32 v48, v48, v64, -v66
	v_fma_f32 v49, v49, v65, -v67
	v_fma_f32 v46, v46, v62, -v68
	v_fma_f32 v47, v47, v63, -v69
	v_fma_f32 v44, v44, v64, v58
	v_fma_f32 v45, v45, v65, v59
	v_fma_f32 v42, v42, v62, v56
	v_fma_f32 v43, v43, v63, v57
.LBB0_655:
	s_or_b64 exec, exec, s[4:5]
	v_mul_f32_e32 v46, v152, v46
	v_mul_f32_e32 v47, v153, v47
	v_mul_f32_e32 v42, v152, v42
	v_mul_f32_e32 v43, v153, v43
	v_mul_f32_e32 v56, v60, v44
	v_mul_f32_e32 v57, v61, v45
	v_cvt_pk_bf16_f32 v44, v46, v47
	v_cvt_pk_bf16_f32 v46, v42, v43
	v_mov_b64_e32 v[42:43], s[30:31]
	v_mad_i64_i32 v[42:43], s[4:5], v54, s16, v[42:43]
	v_mul_f32_e32 v48, v60, v48
	v_mul_f32_e32 v49, v61, v49
	v_lshl_add_u64 v[42:43], s[78:79], 1, v[42:43]
	v_cvt_pk_bf16_f32 v45, v48, v49
	v_cvt_pk_bf16_f32 v47, v56, v57
	v_lshl_add_u64 v[42:43], v[42:43], 0, v[0:1]
	s_and_b64 s[18:19], s[44:45], vcc
	global_store_dwordx4 v[42:43], v[44:47], off
	s_and_saveexec_b64 s[4:5], s[18:19]
	s_cbranch_execz .LBB0_657
	global_load_dwordx4 v[44:47], v[52:53], off
	s_nop 0
	global_load_dwordx4 v[48:51], v[50:51], off
	s_waitcnt vmcnt(0)
	v_mul_f32_e32 v52, v36, v46
	v_mul_f32_e32 v53, v37, v47
	v_mul_f32_e32 v54, v34, v44
	v_mul_f32_e32 v55, v35, v45
	v_mul_f32_e32 v46, v40, v46
	v_mul_f32_e32 v47, v41, v47
	v_mul_f32_e32 v44, v38, v44
	v_mul_f32_e32 v45, v39, v45
	v_fma_f32 v40, v40, v50, -v52
	v_fma_f32 v41, v41, v51, -v53
	v_fma_f32 v38, v38, v48, -v54
	v_fma_f32 v39, v39, v49, -v55
	v_fma_f32 v36, v36, v50, v46
	v_fma_f32 v37, v37, v51, v47
	v_fma_f32 v34, v34, v48, v44
	v_fma_f32 v35, v35, v49, v45
.LBB0_657:
	s_or_b64 exec, exec, s[4:5]
	s_and_b64 s[18:19], s[48:49], vcc
	s_and_saveexec_b64 s[4:5], s[18:19]
	s_cbranch_execz .LBB0_659
	v_mov_b32_e32 v44, s6
	v_cndmask_b32_e64 v44, v157, v44, s[40:41]
	v_lshlrev_b32_e32 v48, 5, v44
	v_mov_b32_e32 v49, v1
	v_lshl_add_u64 v[44:45], v[146:147], 0, v[48:49]
	global_load_dwordx4 v[44:47], v[44:45], off
	v_lshl_add_u64 v[48:49], v[144:145], 0, v[48:49]
	global_load_dwordx4 v[48:51], v[48:49], off
	s_waitcnt vmcnt(0)
	v_mul_f32_e32 v52, v36, v46
	v_mul_f32_e32 v53, v37, v47
	v_mul_f32_e32 v54, v34, v44
	v_mul_f32_e32 v55, v35, v45
	v_mul_f32_e32 v46, v40, v46
	v_mul_f32_e32 v47, v41, v47
	v_mul_f32_e32 v44, v38, v44
	v_mul_f32_e32 v45, v39, v45
	v_fma_f32 v40, v40, v50, -v52
	v_fma_f32 v41, v41, v51, -v53
	v_fma_f32 v38, v38, v48, -v54
	v_fma_f32 v39, v39, v49, -v55
	v_fma_f32 v36, v36, v50, v46
	v_fma_f32 v37, v37, v51, v47
	v_fma_f32 v34, v34, v48, v44
	v_fma_f32 v35, v35, v49, v45
; __device__ __forceinline__ unsigned pk2(float lo, float hi) { f32x2_t v = {lo, hi}; bf16x2_t b = __builtin_convertvector(v, bf16x2_t); return __builtin_bit_cast(unsigned, b); }
;     __device__ __forceinline__ void operator()(const f32x4 (&acc)[2][2][4][2], const pg8::Unit& u, int wr, int wc, int fr, int fq) const {
;     ...
;                 const int row = u.pm * 256 + ai * 128 + wr * 64 + m * 16 + fr;
;                 const bool lat = row < TL; const int t = row & (SEQ - 1), pr = t >> 6, pc = t & 63;
; #pragma unroll
;                 for (int bj = 0; bj < 2; ++bj) {
;                     const int cg = (u.pn * 256 + bj * 128 + wc * 32) >> 5;
;                     f32x4 v0 = acc[ai][bj][m][0], v1 = acc[ai][bj][m][1];
;                     bool r16 = false, r8 = false; float sc = 1.f;
;                     if (IS_UQ) { r8 = (cg % 3) == 2; sc = MLA_C2; }
;                     else { r16 = cg < 32; r8 = cg == 84; if (cg >= 16 && cg < 32) sc = 0.125f; }
;                     if (r16 && lat) {
;                         const int pos = (cg & 1) ? pc : pr;
;                         const f32x4 cs = *(const f32x4*)(rt16c + pos * 16 + 4 * fq), sn = *(const f32x4*)(rt16s + pos * 16 + 4 * fq);
;                         const f32x4 o0 = v0 * cs - v1 * sn, o1 = v1 * cs + v0 * sn; v0 = o0; v1 = o1;
;                     }
;                     if (r8 && lat) {
;                         const int pos = (fq >> 1) ? pc : pr;
;                         const f32x4 cs = *(const f32x4*)(rt8c + pos * 8 + 4 * (fq & 1)), sn = *(const f32x4*)(rt8s + pos * 8 + 4 * (fq & 1));
;                         const f32x4 o0 = v0 * cs - v1 * sn, o1 = v1 * cs + v0 * sn; v0 = o0; v1 = o1;
;                     }
;                     v0 = v0 * sc; v1 = v1 * sc;
;                     u32x4 w; w.x = pk2(v0[0], v0[1]); w.y = pk2(v0[2], v0[3]); w.z = pk2(v1[0], v1[1]); w.w = pk2(v1[2], v1[3]);
;                     *(u32x4*)(O + (size_t)row * LDC + cg * 32 + 8 * fq) = w;
.LBB0_659:
	s_or_b64 exec, exec, s[4:5]
	v_mov_b32_e32 v44, v152
	v_mov_b32_e32 v45, v152
	v_mul_f32_e32 v40, v44, v40
	v_mul_f32_e32 v41, v45, v41
	v_mul_f32_e32 v38, v152, v38
	v_mul_f32_e32 v39, v153, v39
	v_mul_f32_e32 v46, v44, v36
	v_mul_f32_e32 v47, v45, v37
	v_mul_f32_e32 v36, v152, v34
	v_mul_f32_e32 v37, v153, v35
	v_cvt_pk_bf16_f32 v34, v38, v39
	v_cvt_pk_bf16_f32 v35, v40, v41
	v_cvt_pk_bf16_f32 v36, v36, v37
	v_cvt_pk_bf16_f32 v37, v46, v47
	global_store_dwordx4 v[42:43], v[34:37], off offset:256
	v_or_b32_e32 v38, s7, v158
	v_cmp_gt_i32_e32 vcc, s91, v38
	v_mov_b32_e32 v34, s6
	v_cndmask_b32_e64 v34, v158, v34, s[38:39]
	v_lshlrev_b32_e32 v34, 4, v34
	v_mov_b32_e32 v35, v1
	v_lshlrev_b64 v[36:37], 2, v[34:35]
	s_and_b64 s[18:19], s[94:95], vcc
	v_lshl_add_u64 v[34:35], v[140:141], 0, v[36:37]
	v_lshl_add_u64 v[36:37], v[142:143], 0, v[36:37]
	s_and_saveexec_b64 s[4:5], s[18:19]
	s_cbranch_execz .LBB0_661
	global_load_dwordx4 v[40:43], v[36:37], off
	global_load_dwordx4 v[46:49], v[34:35], off
	s_waitcnt vmcnt(0)
	v_mul_f32_e32 v50, v28, v42
	v_mul_f32_e32 v51, v29, v43
	v_mul_f32_e32 v52, v26, v40
	v_mul_f32_e32 v53, v27, v41
	v_mul_f32_e32 v42, v32, v42
	v_mul_f32_e32 v43, v33, v43
	v_mul_f32_e32 v40, v30, v40
	v_mul_f32_e32 v41, v31, v41
	v_fma_f32 v32, v32, v48, -v50
	v_fma_f32 v33, v33, v49, -v51
	v_fma_f32 v30, v30, v46, -v52
	v_fma_f32 v31, v31, v47, -v53
	v_fma_f32 v28, v28, v48, v42
	v_fma_f32 v29, v29, v49, v43
	v_fma_f32 v26, v26, v46, v40
	v_fma_f32 v27, v27, v47, v41
.LBB0_661:
	s_or_b64 exec, exec, s[4:5]
	v_mul_f32_e32 v30, v152, v30
	v_mul_f32_e32 v31, v153, v31
	v_mul_f32_e32 v26, v152, v26
	v_mul_f32_e32 v27, v153, v27
	v_mul_f32_e32 v40, v44, v28
	v_mul_f32_e32 v41, v45, v29
	v_cvt_pk_bf16_f32 v28, v30, v31
	v_cvt_pk_bf16_f32 v30, v26, v27
	v_mov_b64_e32 v[26:27], s[30:31]
	v_mad_i64_i32 v[26:27], s[4:5], v38, s16, v[26:27]
	v_mul_f32_e32 v32, v44, v32
	v_mul_f32_e32 v33, v45, v33
	v_lshl_add_u64 v[26:27], s[78:79], 1, v[26:27]
	v_cvt_pk_bf16_f32 v29, v32, v33
	v_cvt_pk_bf16_f32 v31, v40, v41
	v_lshl_add_u64 v[26:27], v[26:27], 0, v[0:1]
	s_and_b64 s[18:19], s[44:45], vcc
	global_store_dwordx4 v[26:27], v[28:31], off
	s_and_saveexec_b64 s[4:5], s[18:19]
	s_cbranch_execz .LBB0_663
	global_load_dwordx4 v[28:31], v[36:37], off
	s_nop 0
	global_load_dwordx4 v[32:35], v[34:35], off
	s_waitcnt vmcnt(0)
	v_mul_f32_e32 v36, v20, v30
	v_mul_f32_e32 v37, v21, v31
	v_mul_f32_e32 v38, v18, v28
	v_mul_f32_e32 v39, v19, v29
	v_mul_f32_e32 v30, v24, v30
	v_mul_f32_e32 v31, v25, v31
	v_mul_f32_e32 v28, v22, v28
	v_mul_f32_e32 v29, v23, v29
	v_fma_f32 v24, v24, v34, -v36
	v_fma_f32 v25, v25, v35, -v37
	v_fma_f32 v22, v22, v32, -v38
	v_fma_f32 v23, v23, v33, -v39
	v_fma_f32 v20, v20, v34, v30
	v_fma_f32 v21, v21, v35, v31
	v_fma_f32 v18, v18, v32, v28
	v_fma_f32 v19, v19, v33, v29
.LBB0_663:
	s_or_b64 exec, exec, s[4:5]
	s_and_b64 s[18:19], s[48:49], vcc
	s_and_saveexec_b64 s[4:5], s[18:19]
	s_cbranch_execz .LBB0_665
	v_mov_b32_e32 v28, s6
	v_cndmask_b32_e64 v28, v158, v28, s[40:41]
	v_lshlrev_b32_e32 v32, 5, v28
	v_mov_b32_e32 v33, v1
	v_lshl_add_u64 v[28:29], v[146:147], 0, v[32:33]
	global_load_dwordx4 v[28:31], v[28:29], off
	v_lshl_add_u64 v[32:33], v[144:145], 0, v[32:33]
	global_load_dwordx4 v[32:35], v[32:33], off
	s_waitcnt vmcnt(0)
	v_mul_f32_e32 v36, v20, v30
	v_mul_f32_e32 v37, v21, v31
	v_mul_f32_e32 v38, v18, v28
	v_mul_f32_e32 v39, v19, v29
	v_mul_f32_e32 v30, v24, v30
	v_mul_f32_e32 v31, v25, v31
	v_mul_f32_e32 v28, v22, v28
	v_mul_f32_e32 v29, v23, v29
	v_fma_f32 v24, v24, v34, -v36
	v_fma_f32 v25, v25, v35, -v37
	v_fma_f32 v22, v22, v32, -v38
	v_fma_f32 v23, v23, v33, -v39
	v_fma_f32 v20, v20, v34, v30
	v_fma_f32 v21, v21, v35, v31
	v_fma_f32 v18, v18, v32, v28
	v_fma_f32 v19, v19, v33, v29
; __device__ __forceinline__ unsigned pk2(float lo, float hi) { f32x2_t v = {lo, hi}; bf16x2_t b = __builtin_convertvector(v, bf16x2_t); return __builtin_bit_cast(unsigned, b); }
;     __device__ __forceinline__ void operator()(const f32x4 (&acc)[2][2][4][2], const pg8::Unit& u, int wr, int wc, int fr, int fq) const {
;     ...
;                 const int row = u.pm * 256 + ai * 128 + wr * 64 + m * 16 + fr;
;                 const bool lat = row < TL; const int t = row & (SEQ - 1), pr = t >> 6, pc = t & 63;
; #pragma unroll
;                 for (int bj = 0; bj < 2; ++bj) {
;                     const int cg = (u.pn * 256 + bj * 128 + wc * 32) >> 5;
;                     f32x4 v0 = acc[ai][bj][m][0], v1 = acc[ai][bj][m][1];
;                     bool r16 = false, r8 = false; float sc = 1.f;
;                     if (IS_UQ) { r8 = (cg % 3) == 2; sc = MLA_C2; }
;                     else { r16 = cg < 32; r8 = cg == 84; if (cg >= 16 && cg < 32) sc = 0.125f; }
;                     if (r16 && lat) {
;                         const int pos = (cg & 1) ? pc : pr;
;                         const f32x4 cs = *(const f32x4*)(rt16c + pos * 16 + 4 * fq), sn = *(const f32x4*)(rt16s + pos * 16 + 4 * fq);
;                         const f32x4 o0 = v0 * cs - v1 * sn, o1 = v1 * cs + v0 * sn; v0 = o0; v1 = o1;
;                     }
;                     if (r8 && lat) {
;                         const int pos = (fq >> 1) ? pc : pr;
;                         const f32x4 cs = *(const f32x4*)(rt8c + pos * 8 + 4 * (fq & 1)), sn = *(const f32x4*)(rt8s + pos * 8 + 4 * (fq & 1));
;                         const f32x4 o0 = v0 * cs - v1 * sn, o1 = v1 * cs + v0 * sn; v0 = o0; v1 = o1;
;                     }
;                     v0 = v0 * sc; v1 = v1 * sc;
;                     u32x4 w; w.x = pk2(v0[0], v0[1]); w.y = pk2(v0[2], v0[3]); w.z = pk2(v1[0], v1[1]); w.w = pk2(v1[2], v1[3]);
;                     *(u32x4*)(O + (size_t)row * LDC + cg * 32 + 8 * fq) = w;
.LBB0_665:
	s_or_b64 exec, exec, s[4:5]
	v_mov_b32_e32 v28, v152
	v_mov_b32_e32 v29, v152
	v_mul_f32_e32 v24, v28, v24
	v_mul_f32_e32 v25, v29, v25
	v_mul_f32_e32 v22, v152, v22
	v_mul_f32_e32 v23, v153, v23
	v_mul_f32_e32 v30, v28, v20
	v_mul_f32_e32 v31, v29, v21
	v_mul_f32_e32 v20, v152, v18
	v_mul_f32_e32 v21, v153, v19
	v_cvt_pk_bf16_f32 v18, v22, v23
	v_cvt_pk_bf16_f32 v19, v24, v25
	v_cvt_pk_bf16_f32 v20, v20, v21
	v_cvt_pk_bf16_f32 v21, v30, v31
	global_store_dwordx4 v[26:27], v[18:21], off offset:256
	v_or_b32_e32 v22, s7, v159
	v_cmp_gt_i32_e32 vcc, s91, v22
	v_mov_b32_e32 v18, s6
	v_cndmask_b32_e64 v18, v159, v18, s[38:39]
	v_lshlrev_b32_e32 v18, 4, v18
	v_mov_b32_e32 v19, v1
	v_lshlrev_b64 v[20:21], 2, v[18:19]
	s_and_b64 s[18:19], s[94:95], vcc
	v_lshl_add_u64 v[18:19], v[140:141], 0, v[20:21]
	v_lshl_add_u64 v[20:21], v[142:143], 0, v[20:21]
	s_and_saveexec_b64 s[4:5], s[18:19]
	s_cbranch_execz .LBB0_667
	global_load_dwordx4 v[24:27], v[20:21], off
	global_load_dwordx4 v[30:33], v[18:19], off
	s_waitcnt vmcnt(0)
	v_mul_f32_e32 v34, v12, v26
	v_mul_f32_e32 v35, v13, v27
	v_mul_f32_e32 v36, v10, v24
	v_mul_f32_e32 v37, v11, v25
	v_mul_f32_e32 v26, v16, v26
	v_mul_f32_e32 v27, v17, v27
	v_mul_f32_e32 v24, v14, v24
	v_mul_f32_e32 v25, v15, v25
	v_fma_f32 v16, v16, v32, -v34
	v_fma_f32 v17, v17, v33, -v35
	v_fma_f32 v14, v14, v30, -v36
	v_fma_f32 v15, v15, v31, -v37
	v_fma_f32 v12, v12, v32, v26
	v_fma_f32 v13, v13, v33, v27
	v_fma_f32 v10, v10, v30, v24
	v_fma_f32 v11, v11, v31, v25
.LBB0_667:
	s_or_b64 exec, exec, s[4:5]
	v_mul_f32_e32 v14, v152, v14
	v_mul_f32_e32 v15, v153, v15
	v_mul_f32_e32 v10, v152, v10
	v_mul_f32_e32 v11, v153, v11
	v_mul_f32_e32 v24, v28, v12
	v_mul_f32_e32 v25, v29, v13
	v_cvt_pk_bf16_f32 v12, v14, v15
	v_cvt_pk_bf16_f32 v14, v10, v11
	v_mov_b64_e32 v[10:11], s[30:31]
	v_mad_i64_i32 v[10:11], s[4:5], v22, s16, v[10:11]
	v_mul_f32_e32 v16, v28, v16
	v_mul_f32_e32 v17, v29, v17
	v_lshl_add_u64 v[10:11], s[78:79], 1, v[10:11]
	v_cvt_pk_bf16_f32 v13, v16, v17
	v_cvt_pk_bf16_f32 v15, v24, v25
	v_lshl_add_u64 v[10:11], v[10:11], 0, v[0:1]
	s_and_b64 s[18:19], s[44:45], vcc
	global_store_dwordx4 v[10:11], v[12:15], off
	s_and_saveexec_b64 s[4:5], s[18:19]
	s_cbranch_execz .LBB0_669
	global_load_dwordx4 v[12:15], v[20:21], off
	s_nop 0
	global_load_dwordx4 v[16:19], v[18:19], off
	s_waitcnt vmcnt(0)
	v_mul_f32_e32 v20, v4, v14
	v_mul_f32_e32 v21, v5, v15
	v_mul_f32_e32 v22, v2, v12
	v_mul_f32_e32 v23, v3, v13
	v_mul_f32_e32 v14, v8, v14
	v_mul_f32_e32 v15, v9, v15
	v_mul_f32_e32 v12, v6, v12
	v_mul_f32_e32 v13, v7, v13
	v_fma_f32 v8, v8, v18, -v20
	v_fma_f32 v9, v9, v19, -v21
	v_fma_f32 v6, v6, v16, -v22
	v_fma_f32 v7, v7, v17, -v23
	v_fma_f32 v4, v4, v18, v14
	v_fma_f32 v5, v5, v19, v15
	v_fma_f32 v2, v2, v16, v12
	v_fma_f32 v3, v3, v17, v13
.LBB0_669:
	s_or_b64 exec, exec, s[4:5]
	s_and_b64 s[18:19], s[48:49], vcc
	s_and_saveexec_b64 s[4:5], s[18:19]
	s_cbranch_execz .LBB0_671
	v_mov_b32_e32 v0, s6
	v_cndmask_b32_e64 v0, v159, v0, s[40:41]
	v_lshlrev_b32_e32 v0, 5, v0
	v_lshl_add_u64 v[12:13], v[146:147], 0, v[0:1]
	global_load_dwordx4 v[12:15], v[12:13], off
	v_lshl_add_u64 v[16:17], v[144:145], 0, v[0:1]
	global_load_dwordx4 v[16:19], v[16:17], off
	s_waitcnt vmcnt(0)
	v_mul_f32_e32 v20, v4, v14
	v_mul_f32_e32 v21, v5, v15
	v_mul_f32_e32 v22, v2, v12
	v_mul_f32_e32 v23, v3, v13
	v_mul_f32_e32 v14, v8, v14
	v_mul_f32_e32 v15, v9, v15
	v_mul_f32_e32 v12, v6, v12
	v_mul_f32_e32 v13, v7, v13
	v_fma_f32 v8, v8, v18, -v20
	v_fma_f32 v9, v9, v19, -v21
	v_fma_f32 v6, v6, v16, -v22
	v_fma_f32 v7, v7, v17, -v23
	v_fma_f32 v4, v4, v18, v14
	v_fma_f32 v5, v5, v19, v15
	v_fma_f32 v2, v2, v16, v12
	v_fma_f32 v3, v3, v17, v13
.LBB0_671:
	s_or_b64 exec, exec, s[4:5]
	v_mov_b32_e32 v12, v152
	v_mov_b32_e32 v13, v152
	v_mul_f32_e32 v8, v12, v8
	v_mul_f32_e32 v9, v13, v9
	v_mul_f32_e32 v6, v152, v6
	v_mul_f32_e32 v7, v153, v7
	v_mul_f32_e32 v12, v12, v4
	v_mul_f32_e32 v13, v13, v5
	v_mul_f32_e32 v4, v152, v2
	v_mul_f32_e32 v5, v153, v3
	v_cvt_pk_bf16_f32 v2, v6, v7
	v_cvt_pk_bf16_f32 v3, v8, v9
	v_cvt_pk_bf16_f32 v4, v4, v5
	v_cvt_pk_bf16_f32 v5, v12, v13
	s_andn2_b64 vcc, exec, s[42:43]
	s_mov_b64 s[4:5], -1
	global_store_dwordx4 v[10:11], v[2:5], off offset:256
	s_cbranch_vccnz .LBB0_612
	s_andn2_b64 vcc, exec, s[36:37]
	s_cbranch_vccnz .LBB0_611
	s_barrier
	s_branch .LBB0_611

; __device__ __forceinline__ unsigned pk2(float lo, float hi) { f32x2_t v = {lo, hi}; bf16x2_t b = __builtin_convertvector(v, bf16x2_t); return __builtin_bit_cast(unsigned, b); }
;     __device__ __forceinline__ void operator()(const f32x4 (&acc)[2][2][4][2], const pg8::Unit& u, int wr, int wc, int fr, int fq) const {
;     ...
;                 const int row = u.pm * 256 + ai * 128 + wr * 64 + m * 16 + fr;
;                 const bool lat = row < TL; const int t = row & (SEQ - 1), pr = t >> 6, pc = t & 63;
; #pragma unroll
;                 for (int bj = 0; bj < 2; ++bj) {
;                     const int cg = (u.pn * 256 + bj * 128 + wc * 32) >> 5;
;                     f32x4 v0 = acc[ai][bj][m][0], v1 = acc[ai][bj][m][1];
;                     bool r16 = false, r8 = false; float sc = 1.f;
;                     if (IS_UQ) { r8 = (cg % 3) == 2; sc = MLA_C2; }
;                     else { r16 = cg < 32; r8 = cg == 84; if (cg >= 16 && cg < 32) sc = 0.125f; }
;                     if (r16 && lat) {
;                         const int pos = (cg & 1) ? pc : pr;
;                         const f32x4 cs = *(const f32x4*)(rt16c + pos * 16 + 4 * fq), sn = *(const f32x4*)(rt16s + pos * 16 + 4 * fq);
;                         const f32x4 o0 = v0 * cs - v1 * sn, o1 = v1 * cs + v0 * sn; v0 = o0; v1 = o1;
;                     }
;                     if (r8 && lat) {
;                         const int pos = (fq >> 1) ? pc : pr;
;                         const f32x4 cs = *(const f32x4*)(rt8c + pos * 8 + 4 * (fq & 1)), sn = *(const f32x4*)(rt8s + pos * 8 + 4 * (fq & 1));
;                         const f32x4 o0 = v0 * cs - v1 * sn, o1 = v1 * cs + v0 * sn; v0 = o0; v1 = o1;
;                     }
;                     v0 = v0 * sc; v1 = v1 * sc;
;                     u32x4 w; w.x = pk2(v0[0], v0[1]); w.y = pk2(v0[2], v0[3]); w.z = pk2(v1[0], v1[1]); w.w = pk2(v1[2], v1[3]);
;                     *(u32x4*)(O + (size_t)row * LDC + cg * 32 + 8 * fq) = w;
.LBB0_965:
	s_lshl_b32 s4, s72, 8
	s_or_b32 s48, s4, s29
	s_ashr_i32 s18, s48, 5
	s_mul_hi_i32 s4, s18, 0x55555556
	s_lshl_b32 s6, s73, 8
	s_lshr_b32 s5, s4, 31
	s_add_i32 s6, s6, s28
	s_add_i32 s4, s4, s5
	s_bfe_u32 s7, s6, 0x70006
	s_mul_i32 s4, s4, 3
	v_mov_b32_e32 v148, s7
	s_sub_i32 s4, s18, s4
	v_or_b32_e32 v0, s6, v139
	v_cndmask_b32_e64 v148, v139, v148, s[38:39]
	s_cmp_eq_u32 s4, 2
	v_cmp_gt_i32_e32 vcc, s91, v0
	v_lshlrev_b32_e32 v148, 3, v148
	s_cselect_b64 s[68:69], -1, 0
	s_and_b64 s[54:55], s[68:69], vcc
	v_lshlrev_b32_e32 v148, 2, v148
	s_and_saveexec_b64 s[4:5], s[54:55]
	v_readlane_b32 s96, v255, 22
	v_readlane_b32 s97, v255, 23
	s_cbranch_execz .LBB0_967
	v_mov_b32_e32 v149, v1
	v_lshl_add_u64 v[156:157], v[142:143], 0, v[148:149]
	global_load_dwordx4 v[156:159], v[156:157], off
	v_lshl_add_u64 v[160:161], v[140:141], 0, v[148:149]
	global_load_dwordx4 v[160:163], v[160:161], off
	s_waitcnt vmcnt(0)
	v_mul_f32_e32 v164, v124, v158
	v_mul_f32_e32 v165, v125, v159
	v_mul_f32_e32 v166, v122, v156
	v_mul_f32_e32 v167, v123, v157
	v_mul_f32_e32 v158, v128, v158
	v_mul_f32_e32 v159, v129, v159
	v_mul_f32_e32 v156, v126, v156
	v_mul_f32_e32 v157, v127, v157
	v_fma_f32 v128, v128, v162, -v164
	v_fma_f32 v129, v129, v163, -v165
	v_fma_f32 v126, v126, v160, -v166
	v_fma_f32 v127, v127, v161, -v167
	v_fma_f32 v124, v124, v162, v158
	v_fma_f32 v125, v125, v163, v159
	v_fma_f32 v122, v122, v160, v156
	v_fma_f32 v123, v123, v161, v157
.LBB0_967:
	s_or_b64 exec, exec, s[4:5]
	v_mul_f32_e32 v126, s34, v126
	v_mul_f32_e32 v127, s34, v127
	v_mul_f32_e32 v122, s34, v122
	v_mul_f32_e32 v123, s34, v123
	v_mul_f32_e32 v156, s34, v124
	v_mul_f32_e32 v157, s34, v125
	v_cvt_pk_bf16_f32 v124, v126, v127
	v_cvt_pk_bf16_f32 v126, v122, v123
	v_mov_b64_e32 v[122:123], s[0:1]
	s_movk_i32 s4, 0x600
	v_mad_i64_i32 v[122:123], s[4:5], v0, s4, v[122:123]
	s_or_b32 s4, s18, 4
	s_mul_hi_i32 s5, s4, 0x55555556
	s_lshr_b32 s18, s5, 31
	s_add_i32 s5, s5, s18
	s_mul_i32 s5, s5, 3
	s_ashr_i32 s49, s48, 31
	s_sub_i32 s4, s4, s5
	s_cmp_eq_u32 s4, 2
	v_mul_f32_e32 v128, s34, v128
	v_mul_f32_e32 v129, s34, v129
	v_lshl_add_u64 v[122:123], s[48:49], 1, v[122:123]
	v_lshlrev_b32_e32 v0, 1, v138
	s_cselect_b64 s[72:73], -1, 0
	v_cvt_pk_bf16_f32 v125, v128, v129
	v_cvt_pk_bf16_f32 v127, v156, v157
	v_lshl_add_u64 v[122:123], v[122:123], 0, v[0:1]
	s_and_b64 s[18:19], s[72:73], vcc
	global_store_dwordx4 v[122:123], v[124:127], off
	s_and_saveexec_b64 s[4:5], s[18:19]
	s_cbranch_execz .LBB0_969
	v_mov_b32_e32 v149, v1
	v_lshl_add_u64 v[124:125], v[142:143], 0, v[148:149]
	global_load_dwordx4 v[124:127], v[124:125], off
	v_lshl_add_u64 v[128:129], v[140:141], 0, v[148:149]
	global_load_dwordx4 v[156:159], v[128:129], off
	s_waitcnt vmcnt(0)
	v_mul_f32_e32 v128, v116, v126
	v_mul_f32_e32 v129, v117, v127
	v_mul_f32_e32 v148, v114, v124
	v_mul_f32_e32 v149, v115, v125
	v_mul_f32_e32 v126, v120, v126
	v_mul_f32_e32 v127, v121, v127
	v_mul_f32_e32 v124, v118, v124
	v_mul_f32_e32 v125, v119, v125
	v_fma_f32 v120, v120, v158, -v128
	v_fma_f32 v121, v121, v159, -v129
	v_fma_f32 v118, v118, v156, -v148
	v_fma_f32 v119, v119, v157, -v149
	v_fma_f32 v116, v116, v158, v126
	v_fma_f32 v117, v117, v159, v127
	v_fma_f32 v114, v114, v156, v124
	v_fma_f32 v115, v115, v157, v125
.LBB0_969:
	s_or_b64 exec, exec, s[4:5]
	v_mul_f32_e32 v120, s34, v120
	v_mul_f32_e32 v121, s34, v121
	v_mul_f32_e32 v118, s34, v118
	v_mul_f32_e32 v119, s34, v119
	v_mul_f32_e32 v124, s34, v116
	v_mul_f32_e32 v125, s34, v117
	v_mul_f32_e32 v116, s34, v114
	v_mul_f32_e32 v117, s34, v115
	v_cvt_pk_bf16_f32 v114, v118, v119
	v_cvt_pk_bf16_f32 v115, v120, v121
	v_cvt_pk_bf16_f32 v116, v116, v117
	v_cvt_pk_bf16_f32 v117, v124, v125
	global_store_dwordx4 v[122:123], v[114:117], off offset:256
	v_or_b32_e32 v118, s6, v151
	v_cmp_gt_i32_e32 vcc, s91, v118
	v_mov_b32_e32 v114, s7
	v_cndmask_b32_e64 v114, v151, v114, s[38:39]
	v_lshlrev_b32_e32 v114, 3, v114
	v_mov_b32_e32 v115, v1
	v_lshlrev_b64 v[116:117], 2, v[114:115]
	s_and_b64 s[18:19], s[68:69], vcc
	v_lshl_add_u64 v[114:115], v[140:141], 0, v[116:117]
	v_lshl_add_u64 v[116:117], v[142:143], 0, v[116:117]
	s_and_saveexec_b64 s[4:5], s[18:19]
	s_cbranch_execz .LBB0_971
	global_load_dwordx4 v[120:123], v[116:117], off
	global_load_dwordx4 v[124:127], v[114:115], off
	s_waitcnt vmcnt(0)
	v_mul_f32_e32 v128, v108, v122
	v_mul_f32_e32 v129, v109, v123
	v_mul_f32_e32 v148, v106, v120
	v_mul_f32_e32 v149, v107, v121
	v_mul_f32_e32 v122, v112, v122
	v_mul_f32_e32 v123, v113, v123
	v_mul_f32_e32 v120, v110, v120
	v_mul_f32_e32 v121, v111, v121
	v_fma_f32 v112, v112, v126, -v128
	v_fma_f32 v113, v113, v127, -v129
	v_fma_f32 v110, v110, v124, -v148
	v_fma_f32 v111, v111, v125, -v149
	v_fma_f32 v108, v108, v126, v122
	v_fma_f32 v109, v109, v127, v123
	v_fma_f32 v106, v106, v124, v120
	v_fma_f32 v107, v107, v125, v121
.LBB0_971:
	s_or_b64 exec, exec, s[4:5]
	v_mul_f32_e32 v110, s34, v110
	v_mul_f32_e32 v111, s34, v111
	v_mul_f32_e32 v106, s34, v106
	v_mul_f32_e32 v107, s34, v107
	v_mul_f32_e32 v120, s34, v108
	v_mul_f32_e32 v121, s34, v109
	v_cvt_pk_bf16_f32 v108, v110, v111
	v_cvt_pk_bf16_f32 v110, v106, v107
	v_mov_b64_e32 v[106:107], s[0:1]
	s_movk_i32 s4, 0x600
	v_mad_i64_i32 v[106:107], s[4:5], v118, s4, v[106:107]
	v_mul_f32_e32 v112, s34, v112
	v_mul_f32_e32 v113, s34, v113
	v_lshl_add_u64 v[106:107], s[48:49], 1, v[106:107]
	v_cvt_pk_bf16_f32 v109, v112, v113
	v_cvt_pk_bf16_f32 v111, v120, v121
	v_lshl_add_u64 v[106:107], v[106:107], 0, v[0:1]
	s_and_b64 s[18:19], s[72:73], vcc
	global_store_dwordx4 v[106:107], v[108:111], off
	s_and_saveexec_b64 s[4:5], s[18:19]
	s_cbranch_execz .LBB0_973
	global_load_dwordx4 v[108:111], v[116:117], off
	s_nop 0
	global_load_dwordx4 v[112:115], v[114:115], off
	s_waitcnt vmcnt(0)
	v_mul_f32_e32 v116, v100, v110
	v_mul_f32_e32 v117, v101, v111
	v_mul_f32_e32 v118, v98, v108
	v_mul_f32_e32 v119, v99, v109
	v_mul_f32_e32 v110, v104, v110
	v_mul_f32_e32 v111, v105, v111
	v_mul_f32_e32 v108, v102, v108
	v_mul_f32_e32 v109, v103, v109
	v_fma_f32 v104, v104, v114, -v116
	v_fma_f32 v105, v105, v115, -v117
	v_fma_f32 v102, v102, v112, -v118
	v_fma_f32 v103, v103, v113, -v119
	v_fma_f32 v100, v100, v114, v110
	v_fma_f32 v101, v101, v115, v111
	v_fma_f32 v98, v98, v112, v108
	v_fma_f32 v99, v99, v113, v109
; __device__ __forceinline__ unsigned pk2(float lo, float hi) { f32x2_t v = {lo, hi}; bf16x2_t b = __builtin_convertvector(v, bf16x2_t); return __builtin_bit_cast(unsigned, b); }
;     __device__ __forceinline__ void operator()(const f32x4 (&acc)[2][2][4][2], const pg8::Unit& u, int wr, int wc, int fr, int fq) const {
;     ...
;                 const int row = u.pm * 256 + ai * 128 + wr * 64 + m * 16 + fr;
;                 const bool lat = row < TL; const int t = row & (SEQ - 1), pr = t >> 6, pc = t & 63;
; #pragma unroll
;                 for (int bj = 0; bj < 2; ++bj) {
;                     const int cg = (u.pn * 256 + bj * 128 + wc * 32) >> 5;
;                     f32x4 v0 = acc[ai][bj][m][0], v1 = acc[ai][bj][m][1];
;                     bool r16 = false, r8 = false; float sc = 1.f;
;                     if (IS_UQ) { r8 = (cg % 3) == 2; sc = MLA_C2; }
;                     else { r16 = cg < 32; r8 = cg == 84; if (cg >= 16 && cg < 32) sc = 0.125f; }
;                     if (r16 && lat) {
;                         const int pos = (cg & 1) ? pc : pr;
;                         const f32x4 cs = *(const f32x4*)(rt16c + pos * 16 + 4 * fq), sn = *(const f32x4*)(rt16s + pos * 16 + 4 * fq);
;                         const f32x4 o0 = v0 * cs - v1 * sn, o1 = v1 * cs + v0 * sn; v0 = o0; v1 = o1;
;                     }
;                     if (r8 && lat) {
;                         const int pos = (fq >> 1) ? pc : pr;
;                         const f32x4 cs = *(const f32x4*)(rt8c + pos * 8 + 4 * (fq & 1)), sn = *(const f32x4*)(rt8s + pos * 8 + 4 * (fq & 1));
;                         const f32x4 o0 = v0 * cs - v1 * sn, o1 = v1 * cs + v0 * sn; v0 = o0; v1 = o1;
;                     }
;                     v0 = v0 * sc; v1 = v1 * sc;
;                     u32x4 w; w.x = pk2(v0[0], v0[1]); w.y = pk2(v0[2], v0[3]); w.z = pk2(v1[0], v1[1]); w.w = pk2(v1[2], v1[3]);
;                     *(u32x4*)(O + (size_t)row * LDC + cg * 32 + 8 * fq) = w;
.LBB0_973:
	s_or_b64 exec, exec, s[4:5]
	v_mul_f32_e32 v104, s34, v104
	v_mul_f32_e32 v105, s34, v105
	v_mul_f32_e32 v102, s34, v102
	v_mul_f32_e32 v103, s34, v103
	v_mul_f32_e32 v108, s34, v100
	v_mul_f32_e32 v109, s34, v101
	v_mul_f32_e32 v100, s34, v98
	v_mul_f32_e32 v101, s34, v99
	v_cvt_pk_bf16_f32 v98, v102, v103
	v_cvt_pk_bf16_f32 v99, v104, v105
	v_cvt_pk_bf16_f32 v100, v100, v101
	v_cvt_pk_bf16_f32 v101, v108, v109
	global_store_dwordx4 v[106:107], v[98:101], off offset:256
	v_or_b32_e32 v102, s6, v152
	v_cmp_gt_i32_e32 vcc, s91, v102
	v_mov_b32_e32 v98, s7
	v_cndmask_b32_e64 v98, v152, v98, s[38:39]
	v_lshlrev_b32_e32 v98, 3, v98
	v_mov_b32_e32 v99, v1
	v_lshlrev_b64 v[100:101], 2, v[98:99]
	s_and_b64 s[18:19], s[68:69], vcc
	v_lshl_add_u64 v[98:99], v[140:141], 0, v[100:101]
	v_lshl_add_u64 v[100:101], v[142:143], 0, v[100:101]
	s_and_saveexec_b64 s[4:5], s[18:19]
	s_cbranch_execz .LBB0_975
	global_load_dwordx4 v[104:107], v[100:101], off
	global_load_dwordx4 v[108:111], v[98:99], off
	s_waitcnt vmcnt(0)
	v_mul_f32_e32 v112, v92, v106
	v_mul_f32_e32 v113, v93, v107
	v_mul_f32_e32 v114, v90, v104
	v_mul_f32_e32 v115, v91, v105
	v_mul_f32_e32 v106, v96, v106
	v_mul_f32_e32 v107, v97, v107
	v_mul_f32_e32 v104, v94, v104
	v_mul_f32_e32 v105, v95, v105
	v_fma_f32 v96, v96, v110, -v112
	v_fma_f32 v97, v97, v111, -v113
	v_fma_f32 v94, v94, v108, -v114
	v_fma_f32 v95, v95, v109, -v115
	v_fma_f32 v92, v92, v110, v106
	v_fma_f32 v93, v93, v111, v107
	v_fma_f32 v90, v90, v108, v104
	v_fma_f32 v91, v91, v109, v105
.LBB0_975:
	s_or_b64 exec, exec, s[4:5]
	v_mul_f32_e32 v94, s34, v94
	v_mul_f32_e32 v95, s34, v95
	v_mul_f32_e32 v90, s34, v90
	v_mul_f32_e32 v91, s34, v91
	v_mul_f32_e32 v104, s34, v92
	v_mul_f32_e32 v105, s34, v93
	v_cvt_pk_bf16_f32 v92, v94, v95
	v_cvt_pk_bf16_f32 v94, v90, v91
	v_mov_b64_e32 v[90:91], s[0:1]
	s_movk_i32 s4, 0x600
	v_mad_i64_i32 v[90:91], s[4:5], v102, s4, v[90:91]
	v_mul_f32_e32 v96, s34, v96
	v_mul_f32_e32 v97, s34, v97
	v_lshl_add_u64 v[90:91], s[48:49], 1, v[90:91]
	v_cvt_pk_bf16_f32 v93, v96, v97
	v_cvt_pk_bf16_f32 v95, v104, v105
	v_lshl_add_u64 v[90:91], v[90:91], 0, v[0:1]
	s_and_b64 s[18:19], s[72:73], vcc
	global_store_dwordx4 v[90:91], v[92:95], off
	s_and_saveexec_b64 s[4:5], s[18:19]
	s_cbranch_execz .LBB0_977
	global_load_dwordx4 v[92:95], v[100:101], off
	s_nop 0
	global_load_dwordx4 v[96:99], v[98:99], off
	s_waitcnt vmcnt(0)
	v_mul_f32_e32 v100, v84, v94
	v_mul_f32_e32 v101, v85, v95
	v_mul_f32_e32 v102, v82, v92
	v_mul_f32_e32 v103, v83, v93
	v_mul_f32_e32 v94, v88, v94
	v_mul_f32_e32 v95, v89, v95
	v_mul_f32_e32 v92, v86, v92
	v_mul_f32_e32 v93, v87, v93
	v_fma_f32 v88, v88, v98, -v100
	v_fma_f32 v89, v89, v99, -v101
	v_fma_f32 v86, v86, v96, -v102
	v_fma_f32 v87, v87, v97, -v103
	v_fma_f32 v84, v84, v98, v94
	v_fma_f32 v85, v85, v99, v95
	v_fma_f32 v82, v82, v96, v92
	v_fma_f32 v83, v83, v97, v93
.LBB0_977:
	s_or_b64 exec, exec, s[4:5]
	v_mul_f32_e32 v88, s34, v88
	v_mul_f32_e32 v89, s34, v89
	v_mul_f32_e32 v86, s34, v86
	v_mul_f32_e32 v87, s34, v87
	v_mul_f32_e32 v92, s34, v84
	v_mul_f32_e32 v93, s34, v85
	v_mul_f32_e32 v84, s34, v82
	v_mul_f32_e32 v85, s34, v83
	v_cvt_pk_bf16_f32 v82, v86, v87
	v_cvt_pk_bf16_f32 v83, v88, v89
	v_cvt_pk_bf16_f32 v84, v84, v85
	v_cvt_pk_bf16_f32 v85, v92, v93
	global_store_dwordx4 v[90:91], v[82:85], off offset:256
	v_or_b32_e32 v86, s6, v153
	v_cmp_gt_i32_e32 vcc, s91, v86
	v_mov_b32_e32 v82, s7
	v_cndmask_b32_e64 v82, v153, v82, s[38:39]
	v_lshlrev_b32_e32 v82, 3, v82
	v_mov_b32_e32 v83, v1
	v_lshlrev_b64 v[84:85], 2, v[82:83]
	s_and_b64 s[18:19], s[68:69], vcc
	v_lshl_add_u64 v[82:83], v[140:141], 0, v[84:85]
	v_lshl_add_u64 v[84:85], v[142:143], 0, v[84:85]
	s_and_saveexec_b64 s[4:5], s[18:19]
	s_cbranch_execz .LBB0_979
	global_load_dwordx4 v[88:91], v[84:85], off
	global_load_dwordx4 v[92:95], v[82:83], off
	s_waitcnt vmcnt(0)
	v_mul_f32_e32 v96, v76, v90
	v_mul_f32_e32 v97, v77, v91
	v_mul_f32_e32 v98, v74, v88
	v_mul_f32_e32 v99, v75, v89
	v_mul_f32_e32 v90, v80, v90
	v_mul_f32_e32 v91, v81, v91
	v_mul_f32_e32 v88, v78, v88
	v_mul_f32_e32 v89, v79, v89
	v_fma_f32 v80, v80, v94, -v96
	v_fma_f32 v81, v81, v95, -v97
	v_fma_f32 v78, v78, v92, -v98
	v_fma_f32 v79, v79, v93, -v99
	v_fma_f32 v76, v76, v94, v90
	v_fma_f32 v77, v77, v95, v91
	v_fma_f32 v74, v74, v92, v88
	v_fma_f32 v75, v75, v93, v89
.LBB0_979:
	s_or_b64 exec, exec, s[4:5]
	v_mul_f32_e32 v78, s34, v78
	v_mul_f32_e32 v79, s34, v79
	v_mul_f32_e32 v74, s34, v74
	v_mul_f32_e32 v75, s34, v75
	v_mul_f32_e32 v88, s34, v76
	v_mul_f32_e32 v89, s34, v77
	v_cvt_pk_bf16_f32 v76, v78, v79
	v_cvt_pk_bf16_f32 v78, v74, v75
	v_mov_b64_e32 v[74:75], s[0:1]
	s_movk_i32 s4, 0x600
	v_mad_i64_i32 v[74:75], s[4:5], v86, s4, v[74:75]
	v_mul_f32_e32 v80, s34, v80
	v_mul_f32_e32 v81, s34, v81
	v_lshl_add_u64 v[74:75], s[48:49], 1, v[74:75]
	v_cvt_pk_bf16_f32 v77, v80, v81
	v_cvt_pk_bf16_f32 v79, v88, v89
	v_lshl_add_u64 v[74:75], v[74:75], 0, v[0:1]
	s_and_b64 s[18:19], s[72:73], vcc
	global_store_dwordx4 v[74:75], v[76:79], off
	s_and_saveexec_b64 s[4:5], s[18:19]
	s_cbranch_execz .LBB0_981
	global_load_dwordx4 v[76:79], v[84:85], off
	s_nop 0
	global_load_dwordx4 v[80:83], v[82:83], off
	s_waitcnt vmcnt(0)
	v_mul_f32_e32 v84, v68, v78
	v_mul_f32_e32 v85, v69, v79
	v_mul_f32_e32 v86, v66, v76
	v_mul_f32_e32 v87, v67, v77
	v_mul_f32_e32 v78, v72, v78
	v_mul_f32_e32 v79, v73, v79
	v_mul_f32_e32 v76, v70, v76
	v_mul_f32_e32 v77, v71, v77
	v_fma_f32 v72, v72, v82, -v84
	v_fma_f32 v73, v73, v83, -v85
	v_fma_f32 v70, v70, v80, -v86
	v_fma_f32 v71, v71, v81, -v87
	v_fma_f32 v68, v68, v82, v78
	v_fma_f32 v69, v69, v83, v79
	v_fma_f32 v66, v66, v80, v76
	v_fma_f32 v67, v67, v81, v77
; __device__ __forceinline__ unsigned pk2(float lo, float hi) { f32x2_t v = {lo, hi}; bf16x2_t b = __builtin_convertvector(v, bf16x2_t); return __builtin_bit_cast(unsigned, b); }
;     __device__ __forceinline__ void operator()(const f32x4 (&acc)[2][2][4][2], const pg8::Unit& u, int wr, int wc, int fr, int fq) const {
;     ...
;                 const int row = u.pm * 256 + ai * 128 + wr * 64 + m * 16 + fr;
;                 const bool lat = row < TL; const int t = row & (SEQ - 1), pr = t >> 6, pc = t & 63;
; #pragma unroll
;                 for (int bj = 0; bj < 2; ++bj) {
;                     const int cg = (u.pn * 256 + bj * 128 + wc * 32) >> 5;
;                     f32x4 v0 = acc[ai][bj][m][0], v1 = acc[ai][bj][m][1];
;                     bool r16 = false, r8 = false; float sc = 1.f;
;                     if (IS_UQ) { r8 = (cg % 3) == 2; sc = MLA_C2; }
;                     else { r16 = cg < 32; r8 = cg == 84; if (cg >= 16 && cg < 32) sc = 0.125f; }
;                     if (r16 && lat) {
;                         const int pos = (cg & 1) ? pc : pr;
;                         const f32x4 cs = *(const f32x4*)(rt16c + pos * 16 + 4 * fq), sn = *(const f32x4*)(rt16s + pos * 16 + 4 * fq);
;                         const f32x4 o0 = v0 * cs - v1 * sn, o1 = v1 * cs + v0 * sn; v0 = o0; v1 = o1;
;                     }
;                     if (r8 && lat) {
;                         const int pos = (fq >> 1) ? pc : pr;
;                         const f32x4 cs = *(const f32x4*)(rt8c + pos * 8 + 4 * (fq & 1)), sn = *(const f32x4*)(rt8s + pos * 8 + 4 * (fq & 1));
;                         const f32x4 o0 = v0 * cs - v1 * sn, o1 = v1 * cs + v0 * sn; v0 = o0; v1 = o1;
;                     }
;                     v0 = v0 * sc; v1 = v1 * sc;
;                     u32x4 w; w.x = pk2(v0[0], v0[1]); w.y = pk2(v0[2], v0[3]); w.z = pk2(v1[0], v1[1]); w.w = pk2(v1[2], v1[3]);
;                     *(u32x4*)(O + (size_t)row * LDC + cg * 32 + 8 * fq) = w;
.LBB0_981:
	s_or_b64 exec, exec, s[4:5]
	v_mul_f32_e32 v72, s34, v72
	v_mul_f32_e32 v73, s34, v73
	v_mul_f32_e32 v70, s34, v70
	v_mul_f32_e32 v71, s34, v71
	v_mul_f32_e32 v76, s34, v68
	v_mul_f32_e32 v77, s34, v69
	v_mul_f32_e32 v68, s34, v66
	v_mul_f32_e32 v69, s34, v67
	s_add_i32 s7, s6, 0x80
	v_cvt_pk_bf16_f32 v66, v70, v71
	v_cvt_pk_bf16_f32 v67, v72, v73
	v_cvt_pk_bf16_f32 v68, v68, v69
	v_cvt_pk_bf16_f32 v69, v76, v77
	s_bfe_u32 s6, s7, 0x70006
	global_store_dwordx4 v[74:75], v[66:69], off offset:256
	v_or_b32_e32 v70, s7, v139
	v_cmp_gt_i32_e32 vcc, s91, v70
	v_mov_b32_e32 v66, s6
	v_cndmask_b32_e64 v66, v139, v66, s[38:39]
	v_lshlrev_b32_e32 v66, 3, v66
	v_mov_b32_e32 v67, v1
	v_lshlrev_b64 v[68:69], 2, v[66:67]
	s_and_b64 s[18:19], s[68:69], vcc
	v_lshl_add_u64 v[66:67], v[140:141], 0, v[68:69]
	v_lshl_add_u64 v[68:69], v[142:143], 0, v[68:69]
	s_and_saveexec_b64 s[4:5], s[18:19]
	s_cbranch_execz .LBB0_983
	global_load_dwordx4 v[72:75], v[68:69], off
	global_load_dwordx4 v[76:79], v[66:67], off
	s_waitcnt vmcnt(0)
	v_mul_f32_e32 v80, v60, v74
	v_mul_f32_e32 v81, v61, v75
	v_mul_f32_e32 v82, v58, v72
	v_mul_f32_e32 v83, v59, v73
	v_mul_f32_e32 v74, v64, v74
	v_mul_f32_e32 v75, v65, v75
	v_mul_f32_e32 v72, v62, v72
	v_mul_f32_e32 v73, v63, v73
	v_fma_f32 v64, v64, v78, -v80
	v_fma_f32 v65, v65, v79, -v81
	v_fma_f32 v62, v62, v76, -v82
	v_fma_f32 v63, v63, v77, -v83
	v_fma_f32 v60, v60, v78, v74
	v_fma_f32 v61, v61, v79, v75
	v_fma_f32 v58, v58, v76, v72
	v_fma_f32 v59, v59, v77, v73
.LBB0_983:
	s_or_b64 exec, exec, s[4:5]
	v_mul_f32_e32 v62, s34, v62
	v_mul_f32_e32 v63, s34, v63
	v_mul_f32_e32 v58, s34, v58
	v_mul_f32_e32 v59, s34, v59
	v_mul_f32_e32 v72, s34, v60
	v_mul_f32_e32 v73, s34, v61
	v_cvt_pk_bf16_f32 v60, v62, v63
	v_cvt_pk_bf16_f32 v62, v58, v59
	v_mov_b64_e32 v[58:59], s[0:1]
	s_movk_i32 s4, 0x600
	v_mad_i64_i32 v[58:59], s[4:5], v70, s4, v[58:59]
	v_mul_f32_e32 v64, s34, v64
	v_mul_f32_e32 v65, s34, v65
	v_lshl_add_u64 v[58:59], s[48:49], 1, v[58:59]
	v_cvt_pk_bf16_f32 v61, v64, v65
	v_cvt_pk_bf16_f32 v63, v72, v73
	v_lshl_add_u64 v[58:59], v[58:59], 0, v[0:1]
	s_and_b64 s[18:19], s[72:73], vcc
	global_store_dwordx4 v[58:59], v[60:63], off
	s_and_saveexec_b64 s[4:5], s[18:19]
	s_cbranch_execz .LBB0_985
	global_load_dwordx4 v[60:63], v[68:69], off
	s_nop 0
	global_load_dwordx4 v[64:67], v[66:67], off
	s_waitcnt vmcnt(0)
	v_mul_f32_e32 v68, v52, v62
	v_mul_f32_e32 v69, v53, v63
	v_mul_f32_e32 v70, v50, v60
	v_mul_f32_e32 v71, v51, v61
	v_mul_f32_e32 v62, v56, v62
	v_mul_f32_e32 v63, v57, v63
	v_mul_f32_e32 v60, v54, v60
	v_mul_f32_e32 v61, v55, v61
	v_fma_f32 v56, v56, v66, -v68
	v_fma_f32 v57, v57, v67, -v69
	v_fma_f32 v54, v54, v64, -v70
	v_fma_f32 v55, v55, v65, -v71
	v_fma_f32 v52, v52, v66, v62
	v_fma_f32 v53, v53, v67, v63
	v_fma_f32 v50, v50, v64, v60
	v_fma_f32 v51, v51, v65, v61
.LBB0_985:
	s_or_b64 exec, exec, s[4:5]
	v_mul_f32_e32 v56, s34, v56
	v_mul_f32_e32 v57, s34, v57
	v_mul_f32_e32 v54, s34, v54
	v_mul_f32_e32 v55, s34, v55
	v_mul_f32_e32 v60, s34, v52
	v_mul_f32_e32 v61, s34, v53
	v_mul_f32_e32 v52, s34, v50
	v_mul_f32_e32 v53, s34, v51
	v_cvt_pk_bf16_f32 v50, v54, v55
	v_cvt_pk_bf16_f32 v51, v56, v57
	v_cvt_pk_bf16_f32 v52, v52, v53
	v_cvt_pk_bf16_f32 v53, v60, v61
	global_store_dwordx4 v[58:59], v[50:53], off offset:256
	v_or_b32_e32 v54, s7, v151
	v_cmp_gt_i32_e32 vcc, s91, v54
	v_mov_b32_e32 v50, s6
	v_cndmask_b32_e64 v50, v151, v50, s[38:39]
	v_lshlrev_b32_e32 v50, 3, v50
	v_mov_b32_e32 v51, v1
	v_lshlrev_b64 v[52:53], 2, v[50:51]
	s_and_b64 s[18:19], s[68:69], vcc
	v_lshl_add_u64 v[50:51], v[140:141], 0, v[52:53]
	v_lshl_add_u64 v[52:53], v[142:143], 0, v[52:53]
	s_and_saveexec_b64 s[4:5], s[18:19]
	s_cbranch_execz .LBB0_987
	global_load_dwordx4 v[56:59], v[52:53], off
	global_load_dwordx4 v[60:63], v[50:51], off
	s_waitcnt vmcnt(0)
	v_mul_f32_e32 v64, v44, v58
	v_mul_f32_e32 v65, v45, v59
	v_mul_f32_e32 v66, v42, v56
	v_mul_f32_e32 v67, v43, v57
	v_mul_f32_e32 v58, v48, v58
	v_mul_f32_e32 v59, v49, v59
	v_mul_f32_e32 v56, v46, v56
	v_mul_f32_e32 v57, v47, v57
	v_fma_f32 v48, v48, v62, -v64
	v_fma_f32 v49, v49, v63, -v65
	v_fma_f32 v46, v46, v60, -v66
	v_fma_f32 v47, v47, v61, -v67
	v_fma_f32 v44, v44, v62, v58
	v_fma_f32 v45, v45, v63, v59
	v_fma_f32 v42, v42, v60, v56
	v_fma_f32 v43, v43, v61, v57
.LBB0_987:
	s_or_b64 exec, exec, s[4:5]
	v_mul_f32_e32 v46, s34, v46
	v_mul_f32_e32 v47, s34, v47
	v_mul_f32_e32 v42, s34, v42
	v_mul_f32_e32 v43, s34, v43
	v_mul_f32_e32 v56, s34, v44
	v_mul_f32_e32 v57, s34, v45
	v_cvt_pk_bf16_f32 v44, v46, v47
	v_cvt_pk_bf16_f32 v46, v42, v43
	v_mov_b64_e32 v[42:43], s[0:1]
	s_movk_i32 s4, 0x600
	v_mad_i64_i32 v[42:43], s[4:5], v54, s4, v[42:43]
	v_mul_f32_e32 v48, s34, v48
	v_mul_f32_e32 v49, s34, v49
	v_lshl_add_u64 v[42:43], s[48:49], 1, v[42:43]
	v_cvt_pk_bf16_f32 v45, v48, v49
	v_cvt_pk_bf16_f32 v47, v56, v57
	v_lshl_add_u64 v[42:43], v[42:43], 0, v[0:1]
	s_and_b64 s[18:19], s[72:73], vcc
	global_store_dwordx4 v[42:43], v[44:47], off
	s_and_saveexec_b64 s[4:5], s[18:19]
	s_cbranch_execz .LBB0_989
	global_load_dwordx4 v[44:47], v[52:53], off
	s_nop 0
	global_load_dwordx4 v[48:51], v[50:51], off
	s_waitcnt vmcnt(0)
	v_mul_f32_e32 v52, v36, v46
	v_mul_f32_e32 v53, v37, v47
	v_mul_f32_e32 v54, v34, v44
	v_mul_f32_e32 v55, v35, v45
	v_mul_f32_e32 v46, v40, v46
	v_mul_f32_e32 v47, v41, v47
	v_mul_f32_e32 v44, v38, v44
	v_mul_f32_e32 v45, v39, v45
	v_fma_f32 v40, v40, v50, -v52
	v_fma_f32 v41, v41, v51, -v53
	v_fma_f32 v38, v38, v48, -v54
	v_fma_f32 v39, v39, v49, -v55
	v_fma_f32 v36, v36, v50, v46
	v_fma_f32 v37, v37, v51, v47
	v_fma_f32 v34, v34, v48, v44
	v_fma_f32 v35, v35, v49, v45
; __device__ __forceinline__ unsigned pk2(float lo, float hi) { f32x2_t v = {lo, hi}; bf16x2_t b = __builtin_convertvector(v, bf16x2_t); return __builtin_bit_cast(unsigned, b); }
;     __device__ __forceinline__ void operator()(const f32x4 (&acc)[2][2][4][2], const pg8::Unit& u, int wr, int wc, int fr, int fq) const {
;     ...
;                 const int row = u.pm * 256 + ai * 128 + wr * 64 + m * 16 + fr;
;                 const bool lat = row < TL; const int t = row & (SEQ - 1), pr = t >> 6, pc = t & 63;
; #pragma unroll
;                 for (int bj = 0; bj < 2; ++bj) {
;                     const int cg = (u.pn * 256 + bj * 128 + wc * 32) >> 5;
;                     f32x4 v0 = acc[ai][bj][m][0], v1 = acc[ai][bj][m][1];
;                     bool r16 = false, r8 = false; float sc = 1.f;
;                     if (IS_UQ) { r8 = (cg % 3) == 2; sc = MLA_C2; }
;                     else { r16 = cg < 32; r8 = cg == 84; if (cg >= 16 && cg < 32) sc = 0.125f; }
;                     if (r16 && lat) {
;                         const int pos = (cg & 1) ? pc : pr;
;                         const f32x4 cs = *(const f32x4*)(rt16c + pos * 16 + 4 * fq), sn = *(const f32x4*)(rt16s + pos * 16 + 4 * fq);
;                         const f32x4 o0 = v0 * cs - v1 * sn, o1 = v1 * cs + v0 * sn; v0 = o0; v1 = o1;
;                     }
;                     if (r8 && lat) {
;                         const int pos = (fq >> 1) ? pc : pr;
;                         const f32x4 cs = *(const f32x4*)(rt8c + pos * 8 + 4 * (fq & 1)), sn = *(const f32x4*)(rt8s + pos * 8 + 4 * (fq & 1));
;                         const f32x4 o0 = v0 * cs - v1 * sn, o1 = v1 * cs + v0 * sn; v0 = o0; v1 = o1;
;                     }
;                     v0 = v0 * sc; v1 = v1 * sc;
;                     u32x4 w; w.x = pk2(v0[0], v0[1]); w.y = pk2(v0[2], v0[3]); w.z = pk2(v1[0], v1[1]); w.w = pk2(v1[2], v1[3]);
;                     *(u32x4*)(O + (size_t)row * LDC + cg * 32 + 8 * fq) = w;
.LBB0_989:
	s_or_b64 exec, exec, s[4:5]
	v_mul_f32_e32 v40, s34, v40
	v_mul_f32_e32 v41, s34, v41
	v_mul_f32_e32 v38, s34, v38
	v_mul_f32_e32 v39, s34, v39
	v_mul_f32_e32 v44, s34, v36
	v_mul_f32_e32 v45, s34, v37
	v_mul_f32_e32 v36, s34, v34
	v_mul_f32_e32 v37, s34, v35
	v_cvt_pk_bf16_f32 v34, v38, v39
	v_cvt_pk_bf16_f32 v35, v40, v41
	v_cvt_pk_bf16_f32 v36, v36, v37
	v_cvt_pk_bf16_f32 v37, v44, v45
	global_store_dwordx4 v[42:43], v[34:37], off offset:256
	v_or_b32_e32 v38, s7, v152
	v_cmp_gt_i32_e32 vcc, s91, v38
	v_mov_b32_e32 v34, s6
	v_cndmask_b32_e64 v34, v152, v34, s[38:39]
	v_lshlrev_b32_e32 v34, 3, v34
	v_mov_b32_e32 v35, v1
	v_lshlrev_b64 v[36:37], 2, v[34:35]
	s_and_b64 s[18:19], s[68:69], vcc
	v_lshl_add_u64 v[34:35], v[140:141], 0, v[36:37]
	v_lshl_add_u64 v[36:37], v[142:143], 0, v[36:37]
	s_and_saveexec_b64 s[4:5], s[18:19]
	s_cbranch_execz .LBB0_991
	global_load_dwordx4 v[40:43], v[36:37], off
	global_load_dwordx4 v[44:47], v[34:35], off
	s_waitcnt vmcnt(0)
	v_mul_f32_e32 v48, v28, v42
	v_mul_f32_e32 v49, v29, v43
	v_mul_f32_e32 v50, v26, v40
	v_mul_f32_e32 v51, v27, v41
	v_mul_f32_e32 v42, v32, v42
	v_mul_f32_e32 v43, v33, v43
	v_mul_f32_e32 v40, v30, v40
	v_mul_f32_e32 v41, v31, v41
	v_fma_f32 v32, v32, v46, -v48
	v_fma_f32 v33, v33, v47, -v49
	v_fma_f32 v30, v30, v44, -v50
	v_fma_f32 v31, v31, v45, -v51
	v_fma_f32 v28, v28, v46, v42
	v_fma_f32 v29, v29, v47, v43
	v_fma_f32 v26, v26, v44, v40
	v_fma_f32 v27, v27, v45, v41
.LBB0_991:
	s_or_b64 exec, exec, s[4:5]
	v_mul_f32_e32 v30, s34, v30
	v_mul_f32_e32 v31, s34, v31
	v_mul_f32_e32 v26, s34, v26
	v_mul_f32_e32 v27, s34, v27
	v_mul_f32_e32 v40, s34, v28
	v_mul_f32_e32 v41, s34, v29
	v_cvt_pk_bf16_f32 v28, v30, v31
	v_cvt_pk_bf16_f32 v30, v26, v27
	v_mov_b64_e32 v[26:27], s[0:1]
	s_movk_i32 s4, 0x600
	v_mad_i64_i32 v[26:27], s[4:5], v38, s4, v[26:27]
	v_mul_f32_e32 v32, s34, v32
	v_mul_f32_e32 v33, s34, v33
	v_lshl_add_u64 v[26:27], s[48:49], 1, v[26:27]
	v_cvt_pk_bf16_f32 v29, v32, v33
	v_cvt_pk_bf16_f32 v31, v40, v41
	v_lshl_add_u64 v[26:27], v[26:27], 0, v[0:1]
	s_and_b64 s[18:19], s[72:73], vcc
	global_store_dwordx4 v[26:27], v[28:31], off
	s_and_saveexec_b64 s[4:5], s[18:19]
	s_cbranch_execz .LBB0_993
	global_load_dwordx4 v[28:31], v[36:37], off
	s_nop 0
	global_load_dwordx4 v[32:35], v[34:35], off
	s_waitcnt vmcnt(0)
	v_mul_f32_e32 v36, v20, v30
	v_mul_f32_e32 v37, v21, v31
	v_mul_f32_e32 v38, v18, v28
	v_mul_f32_e32 v39, v19, v29
	v_mul_f32_e32 v30, v24, v30
	v_mul_f32_e32 v31, v25, v31
	v_mul_f32_e32 v28, v22, v28
	v_mul_f32_e32 v29, v23, v29
	v_fma_f32 v24, v24, v34, -v36
	v_fma_f32 v25, v25, v35, -v37
	v_fma_f32 v22, v22, v32, -v38
	v_fma_f32 v23, v23, v33, -v39
	v_fma_f32 v20, v20, v34, v30
	v_fma_f32 v21, v21, v35, v31
	v_fma_f32 v18, v18, v32, v28
	v_fma_f32 v19, v19, v33, v29
.LBB0_993:
	s_or_b64 exec, exec, s[4:5]
	v_mul_f32_e32 v24, s34, v24
	v_mul_f32_e32 v25, s34, v25
	v_mul_f32_e32 v22, s34, v22
	v_mul_f32_e32 v23, s34, v23
	v_mul_f32_e32 v28, s34, v20
	v_mul_f32_e32 v29, s34, v21
	v_mul_f32_e32 v20, s34, v18
	v_mul_f32_e32 v21, s34, v19
	v_cvt_pk_bf16_f32 v18, v22, v23
	v_cvt_pk_bf16_f32 v19, v24, v25
	v_cvt_pk_bf16_f32 v20, v20, v21
	v_cvt_pk_bf16_f32 v21, v28, v29
	global_store_dwordx4 v[26:27], v[18:21], off offset:256
	v_or_b32_e32 v22, s7, v153
	v_cmp_gt_i32_e32 vcc, s91, v22
	v_mov_b32_e32 v18, s6
	v_cndmask_b32_e64 v18, v153, v18, s[38:39]
	v_lshlrev_b32_e32 v18, 3, v18
	v_mov_b32_e32 v19, v1
	v_lshlrev_b64 v[20:21], 2, v[18:19]
	s_and_b64 s[6:7], s[68:69], vcc
	v_lshl_add_u64 v[18:19], v[140:141], 0, v[20:21]
	v_lshl_add_u64 v[20:21], v[142:143], 0, v[20:21]
	s_and_saveexec_b64 s[4:5], s[6:7]
	s_cbranch_execz .LBB0_995
	global_load_dwordx4 v[24:27], v[20:21], off
	global_load_dwordx4 v[28:31], v[18:19], off
	s_waitcnt vmcnt(0)
	v_mul_f32_e32 v32, v12, v26
	v_mul_f32_e32 v33, v13, v27
	v_mul_f32_e32 v34, v10, v24
	v_mul_f32_e32 v35, v11, v25
	v_mul_f32_e32 v26, v16, v26
	v_mul_f32_e32 v27, v17, v27
	v_mul_f32_e32 v24, v14, v24
	v_mul_f32_e32 v25, v15, v25
	v_fma_f32 v16, v16, v30, -v32
	v_fma_f32 v17, v17, v31, -v33
	v_fma_f32 v14, v14, v28, -v34
	v_fma_f32 v15, v15, v29, -v35
	v_fma_f32 v12, v12, v30, v26
	v_fma_f32 v13, v13, v31, v27
	v_fma_f32 v10, v10, v28, v24
	v_fma_f32 v11, v11, v29, v25
.LBB0_995:
	s_or_b64 exec, exec, s[4:5]
	v_mul_f32_e32 v14, s34, v14
	v_mul_f32_e32 v15, s34, v15
	v_mul_f32_e32 v10, s34, v10
	v_mul_f32_e32 v11, s34, v11
	v_mul_f32_e32 v24, s34, v12
	v_mul_f32_e32 v25, s34, v13
	v_cvt_pk_bf16_f32 v12, v14, v15
	v_cvt_pk_bf16_f32 v14, v10, v11
	v_mov_b64_e32 v[10:11], s[0:1]
	s_movk_i32 s4, 0x600
	v_mad_i64_i32 v[10:11], s[4:5], v22, s4, v[10:11]
	v_mul_f32_e32 v16, s34, v16
	v_mul_f32_e32 v17, s34, v17
	v_lshl_add_u64 v[10:11], s[48:49], 1, v[10:11]
	v_cvt_pk_bf16_f32 v13, v16, v17
	v_cvt_pk_bf16_f32 v15, v24, v25
	v_lshl_add_u64 v[10:11], v[10:11], 0, v[0:1]
	s_and_b64 s[6:7], s[72:73], vcc
	global_store_dwordx4 v[10:11], v[12:15], off
	s_and_saveexec_b64 s[4:5], s[6:7]
	s_cbranch_execz .LBB0_997
	global_load_dwordx4 v[12:15], v[20:21], off
	s_nop 0
	global_load_dwordx4 v[16:19], v[18:19], off
	s_waitcnt vmcnt(0)
	v_mul_f32_e32 v20, v4, v14
	v_mul_f32_e32 v21, v5, v15
	v_mul_f32_e32 v22, v2, v12
	v_mul_f32_e32 v23, v3, v13
	v_mul_f32_e32 v14, v8, v14
	v_mul_f32_e32 v15, v9, v15
	v_mul_f32_e32 v12, v6, v12
	v_mul_f32_e32 v13, v7, v13
	v_fma_f32 v8, v8, v18, -v20
	v_fma_f32 v9, v9, v19, -v21
	v_fma_f32 v6, v6, v16, -v22
	v_fma_f32 v7, v7, v17, -v23
	v_fma_f32 v4, v4, v18, v14
	v_fma_f32 v5, v5, v19, v15
	v_fma_f32 v2, v2, v16, v12
	v_fma_f32 v3, v3, v17, v13
.LBB0_997:
	s_or_b64 exec, exec, s[4:5]
	v_mul_f32_e32 v8, s34, v8
	v_mul_f32_e32 v9, s34, v9
	v_mul_f32_e32 v6, s34, v6
	v_mul_f32_e32 v7, s34, v7
	v_mul_f32_e32 v12, s34, v4
	v_mul_f32_e32 v13, s34, v5
	v_mul_f32_e32 v4, s34, v2
	v_mul_f32_e32 v5, s34, v3
	v_cvt_pk_bf16_f32 v2, v6, v7
	v_cvt_pk_bf16_f32 v3, v8, v9
	v_cvt_pk_bf16_f32 v4, v4, v5
	v_cvt_pk_bf16_f32 v5, v12, v13
	s_and_b64 vcc, exec, s[40:41]
	s_mov_b64 s[4:5], -1
	global_store_dwordx4 v[10:11], v[2:5], off offset:256
	s_cbranch_vccnz .LBB0_950
	s_andn2_b64 vcc, exec, s[44:45]
	s_cbranch_vccnz .LBB0_949
	s_barrier
	s_branch .LBB0_949

; __device__ __forceinline__ unsigned pk2(float lo, float hi) { f32x2_t v = {lo, hi}; bf16x2_t b = __builtin_convertvector(v, bf16x2_t); return __builtin_bit_cast(unsigned, b); }
; __device__ __forceinline__ float bf_lo(unsigned w) { return __uint_as_float(w << 16); }
; __device__ __forceinline__ float bf_hi(unsigned w) { return __uint_as_float(w & 0xffff0000u); }
;     __device__ __forceinline__ void operator()(const f32x4 (&acc)[2][2][4][2], const pg8::Unit& u, int wr, int wc, int fr, int fq) const {
;     ...
;                     for (int i = 0; i < 4; ++i) { const size_t row = (size_t)(row0 + ai * 128 + (2 * mh + (i >> 1)) * 16); const int co = col0 + (i & 1) * 128;
;                         cw[i] = *(const u32x4*)(O + row * ldc + co); if (MODE >= 3) xw[i] = *(const u32x4*)(X + row * ldx + co); }
;                 }
; #pragma unroll
;                 for (int i = 0; i < 4; ++i) {
;                     const int m = 2 * mh + (i >> 1), bj = i & 1;
;                     bf16_t* p = O + (size_t)(row0 + ai * 128 + m * 16) * ldc + col0 + bj * 128;
;                     const f32x4 v0 = acc[ai][bj][m][0], v1 = acc[ai][bj][m][1];
;                     float v[8] = {v0[0], v0[1], v0[2], v0[3], v1[0], v1[1], v1[2], v1[3]};
;                     if (MODE != 0) {
;                         float c[8] = {bf_lo(cw[i].x), bf_hi(cw[i].x), bf_lo(cw[i].y), bf_hi(cw[i].y), bf_lo(cw[i].z), bf_hi(cw[i].z), bf_lo(cw[i].w), bf_hi(cw[i].w)};
;                         if (MODE == 1) {
; #pragma unroll
;                             for (int e = 0; e < 8; ++e) v[e] = v[e] * sigm2(v[e]) * c[e];
;                         } else if (MODE == 2) {
; #pragma unroll
;                             for (int e = 0; e < 8; ++e) v[e] = sigm2(v[e]) * c[e];
;                         } else {
;                             float x[8] = {bf_lo(xw[i].x), bf_hi(xw[i].x), bf_lo(xw[i].y), bf_hi(xw[i].y), bf_lo(xw[i].z), bf_hi(xw[i].z), bf_lo(xw[i].w), bf_hi(xw[i].w)};
; #pragma unroll
;                             for (int e = 0; e < 8; ++e) v[e] = (MODE == 4 ? 0.f : c[e]) + sigm2(v[e]) * x[e];
;                         }
;                     }
;                     u32x4 w; w.x = pk2(v[0], v[1]); w.y = pk2(v[2], v[3]); w.z = pk2(v[4], v[5]); w.w = pk2(v[6], v[7]);
;                     *(u32x4*)p = w;
.LBB0_1303:
	v_readlane_b32 s4, v254, 50
	v_lshl_or_b32 v118, s13, 8, v163
	v_readlane_b32 s5, v254, 51
	v_lshl_add_u32 v165, s22, 8, v0
	v_ashrrev_i32_e32 v119, 31, v118
	v_mov_b64_e32 v[154:155], s[4:5]
	v_mad_i64_i32 v[120:121], s[4:5], v165, s16, v[154:155]
	v_lshlrev_b64 v[156:157], 1, v[118:119]
	v_lshl_add_u64 v[160:161], v[120:121], 0, v[156:157]
	global_load_dwordx4 v[166:169], v[160:161], off
	global_load_dwordx4 v[138:141], v[160:161], off offset:256
	v_exp_f32_e64 v170, -v134
	v_exp_f32_e64 v171, -v135
	v_or_b32_e32 v118, 16, v165
	v_mad_i64_i32 v[118:119], s[4:5], v118, s16, v[154:155]
	v_add_f32_e32 v170, 1.0, v170
	v_add_f32_e32 v171, 1.0, v171
	v_rcp_f32_e32 v170, v170
	v_rcp_f32_e32 v171, v171
	v_lshl_add_u64 v[158:159], v[118:119], 0, v[156:157]
	global_load_dwordx4 v[130:133], v[158:159], off
	global_load_dwordx4 v[118:121], v[158:159], off offset:256
	s_andn2_b64 vcc, exec, s[38:39]
	v_mul_f32_e32 v134, v134, v170
	v_mul_f32_e32 v135, v135, v171
	s_mov_b32 s33, 0x10000
	s_waitcnt vmcnt(0)
	v_lshlrev_b32_e32 v172, 16, v166
	v_and_b32_e32 v173, 0xffff0000, v166
	v_exp_f32_e64 v166, -v136
	v_mul_f32_e32 v134, v134, v172
	v_mul_f32_e32 v135, v135, v173
	v_add_f32_e32 v166, 1.0, v166
	v_rcp_f32_e32 v170, v166
	v_exp_f32_e64 v166, -v137
	s_nop 0
	v_add_f32_e32 v166, 1.0, v166
	v_rcp_f32_e32 v171, v166
	v_lshlrev_b32_e32 v166, 16, v167
	v_and_b32_e32 v167, 0xffff0000, v167
	v_mul_f32_e32 v136, v136, v170
	v_mul_f32_e32 v137, v137, v171
	s_nop 0
	v_mul_f32_e32 v136, v136, v166
	v_mul_f32_e32 v137, v137, v167
	v_exp_f32_e64 v166, -v126
	v_exp_f32_e64 v167, -v127
	v_lshlrev_b32_e32 v170, 16, v168
	v_and_b32_e32 v171, 0xffff0000, v168
	v_add_f32_e32 v166, 1.0, v166
	v_add_f32_e32 v167, 1.0, v167
	v_rcp_f32_e32 v166, v166
	v_rcp_f32_e32 v167, v167
	v_lshlrev_b32_e32 v168, 16, v169
	v_and_b32_e32 v169, 0xffff0000, v169
	v_mul_f32_e32 v126, v126, v166
	v_mul_f32_e32 v127, v127, v167
	s_nop 0
	v_mul_f32_e32 v166, v126, v170
	v_mul_f32_e32 v167, v127, v171
	v_exp_f32_e64 v126, -v128
	v_exp_f32_e64 v127, -v129
	v_add_f32_e32 v126, 1.0, v126
	v_add_f32_e32 v127, 1.0, v127
	v_rcp_f32_e32 v126, v126
	v_rcp_f32_e32 v127, v127
	s_nop 0
	v_mul_f32_e32 v126, v128, v126
	v_mul_f32_e32 v127, v129, v127
	s_nop 0
	v_mul_f32_e32 v168, v126, v168
	v_mul_f32_e32 v169, v127, v169
	v_cvt_pk_bf16_f32 v126, v134, v135
	v_cvt_pk_bf16_f32 v127, v136, v137
	v_cvt_pk_bf16_f32 v128, v166, v167
	v_cvt_pk_bf16_f32 v129, v168, v169
	global_store_dwordx4 v[160:161], v[126:129], off
	s_nop 1
	v_exp_f32_e64 v126, -v122
	v_exp_f32_e64 v127, -v123
	v_lshlrev_b32_e32 v128, 16, v138
	v_and_b32_e32 v129, 0xffff0000, v138
	v_add_f32_e32 v126, 1.0, v126
	v_add_f32_e32 v127, 1.0, v127
	v_rcp_f32_e32 v126, v126
	v_rcp_f32_e32 v127, v127
	s_nop 0
	v_mul_f32_e32 v122, v122, v126
	v_mul_f32_e32 v123, v123, v127
	v_exp_f32_e64 v126, -v124
	v_exp_f32_e64 v127, -v125
	v_mul_f32_e32 v122, v122, v128
	v_mul_f32_e32 v123, v123, v129
	v_lshlrev_b32_e32 v128, 16, v139
	v_add_f32_e32 v126, 1.0, v126
	v_add_f32_e32 v127, 1.0, v127
	v_rcp_f32_e32 v126, v126
	v_rcp_f32_e32 v127, v127
	v_and_b32_e32 v129, 0xffff0000, v139
	v_mul_f32_e32 v124, v124, v126
	v_mul_f32_e32 v125, v125, v127
	v_exp_f32_e64 v126, -v114
	v_exp_f32_e64 v127, -v115
	v_mul_f32_e32 v124, v124, v128
	v_mul_f32_e32 v125, v125, v129
	v_lshlrev_b32_e32 v128, 16, v140
	v_add_f32_e32 v126, 1.0, v126
	v_add_f32_e32 v127, 1.0, v127
	v_rcp_f32_e32 v126, v126
	v_rcp_f32_e32 v127, v127
	v_and_b32_e32 v129, 0xffff0000, v140
	v_mul_f32_e32 v114, v114, v126
	v_mul_f32_e32 v115, v115, v127
	s_nop 0
	v_mul_f32_e32 v126, v114, v128
	v_mul_f32_e32 v127, v115, v129
	v_exp_f32_e64 v114, -v116
	v_exp_f32_e64 v115, -v117
	v_lshlrev_b32_e32 v128, 16, v141
	v_and_b32_e32 v129, 0xffff0000, v141
	v_add_f32_e32 v114, 1.0, v114
	v_add_f32_e32 v115, 1.0, v115
	v_rcp_f32_e32 v114, v114
	v_rcp_f32_e32 v115, v115
	s_nop 0
	v_mul_f32_e32 v114, v116, v114
	v_mul_f32_e32 v115, v117, v115
	s_nop 0
	v_mul_f32_e32 v128, v114, v128
	v_mul_f32_e32 v129, v115, v129
	v_cvt_pk_bf16_f32 v114, v122, v123
	v_cvt_pk_bf16_f32 v115, v124, v125
	v_cvt_pk_bf16_f32 v116, v126, v127
	v_cvt_pk_bf16_f32 v117, v128, v129
	global_store_dwordx4 v[160:161], v[114:117], off offset:256
	s_nop 1
	v_exp_f32_e64 v114, -v110
	v_exp_f32_e64 v115, -v111
	v_lshlrev_b32_e32 v116, 16, v130
	v_and_b32_e32 v117, 0xffff0000, v130
	v_add_f32_e32 v114, 1.0, v114
	v_add_f32_e32 v115, 1.0, v115
	v_rcp_f32_e32 v114, v114
	v_rcp_f32_e32 v115, v115
	s_nop 0
	v_mul_f32_e32 v110, v110, v114
	v_mul_f32_e32 v111, v111, v115
	v_exp_f32_e64 v114, -v112
	v_exp_f32_e64 v115, -v113
	v_mul_f32_e32 v110, v110, v116
	v_mul_f32_e32 v111, v111, v117
	v_lshlrev_b32_e32 v116, 16, v131
	v_add_f32_e32 v114, 1.0, v114
	v_add_f32_e32 v115, 1.0, v115
	v_rcp_f32_e32 v114, v114
	v_rcp_f32_e32 v115, v115
	v_and_b32_e32 v117, 0xffff0000, v131
	v_mul_f32_e32 v112, v112, v114
	v_mul_f32_e32 v113, v113, v115
	v_exp_f32_e64 v114, -v106
	v_exp_f32_e64 v115, -v107
	v_mul_f32_e32 v112, v112, v116
	v_mul_f32_e32 v113, v113, v117
	v_lshlrev_b32_e32 v116, 16, v132
	v_add_f32_e32 v114, 1.0, v114
	v_add_f32_e32 v115, 1.0, v115
	v_rcp_f32_e32 v114, v114
	v_rcp_f32_e32 v115, v115
	v_and_b32_e32 v117, 0xffff0000, v132
	v_mul_f32_e32 v106, v106, v114
	v_mul_f32_e32 v107, v107, v115
	s_nop 0
	v_mul_f32_e32 v114, v106, v116
	v_mul_f32_e32 v115, v107, v117
	v_exp_f32_e64 v106, -v108
	v_exp_f32_e64 v107, -v109
	v_lshlrev_b32_e32 v116, 16, v133
	v_and_b32_e32 v117, 0xffff0000, v133
	v_add_f32_e32 v106, 1.0, v106
	v_add_f32_e32 v107, 1.0, v107
	v_rcp_f32_e32 v106, v106
	v_rcp_f32_e32 v107, v107
	s_nop 0
	v_mul_f32_e32 v106, v108, v106
; __device__ __forceinline__ unsigned pk2(float lo, float hi) { f32x2_t v = {lo, hi}; bf16x2_t b = __builtin_convertvector(v, bf16x2_t); return __builtin_bit_cast(unsigned, b); }
; __device__ __forceinline__ float bf_lo(unsigned w) { return __uint_as_float(w << 16); }
; __device__ __forceinline__ float bf_hi(unsigned w) { return __uint_as_float(w & 0xffff0000u); }
;     __device__ __forceinline__ void operator()(const f32x4 (&acc)[2][2][4][2], const pg8::Unit& u, int wr, int wc, int fr, int fq) const {
;     ...
;                     for (int i = 0; i < 4; ++i) { const size_t row = (size_t)(row0 + ai * 128 + (2 * mh + (i >> 1)) * 16); const int co = col0 + (i & 1) * 128;
;                         cw[i] = *(const u32x4*)(O + row * ldc + co); if (MODE >= 3) xw[i] = *(const u32x4*)(X + row * ldx + co); }
;                 }
; #pragma unroll
;                 for (int i = 0; i < 4; ++i) {
;                     const int m = 2 * mh + (i >> 1), bj = i & 1;
;                     bf16_t* p = O + (size_t)(row0 + ai * 128 + m * 16) * ldc + col0 + bj * 128;
;                     const f32x4 v0 = acc[ai][bj][m][0], v1 = acc[ai][bj][m][1];
;                     float v[8] = {v0[0], v0[1], v0[2], v0[3], v1[0], v1[1], v1[2], v1[3]};
;                     if (MODE != 0) {
;                         float c[8] = {bf_lo(cw[i].x), bf_hi(cw[i].x), bf_lo(cw[i].y), bf_hi(cw[i].y), bf_lo(cw[i].z), bf_hi(cw[i].z), bf_lo(cw[i].w), bf_hi(cw[i].w)};
;                         if (MODE == 1) {
; #pragma unroll
;                             for (int e = 0; e < 8; ++e) v[e] = v[e] * sigm2(v[e]) * c[e];
;                         } else if (MODE == 2) {
; #pragma unroll
;                             for (int e = 0; e < 8; ++e) v[e] = sigm2(v[e]) * c[e];
;                         } else {
;                             float x[8] = {bf_lo(xw[i].x), bf_hi(xw[i].x), bf_lo(xw[i].y), bf_hi(xw[i].y), bf_lo(xw[i].z), bf_hi(xw[i].z), bf_lo(xw[i].w), bf_hi(xw[i].w)};
; #pragma unroll
;                             for (int e = 0; e < 8; ++e) v[e] = (MODE == 4 ? 0.f : c[e]) + sigm2(v[e]) * x[e];
;                         }
;                     }
;                     u32x4 w; w.x = pk2(v[0], v[1]); w.y = pk2(v[2], v[3]); w.z = pk2(v[4], v[5]); w.w = pk2(v[6], v[7]);
;                     *(u32x4*)p = w;
	v_mul_f32_e32 v107, v109, v107
	s_nop 0
	v_mul_f32_e32 v116, v106, v116
	v_mul_f32_e32 v117, v107, v117
	v_cvt_pk_bf16_f32 v106, v110, v111
	v_cvt_pk_bf16_f32 v107, v112, v113
	v_cvt_pk_bf16_f32 v108, v114, v115
	v_cvt_pk_bf16_f32 v109, v116, v117
	global_store_dwordx4 v[158:159], v[106:109], off
	s_nop 1
	v_exp_f32_e64 v106, -v102
	v_exp_f32_e64 v107, -v103
	v_lshlrev_b32_e32 v108, 16, v118
	v_and_b32_e32 v109, 0xffff0000, v118
	v_add_f32_e32 v106, 1.0, v106
	v_add_f32_e32 v107, 1.0, v107
	v_rcp_f32_e32 v106, v106
	v_rcp_f32_e32 v107, v107
	v_exp_f32_e64 v118, -v94
	v_mul_f32_e32 v102, v102, v106
	v_mul_f32_e32 v103, v103, v107
	v_exp_f32_e64 v106, -v104
	v_exp_f32_e64 v107, -v105
	v_mul_f32_e32 v102, v102, v108
	v_mul_f32_e32 v103, v103, v109
	v_lshlrev_b32_e32 v108, 16, v119
	v_add_f32_e32 v106, 1.0, v106
	v_add_f32_e32 v107, 1.0, v107
	v_rcp_f32_e32 v106, v106
	v_rcp_f32_e32 v107, v107
	v_and_b32_e32 v109, 0xffff0000, v119
	v_exp_f32_e64 v119, -v95
	v_add_f32_e32 v118, 1.0, v118
	v_mul_f32_e32 v104, v104, v106
	v_mul_f32_e32 v105, v105, v107
	v_exp_f32_e64 v106, -v98
	v_exp_f32_e64 v107, -v99
	v_mul_f32_e32 v104, v104, v108
	v_mul_f32_e32 v105, v105, v109
	v_lshlrev_b32_e32 v108, 16, v120
	v_add_f32_e32 v106, 1.0, v106
	v_add_f32_e32 v107, 1.0, v107
	v_rcp_f32_e32 v106, v106
	v_rcp_f32_e32 v107, v107
	v_and_b32_e32 v109, 0xffff0000, v120
	v_add_f32_e32 v119, 1.0, v119
	v_rcp_f32_e32 v118, v118
	v_mul_f32_e32 v98, v98, v106
	v_mul_f32_e32 v99, v99, v107
	v_rcp_f32_e32 v119, v119
	v_mul_f32_e32 v106, v98, v108
	v_mul_f32_e32 v107, v99, v109
	v_exp_f32_e64 v98, -v100
	v_exp_f32_e64 v99, -v101
	v_lshlrev_b32_e32 v108, 16, v121
	v_and_b32_e32 v109, 0xffff0000, v121
	v_add_f32_e32 v98, 1.0, v98
	v_add_f32_e32 v99, 1.0, v99
	v_rcp_f32_e32 v98, v98
	v_rcp_f32_e32 v99, v99
	v_mul_f32_e32 v94, v94, v118
	v_mul_f32_e32 v95, v95, v119
	v_mul_f32_e32 v98, v100, v98
	v_mul_f32_e32 v99, v101, v99
	s_nop 0
	v_mul_f32_e32 v108, v98, v108
	v_mul_f32_e32 v109, v99, v109
	v_cvt_pk_bf16_f32 v98, v102, v103
	v_cvt_pk_bf16_f32 v99, v104, v105
	v_cvt_pk_bf16_f32 v100, v106, v107
	v_cvt_pk_bf16_f32 v101, v108, v109
	global_store_dwordx4 v[158:159], v[98:101], off offset:256
	s_nop 1
	v_or_b32_e32 v98, 32, v165
	v_mad_i64_i32 v[98:99], s[4:5], v98, s16, v[154:155]
	v_lshl_add_u64 v[112:113], v[98:99], 0, v[156:157]
	global_load_dwordx4 v[114:117], v[112:113], off
	global_load_dwordx4 v[106:109], v[112:113], off offset:256
	v_or_b32_e32 v98, 48, v165
	v_mad_i64_i32 v[98:99], s[4:5], v98, s16, v[154:155]
	v_lshl_add_u64 v[110:111], v[98:99], 0, v[156:157]
	global_load_dwordx4 v[102:105], v[110:111], off
	global_load_dwordx4 v[98:101], v[110:111], off offset:256
	s_waitcnt vmcnt(3)
	v_lshlrev_b32_e32 v120, 16, v114
	v_and_b32_e32 v121, 0xffff0000, v114
	v_exp_f32_e64 v114, -v96
	v_mul_f32_e32 v94, v94, v120
	v_mul_f32_e32 v95, v95, v121
	v_add_f32_e32 v114, 1.0, v114
	v_rcp_f32_e32 v118, v114
	v_exp_f32_e64 v114, -v97
	s_nop 0
	v_add_f32_e32 v114, 1.0, v114
	v_rcp_f32_e32 v119, v114
	v_lshlrev_b32_e32 v114, 16, v115
	v_and_b32_e32 v115, 0xffff0000, v115
	v_mul_f32_e32 v96, v96, v118
	v_mul_f32_e32 v97, v97, v119
	s_nop 0
	v_mul_f32_e32 v96, v96, v114
	v_mul_f32_e32 v97, v97, v115
	v_exp_f32_e64 v114, -v90
	v_exp_f32_e64 v115, -v91
	v_lshlrev_b32_e32 v118, 16, v116
	v_and_b32_e32 v119, 0xffff0000, v116
	v_add_f32_e32 v114, 1.0, v114
	v_add_f32_e32 v115, 1.0, v115
	v_rcp_f32_e32 v114, v114
	v_rcp_f32_e32 v115, v115
	v_lshlrev_b32_e32 v116, 16, v117
	v_and_b32_e32 v117, 0xffff0000, v117
	v_mul_f32_e32 v90, v90, v114
	v_mul_f32_e32 v91, v91, v115
	s_nop 0
	v_mul_f32_e32 v114, v90, v118
	v_mul_f32_e32 v115, v91, v119
	v_exp_f32_e64 v90, -v92
	v_exp_f32_e64 v91, -v93
	v_add_f32_e32 v90, 1.0, v90
	v_add_f32_e32 v91, 1.0, v91
	v_rcp_f32_e32 v90, v90
	v_rcp_f32_e32 v91, v91
	s_nop 0
	v_mul_f32_e32 v90, v92, v90
	v_mul_f32_e32 v91, v93, v91
	s_nop 0
	v_mul_f32_e32 v116, v90, v116
	v_mul_f32_e32 v117, v91, v117
	v_cvt_pk_bf16_f32 v90, v94, v95
	v_cvt_pk_bf16_f32 v91, v96, v97
	v_cvt_pk_bf16_f32 v92, v114, v115
	v_cvt_pk_bf16_f32 v93, v116, v117
	global_store_dwordx4 v[112:113], v[90:93], off
	s_nop 1
	v_exp_f32_e64 v90, -v86
	v_exp_f32_e64 v91, -v87
	s_waitcnt vmcnt(3)
	v_lshlrev_b32_e32 v92, 16, v106
	v_and_b32_e32 v93, 0xffff0000, v106
	v_add_f32_e32 v90, 1.0, v90
	v_add_f32_e32 v91, 1.0, v91
	v_rcp_f32_e32 v90, v90
	v_rcp_f32_e32 v91, v91
	s_nop 0
	v_mul_f32_e32 v86, v86, v90
	v_mul_f32_e32 v87, v87, v91
	v_exp_f32_e64 v90, -v88
	v_exp_f32_e64 v91, -v89
	v_mul_f32_e32 v86, v86, v92
	v_mul_f32_e32 v87, v87, v93
	v_lshlrev_b32_e32 v92, 16, v107
	v_add_f32_e32 v90, 1.0, v90
	v_add_f32_e32 v91, 1.0, v91
	v_rcp_f32_e32 v90, v90
	v_rcp_f32_e32 v91, v91
	v_and_b32_e32 v93, 0xffff0000, v107
	v_mul_f32_e32 v88, v88, v90
	v_mul_f32_e32 v89, v89, v91
	v_exp_f32_e64 v90, -v82
	v_exp_f32_e64 v91, -v83
	v_mul_f32_e32 v88, v88, v92
	v_mul_f32_e32 v89, v89, v93
	v_lshlrev_b32_e32 v92, 16, v108
	v_add_f32_e32 v90, 1.0, v90
	v_add_f32_e32 v91, 1.0, v91
	v_rcp_f32_e32 v90, v90
	v_rcp_f32_e32 v91, v91
	v_and_b32_e32 v93, 0xffff0000, v108
	v_mul_f32_e32 v82, v82, v90
	v_mul_f32_e32 v83, v83, v91
	s_nop 0
	v_mul_f32_e32 v90, v82, v92
	v_mul_f32_e32 v91, v83, v93
	v_exp_f32_e64 v82, -v84
	v_exp_f32_e64 v83, -v85
	v_lshlrev_b32_e32 v92, 16, v109
	v_and_b32_e32 v93, 0xffff0000, v109
	v_add_f32_e32 v82, 1.0, v82
	v_add_f32_e32 v83, 1.0, v83
	v_rcp_f32_e32 v82, v82
	v_rcp_f32_e32 v83, v83
	s_nop 0
	v_mul_f32_e32 v82, v84, v82
	v_mul_f32_e32 v83, v85, v83
	s_nop 0
	v_mul_f32_e32 v92, v82, v92
	v_mul_f32_e32 v93, v83, v93
	v_cvt_pk_bf16_f32 v82, v86, v87
	v_cvt_pk_bf16_f32 v83, v88, v89
	v_cvt_pk_bf16_f32 v84, v90, v91
	v_cvt_pk_bf16_f32 v85, v92, v93
	global_store_dwordx4 v[112:113], v[82:85], off offset:256
	v_exp_f32_e64 v86, -v62
	v_exp_f32_e64 v87, -v63
	v_exp_f32_e64 v82, -v78
	v_exp_f32_e64 v83, -v79
	s_waitcnt vmcnt(3)
; __device__ __forceinline__ unsigned pk2(float lo, float hi) { f32x2_t v = {lo, hi}; bf16x2_t b = __builtin_convertvector(v, bf16x2_t); return __builtin_bit_cast(unsigned, b); }
; __device__ __forceinline__ float bf_lo(unsigned w) { return __uint_as_float(w << 16); }
; __device__ __forceinline__ float bf_hi(unsigned w) { return __uint_as_float(w & 0xffff0000u); }
;     __device__ __forceinline__ void operator()(const f32x4 (&acc)[2][2][4][2], const pg8::Unit& u, int wr, int wc, int fr, int fq) const {
;     ...
;                     for (int i = 0; i < 4; ++i) { const size_t row = (size_t)(row0 + ai * 128 + (2 * mh + (i >> 1)) * 16); const int co = col0 + (i & 1) * 128;
;                         cw[i] = *(const u32x4*)(O + row * ldc + co); if (MODE >= 3) xw[i] = *(const u32x4*)(X + row * ldx + co); }
;                 }
; #pragma unroll
;                 for (int i = 0; i < 4; ++i) {
;                     const int m = 2 * mh + (i >> 1), bj = i & 1;
;                     bf16_t* p = O + (size_t)(row0 + ai * 128 + m * 16) * ldc + col0 + bj * 128;
;                     const f32x4 v0 = acc[ai][bj][m][0], v1 = acc[ai][bj][m][1];
;                     float v[8] = {v0[0], v0[1], v0[2], v0[3], v1[0], v1[1], v1[2], v1[3]};
;                     if (MODE != 0) {
;                         float c[8] = {bf_lo(cw[i].x), bf_hi(cw[i].x), bf_lo(cw[i].y), bf_hi(cw[i].y), bf_lo(cw[i].z), bf_hi(cw[i].z), bf_lo(cw[i].w), bf_hi(cw[i].w)};
;                         if (MODE == 1) {
; #pragma unroll
;                             for (int e = 0; e < 8; ++e) v[e] = v[e] * sigm2(v[e]) * c[e];
;                         } else if (MODE == 2) {
; #pragma unroll
;                             for (int e = 0; e < 8; ++e) v[e] = sigm2(v[e]) * c[e];
;                         } else {
;                             float x[8] = {bf_lo(xw[i].x), bf_hi(xw[i].x), bf_lo(xw[i].y), bf_hi(xw[i].y), bf_lo(xw[i].z), bf_hi(xw[i].z), bf_lo(xw[i].w), bf_hi(xw[i].w)};
; #pragma unroll
;                             for (int e = 0; e < 8; ++e) v[e] = (MODE == 4 ? 0.f : c[e]) + sigm2(v[e]) * x[e];
;                         }
;                     }
;                     u32x4 w; w.x = pk2(v[0], v[1]); w.y = pk2(v[2], v[3]); w.z = pk2(v[4], v[5]); w.w = pk2(v[6], v[7]);
;                     *(u32x4*)p = w;
	v_lshlrev_b32_e32 v84, 16, v102
	v_and_b32_e32 v85, 0xffff0000, v102
	v_add_f32_e32 v82, 1.0, v82
	v_add_f32_e32 v83, 1.0, v83
	v_rcp_f32_e32 v82, v82
	v_rcp_f32_e32 v83, v83
	v_add_f32_e32 v86, 1.0, v86
	v_add_f32_e32 v87, 1.0, v87
	v_rcp_f32_e32 v86, v86
	v_mul_f32_e32 v78, v78, v82
	v_mul_f32_e32 v79, v79, v83
	v_exp_f32_e64 v82, -v80
	v_exp_f32_e64 v83, -v81
	v_mul_f32_e32 v78, v78, v84
	v_mul_f32_e32 v79, v79, v85
	v_lshlrev_b32_e32 v84, 16, v103
	v_add_f32_e32 v82, 1.0, v82
	v_add_f32_e32 v83, 1.0, v83
	v_rcp_f32_e32 v82, v82
	v_rcp_f32_e32 v83, v83
	v_and_b32_e32 v85, 0xffff0000, v103
	v_rcp_f32_e32 v87, v87
	v_mul_f32_e32 v80, v80, v82
	v_mul_f32_e32 v81, v81, v83
	v_exp_f32_e64 v82, -v74
	v_exp_f32_e64 v83, -v75
	v_mul_f32_e32 v80, v80, v84
	v_mul_f32_e32 v81, v81, v85
	v_lshlrev_b32_e32 v84, 16, v104
	v_add_f32_e32 v82, 1.0, v82
	v_add_f32_e32 v83, 1.0, v83
	v_rcp_f32_e32 v82, v82
	v_rcp_f32_e32 v83, v83
	v_and_b32_e32 v85, 0xffff0000, v104
	v_mul_f32_e32 v62, v62, v86
	v_mul_f32_e32 v63, v63, v87
	v_mul_f32_e32 v74, v74, v82
	v_mul_f32_e32 v75, v75, v83
	s_nop 0
	v_mul_f32_e32 v82, v74, v84
	v_mul_f32_e32 v83, v75, v85
	v_exp_f32_e64 v74, -v76
	v_exp_f32_e64 v75, -v77
	v_lshlrev_b32_e32 v84, 16, v105
	v_and_b32_e32 v85, 0xffff0000, v105
	v_add_f32_e32 v74, 1.0, v74
	v_add_f32_e32 v75, 1.0, v75
	v_rcp_f32_e32 v74, v74
	v_rcp_f32_e32 v75, v75
	s_nop 0
	v_mul_f32_e32 v74, v76, v74
	v_mul_f32_e32 v75, v77, v75
	s_nop 0
	v_mul_f32_e32 v84, v74, v84
	v_mul_f32_e32 v85, v75, v85
	v_cvt_pk_bf16_f32 v74, v78, v79
	v_cvt_pk_bf16_f32 v75, v80, v81
	v_cvt_pk_bf16_f32 v76, v82, v83
	v_cvt_pk_bf16_f32 v77, v84, v85
	global_store_dwordx4 v[110:111], v[74:77], off
	s_nop 1
	v_exp_f32_e64 v74, -v70
	v_exp_f32_e64 v75, -v71
	s_waitcnt vmcnt(3)
	v_lshlrev_b32_e32 v76, 16, v98
	v_and_b32_e32 v77, 0xffff0000, v98
	v_add_f32_e32 v74, 1.0, v74
	v_add_f32_e32 v75, 1.0, v75
	v_rcp_f32_e32 v74, v74
	v_rcp_f32_e32 v75, v75
	s_nop 0
	v_mul_f32_e32 v70, v70, v74
	v_mul_f32_e32 v71, v71, v75
	v_exp_f32_e64 v74, -v72
	v_exp_f32_e64 v75, -v73
	v_mul_f32_e32 v70, v70, v76
	v_mul_f32_e32 v71, v71, v77
	v_lshlrev_b32_e32 v76, 16, v99
	v_add_f32_e32 v74, 1.0, v74
	v_add_f32_e32 v75, 1.0, v75
	v_rcp_f32_e32 v74, v74
	v_rcp_f32_e32 v75, v75
	v_and_b32_e32 v77, 0xffff0000, v99
	v_mul_f32_e32 v72, v72, v74
	v_mul_f32_e32 v73, v73, v75
	v_exp_f32_e64 v74, -v66
	v_exp_f32_e64 v75, -v67
	v_mul_f32_e32 v72, v72, v76
	v_mul_f32_e32 v73, v73, v77
	v_lshlrev_b32_e32 v76, 16, v100
	v_add_f32_e32 v74, 1.0, v74
	v_add_f32_e32 v75, 1.0, v75
	v_rcp_f32_e32 v74, v74
	v_rcp_f32_e32 v75, v75
	v_and_b32_e32 v77, 0xffff0000, v100
	v_mul_f32_e32 v66, v66, v74
	v_mul_f32_e32 v67, v67, v75
	s_nop 0
	v_mul_f32_e32 v74, v66, v76
	v_mul_f32_e32 v75, v67, v77
	v_exp_f32_e64 v66, -v68
	v_exp_f32_e64 v67, -v69
	v_lshlrev_b32_e32 v76, 16, v101
	v_and_b32_e32 v77, 0xffff0000, v101
	v_add_f32_e32 v66, 1.0, v66
	v_add_f32_e32 v67, 1.0, v67
	v_rcp_f32_e32 v66, v66
	v_rcp_f32_e32 v67, v67
	s_nop 0
	v_mul_f32_e32 v66, v68, v66
	v_mul_f32_e32 v67, v69, v67
	s_nop 0
	v_mul_f32_e32 v76, v66, v76
	v_mul_f32_e32 v77, v67, v77
	v_cvt_pk_bf16_f32 v66, v70, v71
	v_cvt_pk_bf16_f32 v67, v72, v73
	v_cvt_pk_bf16_f32 v68, v74, v75
	v_cvt_pk_bf16_f32 v69, v76, v77
	global_store_dwordx4 v[110:111], v[66:69], off offset:256
	s_nop 1
	v_add_u32_e32 v66, 0x80, v165
	v_mad_i64_i32 v[66:67], s[4:5], v66, s16, v[154:155]
	v_lshl_add_u64 v[80:81], v[66:67], 0, v[156:157]
	global_load_dwordx4 v[82:85], v[80:81], off
	global_load_dwordx4 v[74:77], v[80:81], off offset:256
	v_add_u32_e32 v66, 0x90, v165
	v_mad_i64_i32 v[66:67], s[4:5], v66, s16, v[154:155]
	v_lshl_add_u64 v[78:79], v[66:67], 0, v[156:157]
	global_load_dwordx4 v[70:73], v[78:79], off
	global_load_dwordx4 v[66:69], v[78:79], off offset:256
	s_waitcnt vmcnt(3)
	v_lshlrev_b32_e32 v88, 16, v82
	v_and_b32_e32 v89, 0xffff0000, v82
	v_exp_f32_e64 v82, -v64
	v_mul_f32_e32 v62, v62, v88
	v_mul_f32_e32 v63, v63, v89
	v_add_f32_e32 v82, 1.0, v82
	v_rcp_f32_e32 v86, v82
	v_exp_f32_e64 v82, -v65
	s_nop 0
	v_add_f32_e32 v82, 1.0, v82
	v_rcp_f32_e32 v87, v82
	v_lshlrev_b32_e32 v82, 16, v83
	v_and_b32_e32 v83, 0xffff0000, v83
	v_mul_f32_e32 v64, v64, v86
	v_mul_f32_e32 v65, v65, v87
	s_nop 0
	v_mul_f32_e32 v64, v64, v82
	v_mul_f32_e32 v65, v65, v83
	v_exp_f32_e64 v82, -v58
	v_exp_f32_e64 v83, -v59
	v_lshlrev_b32_e32 v86, 16, v84
	v_and_b32_e32 v87, 0xffff0000, v84
	v_add_f32_e32 v82, 1.0, v82
	v_add_f32_e32 v83, 1.0, v83
	v_rcp_f32_e32 v82, v82
	v_rcp_f32_e32 v83, v83
	v_lshlrev_b32_e32 v84, 16, v85
	v_and_b32_e32 v85, 0xffff0000, v85
	v_mul_f32_e32 v58, v58, v82
	v_mul_f32_e32 v59, v59, v83
	s_nop 0
	v_mul_f32_e32 v82, v58, v86
	v_mul_f32_e32 v83, v59, v87
	v_exp_f32_e64 v58, -v60
	v_exp_f32_e64 v59, -v61
	v_add_f32_e32 v58, 1.0, v58
	v_add_f32_e32 v59, 1.0, v59
	v_rcp_f32_e32 v58, v58
	v_rcp_f32_e32 v59, v59
	s_nop 0
	v_mul_f32_e32 v58, v60, v58
	v_mul_f32_e32 v59, v61, v59
	s_nop 0
	v_mul_f32_e32 v84, v58, v84
	v_mul_f32_e32 v85, v59, v85
	v_cvt_pk_bf16_f32 v58, v62, v63
	v_cvt_pk_bf16_f32 v59, v64, v65
	v_cvt_pk_bf16_f32 v60, v82, v83
	v_cvt_pk_bf16_f32 v61, v84, v85
	global_store_dwordx4 v[80:81], v[58:61], off
	s_nop 1
	v_exp_f32_e64 v58, -v54
	v_exp_f32_e64 v59, -v55
	s_waitcnt vmcnt(3)
; __device__ __forceinline__ unsigned pk2(float lo, float hi) { f32x2_t v = {lo, hi}; bf16x2_t b = __builtin_convertvector(v, bf16x2_t); return __builtin_bit_cast(unsigned, b); }
; __device__ __forceinline__ float bf_lo(unsigned w) { return __uint_as_float(w << 16); }
; __device__ __forceinline__ float bf_hi(unsigned w) { return __uint_as_float(w & 0xffff0000u); }
;     __device__ __forceinline__ void operator()(const f32x4 (&acc)[2][2][4][2], const pg8::Unit& u, int wr, int wc, int fr, int fq) const {
;     ...
;                     for (int i = 0; i < 4; ++i) { const size_t row = (size_t)(row0 + ai * 128 + (2 * mh + (i >> 1)) * 16); const int co = col0 + (i & 1) * 128;
;                         cw[i] = *(const u32x4*)(O + row * ldc + co); if (MODE >= 3) xw[i] = *(const u32x4*)(X + row * ldx + co); }
;                 }
; #pragma unroll
;                 for (int i = 0; i < 4; ++i) {
;                     const int m = 2 * mh + (i >> 1), bj = i & 1;
;                     bf16_t* p = O + (size_t)(row0 + ai * 128 + m * 16) * ldc + col0 + bj * 128;
;                     const f32x4 v0 = acc[ai][bj][m][0], v1 = acc[ai][bj][m][1];
;                     float v[8] = {v0[0], v0[1], v0[2], v0[3], v1[0], v1[1], v1[2], v1[3]};
;                     if (MODE != 0) {
;                         float c[8] = {bf_lo(cw[i].x), bf_hi(cw[i].x), bf_lo(cw[i].y), bf_hi(cw[i].y), bf_lo(cw[i].z), bf_hi(cw[i].z), bf_lo(cw[i].w), bf_hi(cw[i].w)};
;                         if (MODE == 1) {
; #pragma unroll
;                             for (int e = 0; e < 8; ++e) v[e] = v[e] * sigm2(v[e]) * c[e];
;                         } else if (MODE == 2) {
; #pragma unroll
;                             for (int e = 0; e < 8; ++e) v[e] = sigm2(v[e]) * c[e];
;                         } else {
;                             float x[8] = {bf_lo(xw[i].x), bf_hi(xw[i].x), bf_lo(xw[i].y), bf_hi(xw[i].y), bf_lo(xw[i].z), bf_hi(xw[i].z), bf_lo(xw[i].w), bf_hi(xw[i].w)};
; #pragma unroll
;                             for (int e = 0; e < 8; ++e) v[e] = (MODE == 4 ? 0.f : c[e]) + sigm2(v[e]) * x[e];
;                         }
;                     }
;                     u32x4 w; w.x = pk2(v[0], v[1]); w.y = pk2(v[2], v[3]); w.z = pk2(v[4], v[5]); w.w = pk2(v[6], v[7]);
;                     *(u32x4*)p = w;
	v_lshlrev_b32_e32 v60, 16, v74
	v_and_b32_e32 v61, 0xffff0000, v74
	v_add_f32_e32 v58, 1.0, v58
	v_add_f32_e32 v59, 1.0, v59
	v_rcp_f32_e32 v58, v58
	v_rcp_f32_e32 v59, v59
	s_nop 0
	v_mul_f32_e32 v54, v54, v58
	v_mul_f32_e32 v55, v55, v59
	v_exp_f32_e64 v58, -v56
	v_exp_f32_e64 v59, -v57
	v_mul_f32_e32 v54, v54, v60
	v_mul_f32_e32 v55, v55, v61
	v_lshlrev_b32_e32 v60, 16, v75
	v_add_f32_e32 v58, 1.0, v58
	v_add_f32_e32 v59, 1.0, v59
	v_rcp_f32_e32 v58, v58
	v_rcp_f32_e32 v59, v59
	v_and_b32_e32 v61, 0xffff0000, v75
	v_mul_f32_e32 v56, v56, v58
	v_mul_f32_e32 v57, v57, v59
	v_exp_f32_e64 v58, -v50
	v_exp_f32_e64 v59, -v51
	v_mul_f32_e32 v56, v56, v60
	v_mul_f32_e32 v57, v57, v61
	v_lshlrev_b32_e32 v60, 16, v76
	v_add_f32_e32 v58, 1.0, v58
	v_add_f32_e32 v59, 1.0, v59
	v_rcp_f32_e32 v58, v58
	v_rcp_f32_e32 v59, v59
	v_and_b32_e32 v61, 0xffff0000, v76
	v_mul_f32_e32 v50, v50, v58
	v_mul_f32_e32 v51, v51, v59
	s_nop 0
	v_mul_f32_e32 v58, v50, v60
	v_mul_f32_e32 v59, v51, v61
	v_exp_f32_e64 v50, -v52
	v_exp_f32_e64 v51, -v53
	v_lshlrev_b32_e32 v60, 16, v77
	v_and_b32_e32 v61, 0xffff0000, v77
	v_add_f32_e32 v50, 1.0, v50
	v_add_f32_e32 v51, 1.0, v51
	v_rcp_f32_e32 v50, v50
	v_rcp_f32_e32 v51, v51
	s_nop 0
	v_mul_f32_e32 v50, v52, v50
	v_mul_f32_e32 v51, v53, v51
	s_nop 0
	v_mul_f32_e32 v60, v50, v60
	v_mul_f32_e32 v61, v51, v61
	v_cvt_pk_bf16_f32 v50, v54, v55
	v_cvt_pk_bf16_f32 v51, v56, v57
	v_cvt_pk_bf16_f32 v52, v58, v59
	v_cvt_pk_bf16_f32 v53, v60, v61
	global_store_dwordx4 v[80:81], v[50:53], off offset:256
	v_exp_f32_e64 v54, -v30
	v_exp_f32_e64 v55, -v31
	v_exp_f32_e64 v50, -v46
	v_exp_f32_e64 v51, -v47
	s_waitcnt vmcnt(3)
	v_lshlrev_b32_e32 v52, 16, v70
	v_and_b32_e32 v53, 0xffff0000, v70
	v_add_f32_e32 v50, 1.0, v50
	v_add_f32_e32 v51, 1.0, v51
	v_rcp_f32_e32 v50, v50
	v_rcp_f32_e32 v51, v51
	v_add_f32_e32 v54, 1.0, v54
	v_add_f32_e32 v55, 1.0, v55
	v_rcp_f32_e32 v54, v54
	v_mul_f32_e32 v46, v46, v50
	v_mul_f32_e32 v47, v47, v51
	v_exp_f32_e64 v50, -v48
	v_exp_f32_e64 v51, -v49
	v_mul_f32_e32 v46, v46, v52
	v_mul_f32_e32 v47, v47, v53
	v_lshlrev_b32_e32 v52, 16, v71
	v_add_f32_e32 v50, 1.0, v50
	v_add_f32_e32 v51, 1.0, v51
	v_rcp_f32_e32 v50, v50
	v_rcp_f32_e32 v51, v51
	v_and_b32_e32 v53, 0xffff0000, v71
	v_rcp_f32_e32 v55, v55
	v_mul_f32_e32 v48, v48, v50
	v_mul_f32_e32 v49, v49, v51
	v_exp_f32_e64 v50, -v42
	v_exp_f32_e64 v51, -v43
	v_mul_f32_e32 v48, v48, v52
	v_mul_f32_e32 v49, v49, v53
	v_lshlrev_b32_e32 v52, 16, v72
	v_add_f32_e32 v50, 1.0, v50
	v_add_f32_e32 v51, 1.0, v51
	v_rcp_f32_e32 v50, v50
	v_rcp_f32_e32 v51, v51
	v_and_b32_e32 v53, 0xffff0000, v72
	v_mul_f32_e32 v30, v30, v54
	v_mul_f32_e32 v31, v31, v55
	v_mul_f32_e32 v42, v42, v50
	v_mul_f32_e32 v43, v43, v51
	s_nop 0
	v_mul_f32_e32 v50, v42, v52
	v_mul_f32_e32 v51, v43, v53
	v_exp_f32_e64 v42, -v44
	v_exp_f32_e64 v43, -v45
	v_lshlrev_b32_e32 v52, 16, v73
	v_and_b32_e32 v53, 0xffff0000, v73
	v_add_f32_e32 v42, 1.0, v42
	v_add_f32_e32 v43, 1.0, v43
	v_rcp_f32_e32 v42, v42
	v_rcp_f32_e32 v43, v43
	s_nop 0
	v_mul_f32_e32 v42, v44, v42
	v_mul_f32_e32 v43, v45, v43
	s_nop 0
	v_mul_f32_e32 v52, v42, v52
	v_mul_f32_e32 v53, v43, v53
	v_cvt_pk_bf16_f32 v42, v46, v47
	v_cvt_pk_bf16_f32 v43, v48, v49
	v_cvt_pk_bf16_f32 v44, v50, v51
	v_cvt_pk_bf16_f32 v45, v52, v53
	global_store_dwordx4 v[78:79], v[42:45], off
	s_nop 1
	v_exp_f32_e64 v42, -v38
	v_exp_f32_e64 v43, -v39
	s_waitcnt vmcnt(3)
	v_lshlrev_b32_e32 v44, 16, v66
	v_and_b32_e32 v45, 0xffff0000, v66
	v_add_f32_e32 v42, 1.0, v42
	v_add_f32_e32 v43, 1.0, v43
	v_rcp_f32_e32 v42, v42
	v_rcp_f32_e32 v43, v43
	s_nop 0
	v_mul_f32_e32 v38, v38, v42
	v_mul_f32_e32 v39, v39, v43
	v_exp_f32_e64 v42, -v40
	v_exp_f32_e64 v43, -v41
	v_mul_f32_e32 v38, v38, v44
	v_mul_f32_e32 v39, v39, v45
	v_lshlrev_b32_e32 v44, 16, v67
	v_add_f32_e32 v42, 1.0, v42
	v_add_f32_e32 v43, 1.0, v43
	v_rcp_f32_e32 v42, v42
	v_rcp_f32_e32 v43, v43
	v_and_b32_e32 v45, 0xffff0000, v67
	v_mul_f32_e32 v40, v40, v42
	v_mul_f32_e32 v41, v41, v43
	v_exp_f32_e64 v42, -v34
	v_exp_f32_e64 v43, -v35
	v_mul_f32_e32 v40, v40, v44
	v_mul_f32_e32 v41, v41, v45
	v_lshlrev_b32_e32 v44, 16, v68
	v_add_f32_e32 v42, 1.0, v42
	v_add_f32_e32 v43, 1.0, v43
	v_rcp_f32_e32 v42, v42
	v_rcp_f32_e32 v43, v43
	v_and_b32_e32 v45, 0xffff0000, v68
	v_mul_f32_e32 v34, v34, v42
	v_mul_f32_e32 v35, v35, v43
	s_nop 0
	v_mul_f32_e32 v42, v34, v44
	v_mul_f32_e32 v43, v35, v45
	v_exp_f32_e64 v34, -v36
	v_exp_f32_e64 v35, -v37
	v_lshlrev_b32_e32 v44, 16, v69
	v_and_b32_e32 v45, 0xffff0000, v69
	v_add_f32_e32 v34, 1.0, v34
	v_add_f32_e32 v35, 1.0, v35
	v_rcp_f32_e32 v34, v34
	v_rcp_f32_e32 v35, v35
	s_nop 0
	v_mul_f32_e32 v34, v36, v34
	v_mul_f32_e32 v35, v37, v35
	s_nop 0
	v_mul_f32_e32 v44, v34, v44
	v_mul_f32_e32 v45, v35, v45
	v_cvt_pk_bf16_f32 v34, v38, v39
	v_cvt_pk_bf16_f32 v35, v40, v41
	v_cvt_pk_bf16_f32 v36, v42, v43
	v_cvt_pk_bf16_f32 v37, v44, v45
	global_store_dwordx4 v[78:79], v[34:37], off offset:256
	s_nop 1
	v_add_u32_e32 v34, 0xa0, v165
	v_mad_i64_i32 v[34:35], s[4:5], v34, s16, v[154:155]
	v_lshl_add_u64 v[48:49], v[34:35], 0, v[156:157]
	global_load_dwordx4 v[50:53], v[48:49], off
	global_load_dwordx4 v[42:45], v[48:49], off offset:256
	v_add_u32_e32 v34, 0xb0, v165
	v_mad_i64_i32 v[34:35], s[4:5], v34, s16, v[154:155]
	v_lshl_add_u64 v[46:47], v[34:35], 0, v[156:157]
	global_load_dwordx4 v[38:41], v[46:47], off
	global_load_dwordx4 v[34:37], v[46:47], off offset:256
	s_mov_b64 s[4:5], -1
	s_waitcnt vmcnt(3)
; __device__ __forceinline__ unsigned pk2(float lo, float hi) { f32x2_t v = {lo, hi}; bf16x2_t b = __builtin_convertvector(v, bf16x2_t); return __builtin_bit_cast(unsigned, b); }
; __device__ __forceinline__ float bf_lo(unsigned w) { return __uint_as_float(w << 16); }
; __device__ __forceinline__ float bf_hi(unsigned w) { return __uint_as_float(w & 0xffff0000u); }
;     __device__ __forceinline__ void operator()(const f32x4 (&acc)[2][2][4][2], const pg8::Unit& u, int wr, int wc, int fr, int fq) const {
;     ...
;                     for (int i = 0; i < 4; ++i) { const size_t row = (size_t)(row0 + ai * 128 + (2 * mh + (i >> 1)) * 16); const int co = col0 + (i & 1) * 128;
;                         cw[i] = *(const u32x4*)(O + row * ldc + co); if (MODE >= 3) xw[i] = *(const u32x4*)(X + row * ldx + co); }
;                 }
; #pragma unroll
;                 for (int i = 0; i < 4; ++i) {
;                     const int m = 2 * mh + (i >> 1), bj = i & 1;
;                     bf16_t* p = O + (size_t)(row0 + ai * 128 + m * 16) * ldc + col0 + bj * 128;
;                     const f32x4 v0 = acc[ai][bj][m][0], v1 = acc[ai][bj][m][1];
;                     float v[8] = {v0[0], v0[1], v0[2], v0[3], v1[0], v1[1], v1[2], v1[3]};
;                     if (MODE != 0) {
;                         float c[8] = {bf_lo(cw[i].x), bf_hi(cw[i].x), bf_lo(cw[i].y), bf_hi(cw[i].y), bf_lo(cw[i].z), bf_hi(cw[i].z), bf_lo(cw[i].w), bf_hi(cw[i].w)};
;                         if (MODE == 1) {
; #pragma unroll
;                             for (int e = 0; e < 8; ++e) v[e] = v[e] * sigm2(v[e]) * c[e];
;                         } else if (MODE == 2) {
; #pragma unroll
;                             for (int e = 0; e < 8; ++e) v[e] = sigm2(v[e]) * c[e];
;                         } else {
;                             float x[8] = {bf_lo(xw[i].x), bf_hi(xw[i].x), bf_lo(xw[i].y), bf_hi(xw[i].y), bf_lo(xw[i].z), bf_hi(xw[i].z), bf_lo(xw[i].w), bf_hi(xw[i].w)};
; #pragma unroll
;                             for (int e = 0; e < 8; ++e) v[e] = (MODE == 4 ? 0.f : c[e]) + sigm2(v[e]) * x[e];
;                         }
;                     }
;                     u32x4 w; w.x = pk2(v[0], v[1]); w.y = pk2(v[2], v[3]); w.z = pk2(v[4], v[5]); w.w = pk2(v[6], v[7]);
;                     *(u32x4*)p = w;
	v_lshlrev_b32_e32 v56, 16, v50
	v_and_b32_e32 v57, 0xffff0000, v50
	v_exp_f32_e64 v50, -v32
	v_mul_f32_e32 v30, v30, v56
	v_mul_f32_e32 v31, v31, v57
	v_add_f32_e32 v50, 1.0, v50
	v_rcp_f32_e32 v54, v50
	v_exp_f32_e64 v50, -v33
	s_nop 0
	v_add_f32_e32 v50, 1.0, v50
	v_rcp_f32_e32 v55, v50
	v_lshlrev_b32_e32 v50, 16, v51
	v_and_b32_e32 v51, 0xffff0000, v51
	v_mul_f32_e32 v32, v32, v54
	v_mul_f32_e32 v33, v33, v55
	s_nop 0
	v_mul_f32_e32 v32, v32, v50
	v_mul_f32_e32 v33, v33, v51
	v_exp_f32_e64 v50, -v26
	v_exp_f32_e64 v51, -v27
	v_lshlrev_b32_e32 v54, 16, v52
	v_and_b32_e32 v55, 0xffff0000, v52
	v_add_f32_e32 v50, 1.0, v50
	v_add_f32_e32 v51, 1.0, v51
	v_rcp_f32_e32 v50, v50
	v_rcp_f32_e32 v51, v51
	v_lshlrev_b32_e32 v52, 16, v53
	v_and_b32_e32 v53, 0xffff0000, v53
	v_mul_f32_e32 v26, v26, v50
	v_mul_f32_e32 v27, v27, v51
	s_nop 0
	v_mul_f32_e32 v50, v26, v54
	v_mul_f32_e32 v51, v27, v55
	v_exp_f32_e64 v26, -v28
	v_exp_f32_e64 v27, -v29
	v_add_f32_e32 v26, 1.0, v26
	v_add_f32_e32 v27, 1.0, v27
	v_rcp_f32_e32 v26, v26
	v_rcp_f32_e32 v27, v27
	s_nop 0
	v_mul_f32_e32 v26, v28, v26
	v_mul_f32_e32 v27, v29, v27
	s_nop 0
	v_mul_f32_e32 v52, v26, v52
	v_mul_f32_e32 v53, v27, v53
	v_cvt_pk_bf16_f32 v26, v30, v31
	v_cvt_pk_bf16_f32 v27, v32, v33
	v_cvt_pk_bf16_f32 v28, v50, v51
	v_cvt_pk_bf16_f32 v29, v52, v53
	global_store_dwordx4 v[48:49], v[26:29], off
	s_nop 1
	v_exp_f32_e64 v26, -v22
	v_exp_f32_e64 v27, -v23
	s_waitcnt vmcnt(3)
	v_lshlrev_b32_e32 v28, 16, v42
	v_and_b32_e32 v29, 0xffff0000, v42
	v_add_f32_e32 v26, 1.0, v26
	v_add_f32_e32 v27, 1.0, v27
	v_rcp_f32_e32 v26, v26
	v_rcp_f32_e32 v27, v27
	s_nop 0
	v_mul_f32_e32 v22, v22, v26
	v_mul_f32_e32 v23, v23, v27
	v_exp_f32_e64 v26, -v24
	v_exp_f32_e64 v27, -v25
	v_mul_f32_e32 v22, v22, v28
	v_mul_f32_e32 v23, v23, v29
	v_lshlrev_b32_e32 v28, 16, v43
	v_add_f32_e32 v26, 1.0, v26
	v_add_f32_e32 v27, 1.0, v27
	v_rcp_f32_e32 v26, v26
	v_rcp_f32_e32 v27, v27
	v_and_b32_e32 v29, 0xffff0000, v43
	v_mul_f32_e32 v24, v24, v26
	v_mul_f32_e32 v25, v25, v27
	v_exp_f32_e64 v26, -v18
	v_exp_f32_e64 v27, -v19
	v_mul_f32_e32 v24, v24, v28
	v_mul_f32_e32 v25, v25, v29
	v_lshlrev_b32_e32 v28, 16, v44
	v_add_f32_e32 v26, 1.0, v26
	v_add_f32_e32 v27, 1.0, v27
	v_rcp_f32_e32 v26, v26
	v_rcp_f32_e32 v27, v27
	v_and_b32_e32 v29, 0xffff0000, v44
	v_mul_f32_e32 v18, v18, v26
	v_mul_f32_e32 v19, v19, v27
	s_nop 0
	v_mul_f32_e32 v26, v18, v28
	v_mul_f32_e32 v27, v19, v29
	v_exp_f32_e64 v18, -v20
	v_exp_f32_e64 v19, -v21
	v_lshlrev_b32_e32 v28, 16, v45
	v_and_b32_e32 v29, 0xffff0000, v45
	v_add_f32_e32 v18, 1.0, v18
	v_add_f32_e32 v19, 1.0, v19
	v_rcp_f32_e32 v18, v18
	v_rcp_f32_e32 v19, v19
	s_nop 0
	v_mul_f32_e32 v18, v20, v18
	v_mul_f32_e32 v19, v21, v19
	s_nop 0
	v_mul_f32_e32 v28, v18, v28
	v_mul_f32_e32 v29, v19, v29
	v_cvt_pk_bf16_f32 v18, v22, v23
	v_cvt_pk_bf16_f32 v19, v24, v25
	v_cvt_pk_bf16_f32 v20, v26, v27
	v_cvt_pk_bf16_f32 v21, v28, v29
	global_store_dwordx4 v[48:49], v[18:21], off offset:256
	s_nop 1
	v_exp_f32_e64 v18, -v14
	v_exp_f32_e64 v19, -v15
	s_waitcnt vmcnt(3)
	v_lshlrev_b32_e32 v20, 16, v38
	v_and_b32_e32 v21, 0xffff0000, v38
	v_add_f32_e32 v18, 1.0, v18
	v_add_f32_e32 v19, 1.0, v19
	v_rcp_f32_e32 v18, v18
	v_rcp_f32_e32 v19, v19
	s_nop 0
	v_mul_f32_e32 v14, v14, v18
	v_mul_f32_e32 v15, v15, v19
	v_exp_f32_e64 v18, -v16
	v_exp_f32_e64 v19, -v17
	v_mul_f32_e32 v14, v14, v20
	v_mul_f32_e32 v15, v15, v21
	v_lshlrev_b32_e32 v20, 16, v39
	v_add_f32_e32 v18, 1.0, v18
	v_add_f32_e32 v19, 1.0, v19
	v_rcp_f32_e32 v18, v18
	v_rcp_f32_e32 v19, v19
	v_and_b32_e32 v21, 0xffff0000, v39
	v_mul_f32_e32 v16, v16, v18
	v_mul_f32_e32 v17, v17, v19
	v_exp_f32_e64 v18, -v10
	v_exp_f32_e64 v19, -v11
	v_mul_f32_e32 v16, v16, v20
	v_mul_f32_e32 v17, v17, v21
	v_lshlrev_b32_e32 v20, 16, v40
	v_add_f32_e32 v18, 1.0, v18
	v_add_f32_e32 v19, 1.0, v19
	v_rcp_f32_e32 v18, v18
	v_rcp_f32_e32 v19, v19
	v_and_b32_e32 v21, 0xffff0000, v40
	v_mul_f32_e32 v10, v10, v18
	v_mul_f32_e32 v11, v11, v19
	s_nop 0
	v_mul_f32_e32 v18, v10, v20
	v_mul_f32_e32 v19, v11, v21
	v_exp_f32_e64 v10, -v12
	v_exp_f32_e64 v11, -v13
	v_lshlrev_b32_e32 v20, 16, v41
	v_and_b32_e32 v21, 0xffff0000, v41
	v_add_f32_e32 v10, 1.0, v10
	v_add_f32_e32 v11, 1.0, v11
	v_rcp_f32_e32 v10, v10
	v_rcp_f32_e32 v11, v11
	s_nop 0
	v_mul_f32_e32 v10, v12, v10
	v_mul_f32_e32 v11, v13, v11
	s_nop 0
	v_mul_f32_e32 v20, v10, v20
	v_mul_f32_e32 v21, v11, v21
	v_cvt_pk_bf16_f32 v10, v14, v15
	v_cvt_pk_bf16_f32 v11, v16, v17
	v_cvt_pk_bf16_f32 v12, v18, v19
	v_cvt_pk_bf16_f32 v13, v20, v21
	global_store_dwordx4 v[46:47], v[10:13], off
	s_nop 1
	v_exp_f32_e64 v10, -v6
	v_exp_f32_e64 v11, -v7
	s_waitcnt vmcnt(3)
	v_lshlrev_b32_e32 v12, 16, v34
	v_and_b32_e32 v13, 0xffff0000, v34
	v_add_f32_e32 v10, 1.0, v10
	v_add_f32_e32 v11, 1.0, v11
	v_rcp_f32_e32 v10, v10
	v_rcp_f32_e32 v11, v11
	s_nop 0
	v_mul_f32_e32 v6, v6, v10
	v_mul_f32_e32 v7, v7, v11
	v_exp_f32_e64 v10, -v8
	v_exp_f32_e64 v11, -v9
	v_mul_f32_e32 v6, v6, v12
	v_mul_f32_e32 v7, v7, v13
	v_lshlrev_b32_e32 v12, 16, v35
	v_add_f32_e32 v10, 1.0, v10
	v_add_f32_e32 v11, 1.0, v11
	v_rcp_f32_e32 v10, v10
	v_rcp_f32_e32 v11, v11
	v_and_b32_e32 v13, 0xffff0000, v35
	v_mul_f32_e32 v8, v8, v10
	v_mul_f32_e32 v9, v9, v11
	v_exp_f32_e64 v10, -v2
	v_exp_f32_e64 v11, -v3
	v_mul_f32_e32 v8, v8, v12
	v_mul_f32_e32 v9, v9, v13
	v_lshlrev_b32_e32 v12, 16, v36
	v_add_f32_e32 v10, 1.0, v10
	v_add_f32_e32 v11, 1.0, v11
	v_rcp_f32_e32 v10, v10
	v_rcp_f32_e32 v11, v11
	v_and_b32_e32 v13, 0xffff0000, v36
	v_mul_f32_e32 v2, v2, v10
	v_mul_f32_e32 v3, v3, v11
	s_nop 0
	v_mul_f32_e32 v10, v2, v12
	v_mul_f32_e32 v11, v3, v13
	v_exp_f32_e64 v2, -v4
	v_exp_f32_e64 v3, -v5
	v_lshlrev_b32_e32 v12, 16, v37
	v_and_b32_e32 v13, 0xffff0000, v37
	v_add_f32_e32 v2, 1.0, v2
	v_add_f32_e32 v3, 1.0, v3
	v_rcp_f32_e32 v2, v2
	v_rcp_f32_e32 v3, v3
	s_nop 0
	v_mul_f32_e32 v2, v4, v2
	v_mul_f32_e32 v3, v5, v3
	s_nop 0
	v_mul_f32_e32 v12, v2, v12
	v_mul_f32_e32 v13, v3, v13
	v_cvt_pk_bf16_f32 v2, v6, v7
	v_cvt_pk_bf16_f32 v3, v8, v9
	v_cvt_pk_bf16_f32 v4, v10, v11
	v_cvt_pk_bf16_f32 v5, v12, v13
	global_store_dwordx4 v[46:47], v[2:5], off offset:256
	s_cbranch_vccnz .LBB0_1292
	s_andn2_b64 vcc, exec, s[36:37]
	s_cbranch_vccnz .LBB0_1291
	s_barrier
	s_branch .LBB0_1291

; __device__ __forceinline__ unsigned pk2(float lo, float hi) { f32x2_t v = {lo, hi}; bf16x2_t b = __builtin_convertvector(v, bf16x2_t); return __builtin_bit_cast(unsigned, b); }
; __device__ __forceinline__ float bf_lo(unsigned w) { return __uint_as_float(w << 16); }
; __device__ __forceinline__ float bf_hi(unsigned w) { return __uint_as_float(w & 0xffff0000u); }
;     __device__ __forceinline__ void operator()(const f32x4 (&acc)[2][2][4][2], const pg8::Unit& u, int wr, int wc, int fr, int fq) const {
;     ...
;                     for (int i = 0; i < 4; ++i) { const size_t row = (size_t)(row0 + ai * 128 + (2 * mh + (i >> 1)) * 16); const int co = col0 + (i & 1) * 128;
;                         cw[i] = *(const u32x4*)(O + row * ldc + co); if (MODE >= 3) xw[i] = *(const u32x4*)(X + row * ldx + co); }
;                 }
; #pragma unroll
;                 for (int i = 0; i < 4; ++i) {
;                     const int m = 2 * mh + (i >> 1), bj = i & 1;
;                     bf16_t* p = O + (size_t)(row0 + ai * 128 + m * 16) * ldc + col0 + bj * 128;
;                     const f32x4 v0 = acc[ai][bj][m][0], v1 = acc[ai][bj][m][1];
;                     float v[8] = {v0[0], v0[1], v0[2], v0[3], v1[0], v1[1], v1[2], v1[3]};
;                     if (MODE != 0) {
;                         float c[8] = {bf_lo(cw[i].x), bf_hi(cw[i].x), bf_lo(cw[i].y), bf_hi(cw[i].y), bf_lo(cw[i].z), bf_hi(cw[i].z), bf_lo(cw[i].w), bf_hi(cw[i].w)};
;                         if (MODE == 1) {
; #pragma unroll
;                             for (int e = 0; e < 8; ++e) v[e] = v[e] * sigm2(v[e]) * c[e];
;                         } else if (MODE == 2) {
; #pragma unroll
;                             for (int e = 0; e < 8; ++e) v[e] = sigm2(v[e]) * c[e];
;                         } else {
;                             float x[8] = {bf_lo(xw[i].x), bf_hi(xw[i].x), bf_lo(xw[i].y), bf_hi(xw[i].y), bf_lo(xw[i].z), bf_hi(xw[i].z), bf_lo(xw[i].w), bf_hi(xw[i].w)};
; #pragma unroll
;                             for (int e = 0; e < 8; ++e) v[e] = (MODE == 4 ? 0.f : c[e]) + sigm2(v[e]) * x[e];
;                         }
;                     }
;                     u32x4 w; w.x = pk2(v[0], v[1]); w.y = pk2(v[2], v[3]); w.z = pk2(v[4], v[5]); w.w = pk2(v[6], v[7]);
;                     *(u32x4*)p = w;
.LBB0_1402:
	v_lshl_or_b32 v122, s13, 8, v163
	v_lshl_add_u32 v165, s22, 8, v0
	v_ashrrev_i32_e32 v123, 31, v122
	v_mov_b64_e32 v[154:155], s[30:31]
	v_mad_i64_i32 v[124:125], s[4:5], v165, s16, v[154:155]
	v_lshlrev_b64 v[156:157], 1, v[122:123]
	v_lshl_add_u64 v[160:161], v[124:125], 0, v[156:157]
	global_load_dwordx4 v[166:169], v[160:161], off
	global_load_dwordx4 v[138:141], v[160:161], off offset:256
	v_or_b32_e32 v122, 16, v165
	v_mad_i64_i32 v[122:123], s[4:5], v122, s16, v[154:155]
	v_lshl_add_u64 v[158:159], v[122:123], 0, v[156:157]
	global_load_dwordx4 v[130:133], v[158:159], off
	global_load_dwordx4 v[122:125], v[158:159], off offset:256
	v_exp_f32_e64 v136, -v136
	v_exp_f32_e64 v137, -v137
	v_exp_f32_e64 v126, -v126
	v_exp_f32_e64 v127, -v127
	v_add_f32_e32 v136, 1.0, v136
	v_add_f32_e32 v137, 1.0, v137
	v_rcp_f32_e32 v136, v136
	v_rcp_f32_e32 v137, v137
	v_add_f32_e32 v126, 1.0, v126
	v_add_f32_e32 v127, 1.0, v127
	v_rcp_f32_e32 v126, v126
	v_rcp_f32_e32 v127, v127
	v_exp_f32_e64 v134, -v134
	v_exp_f32_e64 v135, -v135
	v_exp_f32_e64 v118, -v118
	v_exp_f32_e64 v119, -v119
	v_add_f32_e32 v134, 1.0, v134
	v_add_f32_e32 v135, 1.0, v135
	v_exp_f32_e64 v120, -v120
	v_exp_f32_e64 v121, -v121
	v_rcp_f32_e32 v134, v134
	v_rcp_f32_e32 v135, v135
	v_exp_f32_e64 v114, -v114
	v_exp_f32_e64 v115, -v115
	v_exp_f32_e64 v116, -v116
	v_exp_f32_e64 v117, -v117
	v_add_f32_e32 v118, 1.0, v118
	v_add_f32_e32 v119, 1.0, v119
	v_exp_f32_e64 v110, -v110
	v_exp_f32_e64 v111, -v111
	v_rcp_f32_e32 v118, v118
	v_rcp_f32_e32 v119, v119
	v_add_f32_e32 v120, 1.0, v120
	v_add_f32_e32 v121, 1.0, v121
	v_exp_f32_e64 v112, -v112
	v_exp_f32_e64 v113, -v113
	v_rcp_f32_e32 v120, v120
	v_rcp_f32_e32 v121, v121
	v_add_f32_e32 v114, 1.0, v114
	v_add_f32_e32 v115, 1.0, v115
	v_exp_f32_e64 v106, -v106
	v_exp_f32_e64 v107, -v107
	v_rcp_f32_e32 v114, v114
	v_rcp_f32_e32 v115, v115
	v_add_f32_e32 v116, 1.0, v116
	v_add_f32_e32 v117, 1.0, v117
	v_rcp_f32_e32 v116, v116
	v_rcp_f32_e32 v117, v117
	v_add_f32_e32 v110, 1.0, v110
	v_add_f32_e32 v111, 1.0, v111
	v_rcp_f32_e32 v110, v110
	v_rcp_f32_e32 v111, v111
	v_add_f32_e32 v112, 1.0, v112
	v_add_f32_e32 v113, 1.0, v113
	v_rcp_f32_e32 v112, v112
	v_rcp_f32_e32 v113, v113
	v_add_f32_e32 v106, 1.0, v106
	v_add_f32_e32 v107, 1.0, v107
	v_rcp_f32_e32 v106, v106
	v_rcp_f32_e32 v107, v107
	v_exp_f32_e64 v102, -v102
	v_exp_f32_e64 v103, -v103
	v_exp_f32_e64 v104, -v104
	v_exp_f32_e64 v105, -v105
	v_exp_f32_e64 v98, -v98
	v_exp_f32_e64 v99, -v99
	v_add_f32_e32 v102, 1.0, v102
	v_add_f32_e32 v103, 1.0, v103
	v_rcp_f32_e32 v102, v102
	v_rcp_f32_e32 v103, v103
	v_add_f32_e32 v104, 1.0, v104
	v_add_f32_e32 v105, 1.0, v105
	v_rcp_f32_e32 v104, v104
	s_waitcnt vmcnt(0)
	v_lshlrev_b32_e32 v170, 16, v166
	v_and_b32_e32 v171, 0xffff0000, v166
	v_lshlrev_b32_e32 v166, 16, v167
	v_and_b32_e32 v167, 0xffff0000, v167
	v_mul_f32_e32 v136, v136, v166
	v_mul_f32_e32 v137, v137, v167
	v_lshlrev_b32_e32 v166, 16, v168
	v_and_b32_e32 v167, 0xffff0000, v168
	v_mul_f32_e32 v166, v126, v166
	v_mul_f32_e32 v167, v127, v167
	v_exp_f32_e64 v126, -v128
	v_exp_f32_e64 v127, -v129
	v_lshlrev_b32_e32 v128, 16, v169
	v_and_b32_e32 v129, 0xffff0000, v169
	v_add_f32_e32 v126, 1.0, v126
	v_add_f32_e32 v127, 1.0, v127
	v_rcp_f32_e32 v126, v126
	v_rcp_f32_e32 v127, v127
	v_mul_f32_e32 v134, v134, v170
	v_mul_f32_e32 v135, v135, v171
	v_rcp_f32_e32 v105, v105
	v_add_f32_e32 v98, 1.0, v98
	v_mul_f32_e32 v168, v126, v128
	v_mul_f32_e32 v169, v127, v129
	v_cvt_pk_bf16_f32 v126, v134, v135
	v_cvt_pk_bf16_f32 v127, v136, v137
	v_cvt_pk_bf16_f32 v128, v166, v167
	v_cvt_pk_bf16_f32 v129, v168, v169
	global_store_dwordx4 v[160:161], v[126:129], off
	v_add_f32_e32 v99, 1.0, v99
	v_rcp_f32_e32 v98, v98
	v_lshlrev_b32_e32 v126, 16, v138
	v_and_b32_e32 v127, 0xffff0000, v138
	v_mul_f32_e32 v118, v118, v126
	v_mul_f32_e32 v119, v119, v127
	v_lshlrev_b32_e32 v126, 16, v139
	v_and_b32_e32 v127, 0xffff0000, v139
	v_mul_f32_e32 v120, v120, v126
	v_mul_f32_e32 v121, v121, v127
	v_lshlrev_b32_e32 v126, 16, v140
	v_and_b32_e32 v127, 0xffff0000, v140
	v_mul_f32_e32 v114, v114, v126
	v_mul_f32_e32 v115, v115, v127
	v_lshlrev_b32_e32 v126, 16, v141
	v_and_b32_e32 v127, 0xffff0000, v141
	v_mul_f32_e32 v126, v116, v126
	v_mul_f32_e32 v127, v117, v127
	v_cvt_pk_bf16_f32 v116, v118, v119
	v_cvt_pk_bf16_f32 v118, v114, v115
	v_lshlrev_b32_e32 v114, 16, v130
	v_and_b32_e32 v115, 0xffff0000, v130
	v_mul_f32_e32 v110, v110, v114
	v_mul_f32_e32 v111, v111, v115
	v_lshlrev_b32_e32 v114, 16, v131
	v_and_b32_e32 v115, 0xffff0000, v131
	v_mul_f32_e32 v112, v112, v114
	v_mul_f32_e32 v113, v113, v115
	v_lshlrev_b32_e32 v114, 16, v132
	v_and_b32_e32 v115, 0xffff0000, v132
	v_mul_f32_e32 v114, v106, v114
	v_mul_f32_e32 v115, v107, v115
	v_exp_f32_e64 v106, -v108
	v_exp_f32_e64 v107, -v109
	v_cvt_pk_bf16_f32 v117, v120, v121
	v_cvt_pk_bf16_f32 v119, v126, v127
	v_add_f32_e32 v106, 1.0, v106
	v_add_f32_e32 v107, 1.0, v107
	v_rcp_f32_e32 v106, v106
	v_rcp_f32_e32 v107, v107
	v_lshlrev_b32_e32 v108, 16, v133
	v_and_b32_e32 v109, 0xffff0000, v133
	global_store_dwordx4 v[160:161], v[116:119], off offset:256
	v_rcp_f32_e32 v99, v99
	v_exp_f32_e64 v96, -v96
	v_mul_f32_e32 v116, v106, v108
	v_mul_f32_e32 v117, v107, v109
	v_cvt_pk_bf16_f32 v106, v110, v111
	v_cvt_pk_bf16_f32 v107, v112, v113
	v_cvt_pk_bf16_f32 v108, v114, v115
	v_cvt_pk_bf16_f32 v109, v116, v117
	global_store_dwordx4 v[158:159], v[106:109], off
	v_exp_f32_e64 v97, -v97
	v_exp_f32_e64 v90, -v90
	v_lshlrev_b32_e32 v106, 16, v122
	v_and_b32_e32 v107, 0xffff0000, v122
	v_mul_f32_e32 v102, v102, v106
	v_mul_f32_e32 v103, v103, v107
; __device__ __forceinline__ unsigned pk2(float lo, float hi) { f32x2_t v = {lo, hi}; bf16x2_t b = __builtin_convertvector(v, bf16x2_t); return __builtin_bit_cast(unsigned, b); }
; __device__ __forceinline__ float bf_lo(unsigned w) { return __uint_as_float(w << 16); }
; __device__ __forceinline__ float bf_hi(unsigned w) { return __uint_as_float(w & 0xffff0000u); }
;     __device__ __forceinline__ void operator()(const f32x4 (&acc)[2][2][4][2], const pg8::Unit& u, int wr, int wc, int fr, int fq) const {
;     ...
;                     for (int i = 0; i < 4; ++i) { const size_t row = (size_t)(row0 + ai * 128 + (2 * mh + (i >> 1)) * 16); const int co = col0 + (i & 1) * 128;
;                         cw[i] = *(const u32x4*)(O + row * ldc + co); if (MODE >= 3) xw[i] = *(const u32x4*)(X + row * ldx + co); }
;                 }
; #pragma unroll
;                 for (int i = 0; i < 4; ++i) {
;                     const int m = 2 * mh + (i >> 1), bj = i & 1;
;                     bf16_t* p = O + (size_t)(row0 + ai * 128 + m * 16) * ldc + col0 + bj * 128;
;                     const f32x4 v0 = acc[ai][bj][m][0], v1 = acc[ai][bj][m][1];
;                     float v[8] = {v0[0], v0[1], v0[2], v0[3], v1[0], v1[1], v1[2], v1[3]};
;                     if (MODE != 0) {
;                         float c[8] = {bf_lo(cw[i].x), bf_hi(cw[i].x), bf_lo(cw[i].y), bf_hi(cw[i].y), bf_lo(cw[i].z), bf_hi(cw[i].z), bf_lo(cw[i].w), bf_hi(cw[i].w)};
;                         if (MODE == 1) {
; #pragma unroll
;                             for (int e = 0; e < 8; ++e) v[e] = v[e] * sigm2(v[e]) * c[e];
;                         } else if (MODE == 2) {
; #pragma unroll
;                             for (int e = 0; e < 8; ++e) v[e] = sigm2(v[e]) * c[e];
;                         } else {
;                             float x[8] = {bf_lo(xw[i].x), bf_hi(xw[i].x), bf_lo(xw[i].y), bf_hi(xw[i].y), bf_lo(xw[i].z), bf_hi(xw[i].z), bf_lo(xw[i].w), bf_hi(xw[i].w)};
; #pragma unroll
;                             for (int e = 0; e < 8; ++e) v[e] = (MODE == 4 ? 0.f : c[e]) + sigm2(v[e]) * x[e];
;                         }
;                     }
;                     u32x4 w; w.x = pk2(v[0], v[1]); w.y = pk2(v[2], v[3]); w.z = pk2(v[4], v[5]); w.w = pk2(v[6], v[7]);
;                     *(u32x4*)p = w;
	v_lshlrev_b32_e32 v106, 16, v123
	v_and_b32_e32 v107, 0xffff0000, v123
	v_mul_f32_e32 v104, v104, v106
	v_mul_f32_e32 v105, v105, v107
	v_lshlrev_b32_e32 v106, 16, v124
	v_and_b32_e32 v107, 0xffff0000, v124
	v_mul_f32_e32 v106, v98, v106
	v_mul_f32_e32 v107, v99, v107
	v_exp_f32_e64 v98, -v100
	v_exp_f32_e64 v99, -v101
	v_lshlrev_b32_e32 v100, 16, v125
	v_and_b32_e32 v101, 0xffff0000, v125
	v_add_f32_e32 v98, 1.0, v98
	v_add_f32_e32 v99, 1.0, v99
	v_rcp_f32_e32 v98, v98
	v_rcp_f32_e32 v99, v99
	v_exp_f32_e64 v91, -v91
	v_add_f32_e32 v96, 1.0, v96
	v_add_f32_e32 v97, 1.0, v97
	v_mul_f32_e32 v108, v98, v100
	v_mul_f32_e32 v109, v99, v101
	v_cvt_pk_bf16_f32 v98, v102, v103
	v_cvt_pk_bf16_f32 v99, v104, v105
	v_cvt_pk_bf16_f32 v100, v106, v107
	v_cvt_pk_bf16_f32 v101, v108, v109
	global_store_dwordx4 v[158:159], v[98:101], off offset:256
	v_rcp_f32_e32 v96, v96
	v_rcp_f32_e32 v97, v97
	v_or_b32_e32 v98, 32, v165
	v_mad_i64_i32 v[98:99], s[4:5], v98, s16, v[154:155]
	v_lshl_add_u64 v[112:113], v[98:99], 0, v[156:157]
	global_load_dwordx4 v[114:117], v[112:113], off
	global_load_dwordx4 v[106:109], v[112:113], off offset:256
	v_or_b32_e32 v98, 48, v165
	v_mad_i64_i32 v[98:99], s[4:5], v98, s16, v[154:155]
	v_lshl_add_u64 v[110:111], v[98:99], 0, v[156:157]
	global_load_dwordx4 v[102:105], v[110:111], off
	global_load_dwordx4 v[98:101], v[110:111], off offset:256
	v_add_f32_e32 v90, 1.0, v90
	v_add_f32_e32 v91, 1.0, v91
	v_rcp_f32_e32 v90, v90
	v_rcp_f32_e32 v91, v91
	v_exp_f32_e64 v94, -v94
	v_exp_f32_e64 v95, -v95
	v_exp_f32_e64 v86, -v86
	v_exp_f32_e64 v87, -v87
	v_add_f32_e32 v94, 1.0, v94
	v_add_f32_e32 v95, 1.0, v95
	v_exp_f32_e64 v88, -v88
	v_exp_f32_e64 v89, -v89
	v_rcp_f32_e32 v94, v94
	v_rcp_f32_e32 v95, v95
	v_exp_f32_e64 v82, -v82
	v_exp_f32_e64 v83, -v83
	v_add_f32_e32 v86, 1.0, v86
	v_add_f32_e32 v87, 1.0, v87
	v_rcp_f32_e32 v86, v86
	v_rcp_f32_e32 v87, v87
	v_add_f32_e32 v88, 1.0, v88
	v_add_f32_e32 v89, 1.0, v89
	v_rcp_f32_e32 v88, v88
	v_rcp_f32_e32 v89, v89
	v_add_f32_e32 v82, 1.0, v82
	v_add_f32_e32 v83, 1.0, v83
	v_rcp_f32_e32 v82, v82
	v_rcp_f32_e32 v83, v83
	v_exp_f32_e64 v78, -v78
	v_exp_f32_e64 v79, -v79
	v_exp_f32_e64 v80, -v80
	v_exp_f32_e64 v81, -v81
	v_exp_f32_e64 v74, -v74
	v_exp_f32_e64 v75, -v75
	v_add_f32_e32 v78, 1.0, v78
	v_add_f32_e32 v79, 1.0, v79
	v_rcp_f32_e32 v78, v78
	v_rcp_f32_e32 v79, v79
	v_add_f32_e32 v80, 1.0, v80
	v_add_f32_e32 v81, 1.0, v81
	v_rcp_f32_e32 v80, v80
	v_rcp_f32_e32 v81, v81
	v_add_f32_e32 v74, 1.0, v74
	v_add_f32_e32 v75, 1.0, v75
	v_rcp_f32_e32 v74, v74
	v_rcp_f32_e32 v75, v75
	v_exp_f32_e64 v70, -v70
	v_exp_f32_e64 v71, -v71
	v_exp_f32_e64 v72, -v72
	v_exp_f32_e64 v73, -v73
	v_exp_f32_e64 v66, -v66
	v_exp_f32_e64 v67, -v67
	v_add_f32_e32 v70, 1.0, v70
	v_add_f32_e32 v71, 1.0, v71
	v_rcp_f32_e32 v70, v70
	v_rcp_f32_e32 v71, v71
	v_add_f32_e32 v72, 1.0, v72
	v_add_f32_e32 v73, 1.0, v73
	v_rcp_f32_e32 v72, v72
	v_rcp_f32_e32 v73, v73
	v_add_f32_e32 v66, 1.0, v66
	v_add_f32_e32 v67, 1.0, v67
	v_rcp_f32_e32 v66, v66
	v_rcp_f32_e32 v67, v67
	v_exp_f32_e64 v64, -v64
	v_exp_f32_e64 v65, -v65
	v_exp_f32_e64 v58, -v58
	v_exp_f32_e64 v59, -v59
	v_add_f32_e32 v64, 1.0, v64
	v_add_f32_e32 v65, 1.0, v65
	v_rcp_f32_e32 v64, v64
	v_rcp_f32_e32 v65, v65
	v_add_f32_e32 v58, 1.0, v58
	s_waitcnt vmcnt(3)
	v_lshlrev_b32_e32 v118, 16, v114
	v_and_b32_e32 v119, 0xffff0000, v114
	v_lshlrev_b32_e32 v114, 16, v115
	v_and_b32_e32 v115, 0xffff0000, v115
	v_mul_f32_e32 v96, v96, v114
	v_mul_f32_e32 v97, v97, v115
	v_lshlrev_b32_e32 v114, 16, v116
	v_and_b32_e32 v115, 0xffff0000, v116
	v_mul_f32_e32 v114, v90, v114
	v_mul_f32_e32 v115, v91, v115
	v_exp_f32_e64 v90, -v92
	v_exp_f32_e64 v91, -v93
	v_lshlrev_b32_e32 v92, 16, v117
	v_and_b32_e32 v93, 0xffff0000, v117
	v_add_f32_e32 v90, 1.0, v90
	v_add_f32_e32 v91, 1.0, v91
	v_rcp_f32_e32 v90, v90
	v_rcp_f32_e32 v91, v91
	v_mul_f32_e32 v94, v94, v118
	v_mul_f32_e32 v95, v95, v119
	v_add_f32_e32 v59, 1.0, v59
	v_rcp_f32_e32 v58, v58
	v_mul_f32_e32 v116, v90, v92
	v_mul_f32_e32 v117, v91, v93
	v_cvt_pk_bf16_f32 v90, v94, v95
	v_cvt_pk_bf16_f32 v91, v96, v97
	v_cvt_pk_bf16_f32 v92, v114, v115
	v_cvt_pk_bf16_f32 v93, v116, v117
	global_store_dwordx4 v[112:113], v[90:93], off
	v_rcp_f32_e32 v59, v59
	v_exp_f32_e64 v62, -v62
	s_waitcnt vmcnt(3)
	v_lshlrev_b32_e32 v90, 16, v106
	v_and_b32_e32 v91, 0xffff0000, v106
	v_mul_f32_e32 v86, v86, v90
	v_mul_f32_e32 v87, v87, v91
	v_lshlrev_b32_e32 v90, 16, v107
	v_and_b32_e32 v91, 0xffff0000, v107
	v_mul_f32_e32 v88, v88, v90
	v_mul_f32_e32 v89, v89, v91
	v_lshlrev_b32_e32 v90, 16, v108
	v_and_b32_e32 v91, 0xffff0000, v108
	v_mul_f32_e32 v90, v82, v90
	v_mul_f32_e32 v91, v83, v91
	v_exp_f32_e64 v82, -v84
	v_exp_f32_e64 v83, -v85
	v_lshlrev_b32_e32 v84, 16, v109
	v_and_b32_e32 v85, 0xffff0000, v109
	v_add_f32_e32 v82, 1.0, v82
	v_add_f32_e32 v83, 1.0, v83
	v_rcp_f32_e32 v82, v82
	v_rcp_f32_e32 v83, v83
	v_exp_f32_e64 v63, -v63
	v_exp_f32_e64 v54, -v54
	v_exp_f32_e64 v55, -v55
	v_mul_f32_e32 v92, v82, v84
	v_mul_f32_e32 v93, v83, v85
	v_cvt_pk_bf16_f32 v82, v86, v87
	v_cvt_pk_bf16_f32 v83, v88, v89
	v_cvt_pk_bf16_f32 v84, v90, v91
	v_cvt_pk_bf16_f32 v85, v92, v93
	global_store_dwordx4 v[112:113], v[82:85], off offset:256
	v_add_f32_e32 v62, 1.0, v62
	v_add_f32_e32 v63, 1.0, v63
	s_waitcnt vmcnt(3)
; __device__ __forceinline__ unsigned pk2(float lo, float hi) { f32x2_t v = {lo, hi}; bf16x2_t b = __builtin_convertvector(v, bf16x2_t); return __builtin_bit_cast(unsigned, b); }
; __device__ __forceinline__ float bf_lo(unsigned w) { return __uint_as_float(w << 16); }
; __device__ __forceinline__ float bf_hi(unsigned w) { return __uint_as_float(w & 0xffff0000u); }
;     __device__ __forceinline__ void operator()(const f32x4 (&acc)[2][2][4][2], const pg8::Unit& u, int wr, int wc, int fr, int fq) const {
;     ...
;                     for (int i = 0; i < 4; ++i) { const size_t row = (size_t)(row0 + ai * 128 + (2 * mh + (i >> 1)) * 16); const int co = col0 + (i & 1) * 128;
;                         cw[i] = *(const u32x4*)(O + row * ldc + co); if (MODE >= 3) xw[i] = *(const u32x4*)(X + row * ldx + co); }
;                 }
; #pragma unroll
;                 for (int i = 0; i < 4; ++i) {
;                     const int m = 2 * mh + (i >> 1), bj = i & 1;
;                     bf16_t* p = O + (size_t)(row0 + ai * 128 + m * 16) * ldc + col0 + bj * 128;
;                     const f32x4 v0 = acc[ai][bj][m][0], v1 = acc[ai][bj][m][1];
;                     float v[8] = {v0[0], v0[1], v0[2], v0[3], v1[0], v1[1], v1[2], v1[3]};
;                     if (MODE != 0) {
;                         float c[8] = {bf_lo(cw[i].x), bf_hi(cw[i].x), bf_lo(cw[i].y), bf_hi(cw[i].y), bf_lo(cw[i].z), bf_hi(cw[i].z), bf_lo(cw[i].w), bf_hi(cw[i].w)};
;                         if (MODE == 1) {
; #pragma unroll
;                             for (int e = 0; e < 8; ++e) v[e] = v[e] * sigm2(v[e]) * c[e];
;                         } else if (MODE == 2) {
; #pragma unroll
;                             for (int e = 0; e < 8; ++e) v[e] = sigm2(v[e]) * c[e];
;                         } else {
;                             float x[8] = {bf_lo(xw[i].x), bf_hi(xw[i].x), bf_lo(xw[i].y), bf_hi(xw[i].y), bf_lo(xw[i].z), bf_hi(xw[i].z), bf_lo(xw[i].w), bf_hi(xw[i].w)};
; #pragma unroll
;                             for (int e = 0; e < 8; ++e) v[e] = (MODE == 4 ? 0.f : c[e]) + sigm2(v[e]) * x[e];
;                         }
;                     }
;                     u32x4 w; w.x = pk2(v[0], v[1]); w.y = pk2(v[2], v[3]); w.z = pk2(v[4], v[5]); w.w = pk2(v[6], v[7]);
;                     *(u32x4*)p = w;
	v_lshlrev_b32_e32 v82, 16, v102
	v_and_b32_e32 v83, 0xffff0000, v102
	v_mul_f32_e32 v78, v78, v82
	v_mul_f32_e32 v79, v79, v83
	v_lshlrev_b32_e32 v82, 16, v103
	v_and_b32_e32 v83, 0xffff0000, v103
	v_mul_f32_e32 v80, v80, v82
	v_mul_f32_e32 v81, v81, v83
	v_lshlrev_b32_e32 v82, 16, v104
	v_and_b32_e32 v83, 0xffff0000, v104
	v_mul_f32_e32 v82, v74, v82
	v_mul_f32_e32 v83, v75, v83
	v_exp_f32_e64 v74, -v76
	v_exp_f32_e64 v75, -v77
	v_lshlrev_b32_e32 v76, 16, v105
	v_and_b32_e32 v77, 0xffff0000, v105
	v_add_f32_e32 v74, 1.0, v74
	v_add_f32_e32 v75, 1.0, v75
	v_rcp_f32_e32 v74, v74
	v_rcp_f32_e32 v75, v75
	v_exp_f32_e64 v56, -v56
	v_exp_f32_e64 v57, -v57
	v_rcp_f32_e32 v62, v62
	v_mul_f32_e32 v84, v74, v76
	v_mul_f32_e32 v85, v75, v77
	v_cvt_pk_bf16_f32 v74, v78, v79
	v_cvt_pk_bf16_f32 v75, v80, v81
	v_cvt_pk_bf16_f32 v76, v82, v83
	v_cvt_pk_bf16_f32 v77, v84, v85
	global_store_dwordx4 v[110:111], v[74:77], off
	v_rcp_f32_e32 v63, v63
	v_exp_f32_e64 v50, -v50
	s_waitcnt vmcnt(3)
	v_lshlrev_b32_e32 v74, 16, v98
	v_and_b32_e32 v75, 0xffff0000, v98
	v_mul_f32_e32 v70, v70, v74
	v_mul_f32_e32 v71, v71, v75
	v_lshlrev_b32_e32 v74, 16, v99
	v_and_b32_e32 v75, 0xffff0000, v99
	v_mul_f32_e32 v72, v72, v74
	v_mul_f32_e32 v73, v73, v75
	v_lshlrev_b32_e32 v74, 16, v100
	v_and_b32_e32 v75, 0xffff0000, v100
	v_mul_f32_e32 v74, v66, v74
	v_mul_f32_e32 v75, v67, v75
	v_exp_f32_e64 v66, -v68
	v_exp_f32_e64 v67, -v69
	v_lshlrev_b32_e32 v68, 16, v101
	v_and_b32_e32 v69, 0xffff0000, v101
	v_add_f32_e32 v66, 1.0, v66
	v_add_f32_e32 v67, 1.0, v67
	v_rcp_f32_e32 v66, v66
	v_rcp_f32_e32 v67, v67
	v_exp_f32_e64 v51, -v51
	v_add_f32_e32 v54, 1.0, v54
	v_add_f32_e32 v55, 1.0, v55
	v_mul_f32_e32 v76, v66, v68
	v_mul_f32_e32 v77, v67, v69
	v_cvt_pk_bf16_f32 v66, v70, v71
	v_cvt_pk_bf16_f32 v67, v72, v73
	v_cvt_pk_bf16_f32 v68, v74, v75
	v_cvt_pk_bf16_f32 v69, v76, v77
	global_store_dwordx4 v[110:111], v[66:69], off offset:256
	v_rcp_f32_e32 v54, v54
	v_rcp_f32_e32 v55, v55
	v_add_u32_e32 v66, 0x80, v165
	v_mad_i64_i32 v[66:67], s[4:5], v66, s16, v[154:155]
	v_lshl_add_u64 v[80:81], v[66:67], 0, v[156:157]
	global_load_dwordx4 v[82:85], v[80:81], off
	global_load_dwordx4 v[74:77], v[80:81], off offset:256
	v_add_u32_e32 v66, 0x90, v165
	v_mad_i64_i32 v[66:67], s[4:5], v66, s16, v[154:155]
	v_lshl_add_u64 v[78:79], v[66:67], 0, v[156:157]
	global_load_dwordx4 v[70:73], v[78:79], off
	global_load_dwordx4 v[66:69], v[78:79], off offset:256
	v_add_f32_e32 v56, 1.0, v56
	v_add_f32_e32 v57, 1.0, v57
	v_rcp_f32_e32 v56, v56
	v_rcp_f32_e32 v57, v57
	v_add_f32_e32 v50, 1.0, v50
	v_add_f32_e32 v51, 1.0, v51
	v_rcp_f32_e32 v50, v50
	v_rcp_f32_e32 v51, v51
	v_exp_f32_e64 v46, -v46
	v_exp_f32_e64 v47, -v47
	v_exp_f32_e64 v48, -v48
	v_exp_f32_e64 v49, -v49
	v_exp_f32_e64 v42, -v42
	v_exp_f32_e64 v43, -v43
	v_add_f32_e32 v46, 1.0, v46
	v_add_f32_e32 v47, 1.0, v47
	v_rcp_f32_e32 v46, v46
	v_rcp_f32_e32 v47, v47
	v_add_f32_e32 v48, 1.0, v48
	v_add_f32_e32 v49, 1.0, v49
	v_rcp_f32_e32 v48, v48
	v_rcp_f32_e32 v49, v49
	v_add_f32_e32 v42, 1.0, v42
	v_add_f32_e32 v43, 1.0, v43
	v_rcp_f32_e32 v42, v42
	v_rcp_f32_e32 v43, v43
	v_exp_f32_e64 v38, -v38
	v_exp_f32_e64 v39, -v39
	v_exp_f32_e64 v40, -v40
	v_exp_f32_e64 v41, -v41
	v_exp_f32_e64 v34, -v34
	v_exp_f32_e64 v35, -v35
	v_add_f32_e32 v38, 1.0, v38
	v_add_f32_e32 v39, 1.0, v39
	v_rcp_f32_e32 v38, v38
	v_rcp_f32_e32 v39, v39
	v_add_f32_e32 v40, 1.0, v40
	v_add_f32_e32 v41, 1.0, v41
	v_rcp_f32_e32 v40, v40
	v_rcp_f32_e32 v41, v41
	v_add_f32_e32 v34, 1.0, v34
	v_add_f32_e32 v35, 1.0, v35
	v_rcp_f32_e32 v34, v34
	v_rcp_f32_e32 v35, v35
	v_exp_f32_e64 v32, -v32
	v_exp_f32_e64 v33, -v33
	v_exp_f32_e64 v26, -v26
	v_exp_f32_e64 v27, -v27
	v_add_f32_e32 v32, 1.0, v32
	v_add_f32_e32 v33, 1.0, v33
	v_rcp_f32_e32 v32, v32
	v_rcp_f32_e32 v33, v33
	v_add_f32_e32 v26, 1.0, v26
	v_add_f32_e32 v27, 1.0, v27
	v_rcp_f32_e32 v26, v26
	v_rcp_f32_e32 v27, v27
	v_exp_f32_e64 v30, -v30
	v_exp_f32_e64 v31, -v31
	v_exp_f32_e64 v22, -v22
	v_exp_f32_e64 v23, -v23
	v_add_f32_e32 v30, 1.0, v30
	v_add_f32_e32 v31, 1.0, v31
	v_exp_f32_e64 v24, -v24
	v_exp_f32_e64 v25, -v25
	v_rcp_f32_e32 v30, v30
	v_rcp_f32_e32 v31, v31
	v_exp_f32_e64 v18, -v18
	v_exp_f32_e64 v19, -v19
	v_add_f32_e32 v22, 1.0, v22
	v_add_f32_e32 v23, 1.0, v23
	v_rcp_f32_e32 v22, v22
	v_rcp_f32_e32 v23, v23
	v_add_f32_e32 v24, 1.0, v24
	s_waitcnt vmcnt(3)
	v_lshlrev_b32_e32 v86, 16, v82
	v_and_b32_e32 v87, 0xffff0000, v82
	v_lshlrev_b32_e32 v82, 16, v83
	v_and_b32_e32 v83, 0xffff0000, v83
	v_mul_f32_e32 v64, v64, v82
	v_mul_f32_e32 v65, v65, v83
	v_lshlrev_b32_e32 v82, 16, v84
	v_and_b32_e32 v83, 0xffff0000, v84
	v_mul_f32_e32 v82, v58, v82
	v_mul_f32_e32 v83, v59, v83
	v_exp_f32_e64 v58, -v60
	v_exp_f32_e64 v59, -v61
	v_lshlrev_b32_e32 v60, 16, v85
	v_and_b32_e32 v61, 0xffff0000, v85
	v_add_f32_e32 v58, 1.0, v58
	v_add_f32_e32 v59, 1.0, v59
	v_rcp_f32_e32 v58, v58
	v_rcp_f32_e32 v59, v59
	v_mul_f32_e32 v62, v62, v86
	v_mul_f32_e32 v63, v63, v87
	v_add_f32_e32 v25, 1.0, v25
	v_rcp_f32_e32 v24, v24
	v_mul_f32_e32 v84, v58, v60
	v_mul_f32_e32 v85, v59, v61
	v_cvt_pk_bf16_f32 v58, v62, v63
	v_cvt_pk_bf16_f32 v59, v64, v65
	v_cvt_pk_bf16_f32 v60, v82, v83
	v_cvt_pk_bf16_f32 v61, v84, v85
	global_store_dwordx4 v[80:81], v[58:61], off
	v_rcp_f32_e32 v25, v25
	v_add_f32_e32 v18, 1.0, v18
	s_waitcnt vmcnt(3)
; __device__ __forceinline__ unsigned pk2(float lo, float hi) { f32x2_t v = {lo, hi}; bf16x2_t b = __builtin_convertvector(v, bf16x2_t); return __builtin_bit_cast(unsigned, b); }
; __device__ __forceinline__ float bf_lo(unsigned w) { return __uint_as_float(w << 16); }
; __device__ __forceinline__ float bf_hi(unsigned w) { return __uint_as_float(w & 0xffff0000u); }
;     __device__ __forceinline__ void operator()(const f32x4 (&acc)[2][2][4][2], const pg8::Unit& u, int wr, int wc, int fr, int fq) const {
;     ...
;                     for (int i = 0; i < 4; ++i) { const size_t row = (size_t)(row0 + ai * 128 + (2 * mh + (i >> 1)) * 16); const int co = col0 + (i & 1) * 128;
;                         cw[i] = *(const u32x4*)(O + row * ldc + co); if (MODE >= 3) xw[i] = *(const u32x4*)(X + row * ldx + co); }
;                 }
; #pragma unroll
;                 for (int i = 0; i < 4; ++i) {
;                     const int m = 2 * mh + (i >> 1), bj = i & 1;
;                     bf16_t* p = O + (size_t)(row0 + ai * 128 + m * 16) * ldc + col0 + bj * 128;
;                     const f32x4 v0 = acc[ai][bj][m][0], v1 = acc[ai][bj][m][1];
;                     float v[8] = {v0[0], v0[1], v0[2], v0[3], v1[0], v1[1], v1[2], v1[3]};
;                     if (MODE != 0) {
;                         float c[8] = {bf_lo(cw[i].x), bf_hi(cw[i].x), bf_lo(cw[i].y), bf_hi(cw[i].y), bf_lo(cw[i].z), bf_hi(cw[i].z), bf_lo(cw[i].w), bf_hi(cw[i].w)};
;                         if (MODE == 1) {
; #pragma unroll
;                             for (int e = 0; e < 8; ++e) v[e] = v[e] * sigm2(v[e]) * c[e];
;                         } else if (MODE == 2) {
; #pragma unroll
;                             for (int e = 0; e < 8; ++e) v[e] = sigm2(v[e]) * c[e];
;                         } else {
;                             float x[8] = {bf_lo(xw[i].x), bf_hi(xw[i].x), bf_lo(xw[i].y), bf_hi(xw[i].y), bf_lo(xw[i].z), bf_hi(xw[i].z), bf_lo(xw[i].w), bf_hi(xw[i].w)};
; #pragma unroll
;                             for (int e = 0; e < 8; ++e) v[e] = (MODE == 4 ? 0.f : c[e]) + sigm2(v[e]) * x[e];
;                         }
;                     }
;                     u32x4 w; w.x = pk2(v[0], v[1]); w.y = pk2(v[2], v[3]); w.z = pk2(v[4], v[5]); w.w = pk2(v[6], v[7]);
;                     *(u32x4*)p = w;
	v_lshlrev_b32_e32 v58, 16, v74
	v_and_b32_e32 v59, 0xffff0000, v74
	v_mul_f32_e32 v54, v54, v58
	v_mul_f32_e32 v55, v55, v59
	v_lshlrev_b32_e32 v58, 16, v75
	v_and_b32_e32 v59, 0xffff0000, v75
	v_mul_f32_e32 v56, v56, v58
	v_mul_f32_e32 v57, v57, v59
	v_lshlrev_b32_e32 v58, 16, v76
	v_and_b32_e32 v59, 0xffff0000, v76
	v_mul_f32_e32 v58, v50, v58
	v_mul_f32_e32 v59, v51, v59
	v_exp_f32_e64 v50, -v52
	v_exp_f32_e64 v51, -v53
	v_lshlrev_b32_e32 v52, 16, v77
	v_and_b32_e32 v53, 0xffff0000, v77
	v_add_f32_e32 v50, 1.0, v50
	v_add_f32_e32 v51, 1.0, v51
	v_rcp_f32_e32 v50, v50
	v_rcp_f32_e32 v51, v51
	v_add_f32_e32 v19, 1.0, v19
	v_rcp_f32_e32 v18, v18
	v_rcp_f32_e32 v19, v19
	v_mul_f32_e32 v60, v50, v52
	v_mul_f32_e32 v61, v51, v53
	v_cvt_pk_bf16_f32 v50, v54, v55
	v_cvt_pk_bf16_f32 v51, v56, v57
	v_cvt_pk_bf16_f32 v52, v58, v59
	v_cvt_pk_bf16_f32 v53, v60, v61
	global_store_dwordx4 v[80:81], v[50:53], off offset:256
	v_exp_f32_e64 v14, -v14
	v_exp_f32_e64 v15, -v15
	s_waitcnt vmcnt(3)
	v_lshlrev_b32_e32 v50, 16, v70
	v_and_b32_e32 v51, 0xffff0000, v70
	v_mul_f32_e32 v46, v46, v50
	v_mul_f32_e32 v47, v47, v51
	v_lshlrev_b32_e32 v50, 16, v71
	v_and_b32_e32 v51, 0xffff0000, v71
	v_mul_f32_e32 v48, v48, v50
	v_mul_f32_e32 v49, v49, v51
	v_lshlrev_b32_e32 v50, 16, v72
	v_and_b32_e32 v51, 0xffff0000, v72
	v_mul_f32_e32 v50, v42, v50
	v_mul_f32_e32 v51, v43, v51
	v_exp_f32_e64 v42, -v44
	v_exp_f32_e64 v43, -v45
	v_lshlrev_b32_e32 v44, 16, v73
	v_and_b32_e32 v45, 0xffff0000, v73
	v_add_f32_e32 v42, 1.0, v42
	v_add_f32_e32 v43, 1.0, v43
	v_rcp_f32_e32 v42, v42
	v_rcp_f32_e32 v43, v43
	v_exp_f32_e64 v16, -v16
	v_exp_f32_e64 v17, -v17
	v_exp_f32_e64 v10, -v10
	v_mul_f32_e32 v52, v42, v44
	v_mul_f32_e32 v53, v43, v45
	v_cvt_pk_bf16_f32 v42, v46, v47
	v_cvt_pk_bf16_f32 v43, v48, v49
	v_cvt_pk_bf16_f32 v44, v50, v51
	v_cvt_pk_bf16_f32 v45, v52, v53
	global_store_dwordx4 v[78:79], v[42:45], off
	v_exp_f32_e64 v11, -v11
	v_add_f32_e32 v14, 1.0, v14
	s_waitcnt vmcnt(3)
	v_lshlrev_b32_e32 v42, 16, v66
	v_and_b32_e32 v43, 0xffff0000, v66
	v_mul_f32_e32 v38, v38, v42
	v_mul_f32_e32 v39, v39, v43
	v_lshlrev_b32_e32 v42, 16, v67
	v_and_b32_e32 v43, 0xffff0000, v67
	v_mul_f32_e32 v40, v40, v42
	v_mul_f32_e32 v41, v41, v43
	v_lshlrev_b32_e32 v42, 16, v68
	v_and_b32_e32 v43, 0xffff0000, v68
	v_mul_f32_e32 v42, v34, v42
	v_mul_f32_e32 v43, v35, v43
	v_exp_f32_e64 v34, -v36
	v_exp_f32_e64 v35, -v37
	v_lshlrev_b32_e32 v36, 16, v69
	v_and_b32_e32 v37, 0xffff0000, v69
	v_add_f32_e32 v34, 1.0, v34
	v_add_f32_e32 v35, 1.0, v35
	v_rcp_f32_e32 v34, v34
	v_rcp_f32_e32 v35, v35
	v_add_f32_e32 v15, 1.0, v15
	v_rcp_f32_e32 v14, v14
	v_rcp_f32_e32 v15, v15
	v_mul_f32_e32 v44, v34, v36
	v_mul_f32_e32 v45, v35, v37
	v_cvt_pk_bf16_f32 v34, v38, v39
	v_cvt_pk_bf16_f32 v35, v40, v41
	v_cvt_pk_bf16_f32 v36, v42, v43
	v_cvt_pk_bf16_f32 v37, v44, v45
	global_store_dwordx4 v[78:79], v[34:37], off offset:256
	v_add_f32_e32 v16, 1.0, v16
	v_add_f32_e32 v17, 1.0, v17
	v_add_u32_e32 v34, 0xa0, v165
	v_mad_i64_i32 v[34:35], s[4:5], v34, s16, v[154:155]
	v_lshl_add_u64 v[48:49], v[34:35], 0, v[156:157]
	global_load_dwordx4 v[50:53], v[48:49], off
	global_load_dwordx4 v[42:45], v[48:49], off offset:256
	v_add_u32_e32 v34, 0xb0, v165
	v_mad_i64_i32 v[34:35], s[4:5], v34, s16, v[154:155]
	v_lshl_add_u64 v[46:47], v[34:35], 0, v[156:157]
	global_load_dwordx4 v[38:41], v[46:47], off
	global_load_dwordx4 v[34:37], v[46:47], off offset:256
	v_rcp_f32_e32 v16, v16
	v_rcp_f32_e32 v17, v17
	v_add_f32_e32 v10, 1.0, v10
	v_add_f32_e32 v11, 1.0, v11
	v_rcp_f32_e32 v10, v10
	v_rcp_f32_e32 v11, v11
	v_exp_f32_e64 v6, -v6
	v_exp_f32_e64 v7, -v7
	v_exp_f32_e64 v8, -v8
	v_exp_f32_e64 v9, -v9
	v_exp_f32_e64 v2, -v2
	v_exp_f32_e64 v3, -v3
	v_add_f32_e32 v6, 1.0, v6
	v_add_f32_e32 v7, 1.0, v7
	v_rcp_f32_e32 v6, v6
	v_rcp_f32_e32 v7, v7
	v_add_f32_e32 v8, 1.0, v8
	v_add_f32_e32 v9, 1.0, v9
	v_rcp_f32_e32 v8, v8
	v_rcp_f32_e32 v9, v9
	v_add_f32_e32 v2, 1.0, v2
	v_add_f32_e32 v3, 1.0, v3
	v_rcp_f32_e32 v2, v2
	v_rcp_f32_e32 v3, v3
	s_mov_b64 s[4:5], -1
	s_andn2_b64 vcc, exec, s[38:39]
	s_mov_b32 s33, 0x10000
	s_waitcnt vmcnt(3)
; __device__ __forceinline__ unsigned pk2(float lo, float hi) { f32x2_t v = {lo, hi}; bf16x2_t b = __builtin_convertvector(v, bf16x2_t); return __builtin_bit_cast(unsigned, b); }
; __device__ __forceinline__ float bf_lo(unsigned w) { return __uint_as_float(w << 16); }
; __device__ __forceinline__ float bf_hi(unsigned w) { return __uint_as_float(w & 0xffff0000u); }
;     __device__ __forceinline__ void operator()(const f32x4 (&acc)[2][2][4][2], const pg8::Unit& u, int wr, int wc, int fr, int fq) const {
;     ...
;                 if (MODE != 0) {
; #pragma unroll
;                     for (int i = 0; i < 4; ++i) { const size_t row = (size_t)(row0 + ai * 128 + (2 * mh + (i >> 1)) * 16); const int co = col0 + (i & 1) * 128;
;                         cw[i] = *(const u32x4*)(O + row * ldc + co); if (MODE >= 3) xw[i] = *(const u32x4*)(X + row * ldx + co); }
;                 }
; #pragma unroll
;                 for (int i = 0; i < 4; ++i) {
;                     const int m = 2 * mh + (i >> 1), bj = i & 1;
;                     bf16_t* p = O + (size_t)(row0 + ai * 128 + m * 16) * ldc + col0 + bj * 128;
;                     const f32x4 v0 = acc[ai][bj][m][0], v1 = acc[ai][bj][m][1];
;                     float v[8] = {v0[0], v0[1], v0[2], v0[3], v1[0], v1[1], v1[2], v1[3]};
;                     if (MODE != 0) {
;                         float c[8] = {bf_lo(cw[i].x), bf_hi(cw[i].x), bf_lo(cw[i].y), bf_hi(cw[i].y), bf_lo(cw[i].z), bf_hi(cw[i].z), bf_lo(cw[i].w), bf_hi(cw[i].w)};
;                         if (MODE == 1) {
; #pragma unroll
;                             for (int e = 0; e < 8; ++e) v[e] = v[e] * sigm2(v[e]) * c[e];
;                         } else if (MODE == 2) {
; #pragma unroll
;                             for (int e = 0; e < 8; ++e) v[e] = sigm2(v[e]) * c[e];
;                         } else {
;                             float x[8] = {bf_lo(xw[i].x), bf_hi(xw[i].x), bf_lo(xw[i].y), bf_hi(xw[i].y), bf_lo(xw[i].z), bf_hi(xw[i].z), bf_lo(xw[i].w), bf_hi(xw[i].w)};
; #pragma unroll
;                             for (int e = 0; e < 8; ++e) v[e] = (MODE == 4 ? 0.f : c[e]) + sigm2(v[e]) * x[e];
;                         }
;                     }
;                     u32x4 w; w.x = pk2(v[0], v[1]); w.y = pk2(v[2], v[3]); w.z = pk2(v[4], v[5]); w.w = pk2(v[6], v[7]);
;                     *(u32x4*)p = w;
	v_lshlrev_b32_e32 v54, 16, v50
	v_and_b32_e32 v55, 0xffff0000, v50
	v_lshlrev_b32_e32 v50, 16, v51
	v_and_b32_e32 v51, 0xffff0000, v51
	v_mul_f32_e32 v32, v32, v50
	v_mul_f32_e32 v33, v33, v51
	v_lshlrev_b32_e32 v50, 16, v52
	v_and_b32_e32 v51, 0xffff0000, v52
	v_mul_f32_e32 v50, v26, v50
	v_mul_f32_e32 v51, v27, v51
	v_exp_f32_e64 v26, -v28
	v_exp_f32_e64 v27, -v29
	v_lshlrev_b32_e32 v28, 16, v53
	v_and_b32_e32 v29, 0xffff0000, v53
	v_add_f32_e32 v26, 1.0, v26
	v_add_f32_e32 v27, 1.0, v27
	v_rcp_f32_e32 v26, v26
	v_rcp_f32_e32 v27, v27
	v_mul_f32_e32 v30, v30, v54
	v_mul_f32_e32 v31, v31, v55
	v_mul_f32_e32 v52, v26, v28
	v_mul_f32_e32 v53, v27, v29
	v_cvt_pk_bf16_f32 v26, v30, v31
	v_cvt_pk_bf16_f32 v27, v32, v33
	v_cvt_pk_bf16_f32 v28, v50, v51
	v_cvt_pk_bf16_f32 v29, v52, v53
	global_store_dwordx4 v[48:49], v[26:29], off
	s_waitcnt vmcnt(3)
	s_nop 0
	v_lshlrev_b32_e32 v26, 16, v42
	v_and_b32_e32 v27, 0xffff0000, v42
	v_mul_f32_e32 v22, v22, v26
	v_mul_f32_e32 v23, v23, v27
	v_lshlrev_b32_e32 v26, 16, v43
	v_and_b32_e32 v27, 0xffff0000, v43
	v_mul_f32_e32 v24, v24, v26
	v_mul_f32_e32 v25, v25, v27
	v_lshlrev_b32_e32 v26, 16, v44
	v_and_b32_e32 v27, 0xffff0000, v44
	v_mul_f32_e32 v26, v18, v26
	v_mul_f32_e32 v27, v19, v27
	v_exp_f32_e64 v18, -v20
	v_exp_f32_e64 v19, -v21
	v_lshlrev_b32_e32 v20, 16, v45
	v_and_b32_e32 v21, 0xffff0000, v45
	v_add_f32_e32 v18, 1.0, v18
	v_add_f32_e32 v19, 1.0, v19
	v_rcp_f32_e32 v18, v18
	v_rcp_f32_e32 v19, v19
	s_nop 0
	v_mul_f32_e32 v28, v18, v20
	v_mul_f32_e32 v29, v19, v21
	v_cvt_pk_bf16_f32 v18, v22, v23
	v_cvt_pk_bf16_f32 v19, v24, v25
	v_cvt_pk_bf16_f32 v20, v26, v27
	v_cvt_pk_bf16_f32 v21, v28, v29
	global_store_dwordx4 v[48:49], v[18:21], off offset:256
	s_waitcnt vmcnt(3)
	s_nop 0
	v_lshlrev_b32_e32 v18, 16, v38
	v_and_b32_e32 v19, 0xffff0000, v38
	v_mul_f32_e32 v14, v14, v18
	v_mul_f32_e32 v15, v15, v19
	v_lshlrev_b32_e32 v18, 16, v39
	v_and_b32_e32 v19, 0xffff0000, v39
	v_mul_f32_e32 v16, v16, v18
	v_mul_f32_e32 v17, v17, v19
	v_lshlrev_b32_e32 v18, 16, v40
	v_and_b32_e32 v19, 0xffff0000, v40
	v_mul_f32_e32 v18, v10, v18
	v_mul_f32_e32 v19, v11, v19
	v_exp_f32_e64 v10, -v12
	v_exp_f32_e64 v11, -v13
	v_lshlrev_b32_e32 v12, 16, v41
	v_and_b32_e32 v13, 0xffff0000, v41
	v_add_f32_e32 v10, 1.0, v10
	v_add_f32_e32 v11, 1.0, v11
	v_rcp_f32_e32 v10, v10
	v_rcp_f32_e32 v11, v11
	s_nop 0
	v_mul_f32_e32 v20, v10, v12
	v_mul_f32_e32 v21, v11, v13
	v_cvt_pk_bf16_f32 v10, v14, v15
	v_cvt_pk_bf16_f32 v11, v16, v17
	v_cvt_pk_bf16_f32 v12, v18, v19
	v_cvt_pk_bf16_f32 v13, v20, v21
	global_store_dwordx4 v[46:47], v[10:13], off
	s_waitcnt vmcnt(3)
	s_nop 0
	v_lshlrev_b32_e32 v10, 16, v34
	v_and_b32_e32 v11, 0xffff0000, v34
	v_mul_f32_e32 v6, v6, v10
	v_mul_f32_e32 v7, v7, v11
	v_lshlrev_b32_e32 v10, 16, v35
	v_and_b32_e32 v11, 0xffff0000, v35
	v_mul_f32_e32 v8, v8, v10
	v_mul_f32_e32 v9, v9, v11
	v_lshlrev_b32_e32 v10, 16, v36
	v_and_b32_e32 v11, 0xffff0000, v36
	v_mul_f32_e32 v10, v2, v10
	v_mul_f32_e32 v11, v3, v11
	v_exp_f32_e64 v2, -v4
	v_exp_f32_e64 v3, -v5
	v_lshlrev_b32_e32 v4, 16, v37
	v_and_b32_e32 v5, 0xffff0000, v37
	v_add_f32_e32 v2, 1.0, v2
	v_add_f32_e32 v3, 1.0, v3
	v_rcp_f32_e32 v2, v2
	v_rcp_f32_e32 v3, v3
	s_nop 0
	v_mul_f32_e32 v12, v2, v4
	v_mul_f32_e32 v13, v3, v5
	v_cvt_pk_bf16_f32 v2, v6, v7
	v_cvt_pk_bf16_f32 v3, v8, v9
	v_cvt_pk_bf16_f32 v4, v10, v11
	v_cvt_pk_bf16_f32 v5, v12, v13
	global_store_dwordx4 v[46:47], v[2:5], off offset:256
	s_cbranch_vccnz .LBB0_1391
	s_andn2_b64 vcc, exec, s[36:37]
	s_cbranch_vccnz .LBB0_1390
	s_barrier
	s_branch .LBB0_1390

; __device__ __forceinline__ unsigned pk2(float lo, float hi) { f32x2_t v = {lo, hi}; bf16x2_t b = __builtin_convertvector(v, bf16x2_t); return __builtin_bit_cast(unsigned, b); }
; __device__ __forceinline__ float bf_lo(unsigned w) { return __uint_as_float(w << 16); }
; __device__ __forceinline__ float bf_hi(unsigned w) { return __uint_as_float(w & 0xffff0000u); }
;     __device__ __forceinline__ void operator()(const f32x4 (&acc)[2][2][4][2], const pg8::Unit& u, int wr, int wc, int fr, int fq) const {
;     ...
;                 if (MODE != 0) {
; #pragma unroll
;                     for (int i = 0; i < 4; ++i) { const size_t row = (size_t)(row0 + ai * 128 + (2 * mh + (i >> 1)) * 16); const int co = col0 + (i & 1) * 128;
;                         cw[i] = *(const u32x4*)(O + row * ldc + co); if (MODE >= 3) xw[i] = *(const u32x4*)(X + row * ldx + co); }
;                 }
; #pragma unroll
;                 for (int i = 0; i < 4; ++i) {
;                     const int m = 2 * mh + (i >> 1), bj = i & 1;
;                     bf16_t* p = O + (size_t)(row0 + ai * 128 + m * 16) * ldc + col0 + bj * 128;
;                     const f32x4 v0 = acc[ai][bj][m][0], v1 = acc[ai][bj][m][1];
;                     float v[8] = {v0[0], v0[1], v0[2], v0[3], v1[0], v1[1], v1[2], v1[3]};
;                     if (MODE != 0) {
;                         float c[8] = {bf_lo(cw[i].x), bf_hi(cw[i].x), bf_lo(cw[i].y), bf_hi(cw[i].y), bf_lo(cw[i].z), bf_hi(cw[i].z), bf_lo(cw[i].w), bf_hi(cw[i].w)};
;                         if (MODE == 1) {
; #pragma unroll
;                             for (int e = 0; e < 8; ++e) v[e] = v[e] * sigm2(v[e]) * c[e];
;                         } else if (MODE == 2) {
; #pragma unroll
;                             for (int e = 0; e < 8; ++e) v[e] = sigm2(v[e]) * c[e];
;                         } else {
;                             float x[8] = {bf_lo(xw[i].x), bf_hi(xw[i].x), bf_lo(xw[i].y), bf_hi(xw[i].y), bf_lo(xw[i].z), bf_hi(xw[i].z), bf_lo(xw[i].w), bf_hi(xw[i].w)};
; #pragma unroll
;                             for (int e = 0; e < 8; ++e) v[e] = (MODE == 4 ? 0.f : c[e]) + sigm2(v[e]) * x[e];
;                         }
;                     }
;                     u32x4 w; w.x = pk2(v[0], v[1]); w.y = pk2(v[2], v[3]); w.z = pk2(v[4], v[5]); w.w = pk2(v[6], v[7]);
;                     *(u32x4*)p = w;
.LBB0_1444:
	v_lshl_or_b32 v122, s13, 8, v185
	v_lshl_add_u32 v174, s22, 8, v0
	v_ashrrev_i32_e32 v123, 31, v122
	v_mov_b64_e32 v[178:179], s[30:31]
	v_ashrrev_i32_e32 v175, 31, v174
	v_mad_i64_i32 v[124:125], s[4:5], v174, s16, v[178:179]
	v_lshlrev_b64 v[176:177], 1, v[122:123]
	v_lshl_add_u64 v[182:183], v[124:125], 0, v[176:177]
	v_lshlrev_b64 v[122:123], 11, v[174:175]
	global_load_dwordx4 v[154:157], v[182:183], off
	v_lshl_add_u64 v[122:123], s[92:93], 0, v[122:123]
	v_lshl_add_u64 v[122:123], v[122:123], 0, v[176:177]
	global_load_dwordx4 v[158:161], v[122:123], off
	global_load_dwordx4 v[146:149], v[182:183], off offset:256
	global_load_dwordx4 v[150:153], v[122:123], off offset:256
	v_or_b32_e32 v122, 16, v174
	v_ashrrev_i32_e32 v123, 31, v122
	v_mad_i64_i32 v[124:125], s[4:5], v122, s16, v[178:179]
	v_lshl_add_u64 v[180:181], v[124:125], 0, v[176:177]
	v_lshlrev_b64 v[122:123], 11, v[122:123]
	global_load_dwordx4 v[134:137], v[180:181], off
	v_lshl_add_u64 v[122:123], s[92:93], 0, v[122:123]
	v_lshl_add_u64 v[122:123], v[122:123], 0, v[176:177]
	global_load_dwordx4 v[138:141], v[122:123], off
	global_load_dwordx4 v[126:129], v[180:181], off offset:256
	s_nop 0
	global_load_dwordx4 v[122:125], v[122:123], off offset:256
	v_exp_f32_e64 v144, -v144
	v_exp_f32_e64 v145, -v145
	v_exp_f32_e64 v130, -v130
	v_exp_f32_e64 v131, -v131
	v_add_f32_e32 v144, 1.0, v144
	v_add_f32_e32 v145, 1.0, v145
	v_rcp_f32_e32 v144, v144
	v_rcp_f32_e32 v145, v145
	v_add_f32_e32 v130, 1.0, v130
	v_add_f32_e32 v131, 1.0, v131
	v_rcp_f32_e32 v130, v130
	v_rcp_f32_e32 v131, v131
	v_exp_f32_e64 v142, -v142
	v_exp_f32_e64 v143, -v143
	v_exp_f32_e64 v118, -v118
	v_exp_f32_e64 v119, -v119
	v_add_f32_e32 v142, 1.0, v142
	v_add_f32_e32 v143, 1.0, v143
	v_exp_f32_e64 v120, -v120
	v_exp_f32_e64 v121, -v121
	v_rcp_f32_e32 v142, v142
	v_rcp_f32_e32 v143, v143
	v_exp_f32_e64 v114, -v114
	v_exp_f32_e64 v115, -v115
	v_add_f32_e32 v118, 1.0, v118
	v_add_f32_e32 v119, 1.0, v119
	v_rcp_f32_e32 v118, v118
	v_rcp_f32_e32 v119, v119
	v_add_f32_e32 v120, 1.0, v120
	v_add_f32_e32 v121, 1.0, v121
	v_rcp_f32_e32 v120, v120
	v_rcp_f32_e32 v121, v121
	v_add_f32_e32 v114, 1.0, v114
	v_add_f32_e32 v115, 1.0, v115
	v_rcp_f32_e32 v114, v114
	v_rcp_f32_e32 v115, v115
	v_exp_f32_e64 v110, -v110
	v_exp_f32_e64 v111, -v111
	v_exp_f32_e64 v112, -v112
	v_exp_f32_e64 v113, -v113
	v_exp_f32_e64 v106, -v106
	v_exp_f32_e64 v107, -v107
	v_add_f32_e32 v110, 1.0, v110
	v_add_f32_e32 v111, 1.0, v111
	v_rcp_f32_e32 v110, v110
	v_rcp_f32_e32 v111, v111
	v_add_f32_e32 v112, 1.0, v112
	v_add_f32_e32 v113, 1.0, v113
	v_rcp_f32_e32 v112, v112
	v_rcp_f32_e32 v113, v113
	v_add_f32_e32 v106, 1.0, v106
	v_add_f32_e32 v107, 1.0, v107
	v_rcp_f32_e32 v106, v106
	v_rcp_f32_e32 v107, v107
	v_exp_f32_e64 v102, -v102
	v_exp_f32_e64 v103, -v103
	v_exp_f32_e64 v104, -v104
	v_exp_f32_e64 v105, -v105
	v_exp_f32_e64 v98, -v98
	v_exp_f32_e64 v99, -v99
	v_add_f32_e32 v102, 1.0, v102
	v_add_f32_e32 v103, 1.0, v103
	v_rcp_f32_e32 v102, v102
	v_rcp_f32_e32 v103, v103
	v_add_f32_e32 v104, 1.0, v104
	v_add_f32_e32 v105, 1.0, v105
	s_waitcnt vmcnt(0)
	v_lshlrev_b32_e32 v188, 16, v154
	v_and_b32_e32 v189, 0xffff0000, v154
	v_lshlrev_b32_e32 v194, 16, v158
	v_and_b32_e32 v195, 0xffff0000, v158
	v_lshlrev_b32_e32 v154, 16, v155
	v_and_b32_e32 v155, 0xffff0000, v155
	v_lshlrev_b32_e32 v158, 16, v159
	v_and_b32_e32 v159, 0xffff0000, v159
	v_fma_f32 v144, v144, v158, v154
	v_fma_f32 v145, v145, v159, v155
	v_lshlrev_b32_e32 v154, 16, v156
	v_and_b32_e32 v155, 0xffff0000, v156
	v_lshlrev_b32_e32 v158, 16, v160
	v_and_b32_e32 v159, 0xffff0000, v160
	v_fma_f32 v154, v130, v158, v154
	v_fma_f32 v155, v131, v159, v155
	v_exp_f32_e64 v130, -v132
	v_exp_f32_e64 v131, -v133
	v_lshlrev_b32_e32 v132, 16, v157
	v_and_b32_e32 v133, 0xffff0000, v157
	v_add_f32_e32 v130, 1.0, v130
	v_add_f32_e32 v131, 1.0, v131
	v_rcp_f32_e32 v130, v130
	v_rcp_f32_e32 v131, v131
	v_lshlrev_b32_e32 v156, 16, v161
	v_and_b32_e32 v157, 0xffff0000, v161
	v_fma_f32 v142, v142, v194, v188
	v_fma_f32 v143, v143, v195, v189
	v_fma_f32 v156, v130, v156, v132
	v_fma_f32 v157, v131, v157, v133
	v_cvt_pk_bf16_f32 v130, v142, v143
	v_cvt_pk_bf16_f32 v131, v144, v145
	v_cvt_pk_bf16_f32 v132, v154, v155
	v_cvt_pk_bf16_f32 v133, v156, v157
	global_store_dwordx4 v[182:183], v[130:133], off
	v_rcp_f32_e32 v104, v104
	v_rcp_f32_e32 v105, v105
	v_lshlrev_b32_e32 v130, 16, v146
	v_and_b32_e32 v131, 0xffff0000, v146
	v_lshlrev_b32_e32 v132, 16, v150
	v_and_b32_e32 v133, 0xffff0000, v150
	v_fma_f32 v118, v118, v132, v130
	v_fma_f32 v119, v119, v133, v131
	v_lshlrev_b32_e32 v130, 16, v147
	v_and_b32_e32 v131, 0xffff0000, v147
	v_lshlrev_b32_e32 v132, 16, v151
	v_and_b32_e32 v133, 0xffff0000, v151
	v_fma_f32 v120, v120, v132, v130
	v_fma_f32 v121, v121, v133, v131
	v_lshlrev_b32_e32 v130, 16, v148
	v_and_b32_e32 v131, 0xffff0000, v148
	v_lshlrev_b32_e32 v132, 16, v152
	v_and_b32_e32 v133, 0xffff0000, v152
	v_fma_f32 v130, v114, v132, v130
	v_fma_f32 v131, v115, v133, v131
	v_exp_f32_e64 v114, -v116
	v_exp_f32_e64 v115, -v117
	v_lshlrev_b32_e32 v116, 16, v149
	v_and_b32_e32 v117, 0xffff0000, v149
	v_add_f32_e32 v114, 1.0, v114
	v_add_f32_e32 v115, 1.0, v115
	v_rcp_f32_e32 v114, v114
	v_rcp_f32_e32 v115, v115
	v_lshlrev_b32_e32 v132, 16, v153
	v_and_b32_e32 v133, 0xffff0000, v153
	v_add_f32_e32 v98, 1.0, v98
	v_fma_f32 v132, v114, v132, v116
	v_fma_f32 v133, v115, v133, v117
	v_cvt_pk_bf16_f32 v114, v118, v119
	v_cvt_pk_bf16_f32 v115, v120, v121
	v_cvt_pk_bf16_f32 v116, v130, v131
	v_cvt_pk_bf16_f32 v117, v132, v133
	global_store_dwordx4 v[182:183], v[114:117], off offset:256
; __device__ __forceinline__ unsigned pk2(float lo, float hi) { f32x2_t v = {lo, hi}; bf16x2_t b = __builtin_convertvector(v, bf16x2_t); return __builtin_bit_cast(unsigned, b); }
; __device__ __forceinline__ float bf_lo(unsigned w) { return __uint_as_float(w << 16); }
; __device__ __forceinline__ float bf_hi(unsigned w) { return __uint_as_float(w & 0xffff0000u); }
;     __device__ __forceinline__ void operator()(const f32x4 (&acc)[2][2][4][2], const pg8::Unit& u, int wr, int wc, int fr, int fq) const {
;     ...
;                 if (MODE != 0) {
; #pragma unroll
;                     for (int i = 0; i < 4; ++i) { const size_t row = (size_t)(row0 + ai * 128 + (2 * mh + (i >> 1)) * 16); const int co = col0 + (i & 1) * 128;
;                         cw[i] = *(const u32x4*)(O + row * ldc + co); if (MODE >= 3) xw[i] = *(const u32x4*)(X + row * ldx + co); }
;                 }
; #pragma unroll
;                 for (int i = 0; i < 4; ++i) {
;                     const int m = 2 * mh + (i >> 1), bj = i & 1;
;                     bf16_t* p = O + (size_t)(row0 + ai * 128 + m * 16) * ldc + col0 + bj * 128;
;                     const f32x4 v0 = acc[ai][bj][m][0], v1 = acc[ai][bj][m][1];
;                     float v[8] = {v0[0], v0[1], v0[2], v0[3], v1[0], v1[1], v1[2], v1[3]};
;                     if (MODE != 0) {
;                         float c[8] = {bf_lo(cw[i].x), bf_hi(cw[i].x), bf_lo(cw[i].y), bf_hi(cw[i].y), bf_lo(cw[i].z), bf_hi(cw[i].z), bf_lo(cw[i].w), bf_hi(cw[i].w)};
;                         if (MODE == 1) {
; #pragma unroll
;                             for (int e = 0; e < 8; ++e) v[e] = v[e] * sigm2(v[e]) * c[e];
;                         } else if (MODE == 2) {
; #pragma unroll
;                             for (int e = 0; e < 8; ++e) v[e] = sigm2(v[e]) * c[e];
;                         } else {
;                             float x[8] = {bf_lo(xw[i].x), bf_hi(xw[i].x), bf_lo(xw[i].y), bf_hi(xw[i].y), bf_lo(xw[i].z), bf_hi(xw[i].z), bf_lo(xw[i].w), bf_hi(xw[i].w)};
; #pragma unroll
;                             for (int e = 0; e < 8; ++e) v[e] = (MODE == 4 ? 0.f : c[e]) + sigm2(v[e]) * x[e];
;                         }
;                     }
;                     u32x4 w; w.x = pk2(v[0], v[1]); w.y = pk2(v[2], v[3]); w.z = pk2(v[4], v[5]); w.w = pk2(v[6], v[7]);
;                     *(u32x4*)p = w;
	v_add_f32_e32 v99, 1.0, v99
	v_rcp_f32_e32 v98, v98
	v_lshlrev_b32_e32 v114, 16, v134
	v_and_b32_e32 v115, 0xffff0000, v134
	v_lshlrev_b32_e32 v116, 16, v138
	v_and_b32_e32 v117, 0xffff0000, v138
	v_fma_f32 v110, v110, v116, v114
	v_fma_f32 v111, v111, v117, v115
	v_lshlrev_b32_e32 v114, 16, v135
	v_and_b32_e32 v115, 0xffff0000, v135
	v_lshlrev_b32_e32 v116, 16, v139
	v_and_b32_e32 v117, 0xffff0000, v139
	v_fma_f32 v112, v112, v116, v114
	v_fma_f32 v113, v113, v117, v115
	v_lshlrev_b32_e32 v114, 16, v136
	v_and_b32_e32 v115, 0xffff0000, v136
	v_lshlrev_b32_e32 v116, 16, v140
	v_and_b32_e32 v117, 0xffff0000, v140
	v_fma_f32 v114, v106, v116, v114
	v_fma_f32 v115, v107, v117, v115
	v_exp_f32_e64 v106, -v108
	v_exp_f32_e64 v107, -v109
	v_lshlrev_b32_e32 v108, 16, v137
	v_and_b32_e32 v109, 0xffff0000, v137
	v_add_f32_e32 v106, 1.0, v106
	v_add_f32_e32 v107, 1.0, v107
	v_rcp_f32_e32 v106, v106
	v_rcp_f32_e32 v107, v107
	v_lshlrev_b32_e32 v116, 16, v141
	v_and_b32_e32 v117, 0xffff0000, v141
	v_rcp_f32_e32 v99, v99
	v_fma_f32 v116, v106, v116, v108
	v_fma_f32 v117, v107, v117, v109
	v_cvt_pk_bf16_f32 v106, v110, v111
	v_cvt_pk_bf16_f32 v107, v112, v113
	v_cvt_pk_bf16_f32 v108, v114, v115
	v_cvt_pk_bf16_f32 v109, v116, v117
	global_store_dwordx4 v[180:181], v[106:109], off
	v_exp_f32_e64 v96, -v96
	v_exp_f32_e64 v97, -v97
	v_lshlrev_b32_e32 v106, 16, v126
	v_and_b32_e32 v107, 0xffff0000, v126
	v_lshlrev_b32_e32 v108, 16, v122
	v_and_b32_e32 v109, 0xffff0000, v122
	v_fma_f32 v102, v102, v108, v106
	v_fma_f32 v103, v103, v109, v107
	v_lshlrev_b32_e32 v106, 16, v127
	v_and_b32_e32 v107, 0xffff0000, v127
	v_lshlrev_b32_e32 v108, 16, v123
	v_and_b32_e32 v109, 0xffff0000, v123
	v_fma_f32 v104, v104, v108, v106
	v_fma_f32 v105, v105, v109, v107
	v_lshlrev_b32_e32 v106, 16, v128
	v_and_b32_e32 v107, 0xffff0000, v128
	v_lshlrev_b32_e32 v108, 16, v124
	v_and_b32_e32 v109, 0xffff0000, v124
	v_fma_f32 v106, v98, v108, v106
	v_fma_f32 v107, v99, v109, v107
	v_exp_f32_e64 v98, -v100
	v_exp_f32_e64 v99, -v101
	v_lshlrev_b32_e32 v100, 16, v129
	v_and_b32_e32 v101, 0xffff0000, v129
	v_add_f32_e32 v98, 1.0, v98
	v_add_f32_e32 v99, 1.0, v99
	v_rcp_f32_e32 v98, v98
	v_rcp_f32_e32 v99, v99
	v_lshlrev_b32_e32 v108, 16, v125
	v_and_b32_e32 v109, 0xffff0000, v125
	v_exp_f32_e64 v90, -v90
	v_fma_f32 v108, v98, v108, v100
	v_fma_f32 v109, v99, v109, v101
	v_cvt_pk_bf16_f32 v98, v102, v103
	v_cvt_pk_bf16_f32 v99, v104, v105
	v_cvt_pk_bf16_f32 v100, v106, v107
	v_cvt_pk_bf16_f32 v101, v108, v109
	global_store_dwordx4 v[180:181], v[98:101], off offset:256
	v_exp_f32_e64 v91, -v91
	v_add_f32_e32 v96, 1.0, v96
	v_or_b32_e32 v98, 32, v174
	v_ashrrev_i32_e32 v99, 31, v98
	v_mad_i64_i32 v[100:101], s[4:5], v98, s16, v[178:179]
	v_lshl_add_u64 v[124:125], v[100:101], 0, v[176:177]
	v_lshlrev_b64 v[98:99], 11, v[98:99]
	global_load_dwordx4 v[126:129], v[124:125], off
	v_lshl_add_u64 v[98:99], s[92:93], 0, v[98:99]
	v_lshl_add_u64 v[98:99], v[98:99], 0, v[176:177]
	global_load_dwordx4 v[130:133], v[98:99], off
	global_load_dwordx4 v[118:121], v[124:125], off offset:256
	global_load_dwordx4 v[114:117], v[98:99], off offset:256
	v_or_b32_e32 v98, 48, v174
	v_ashrrev_i32_e32 v99, 31, v98
	v_mad_i64_i32 v[100:101], s[4:5], v98, s16, v[178:179]
	v_lshl_add_u64 v[122:123], v[100:101], 0, v[176:177]
	v_lshlrev_b64 v[98:99], 11, v[98:99]
	global_load_dwordx4 v[106:109], v[122:123], off
	v_lshl_add_u64 v[98:99], s[92:93], 0, v[98:99]
	v_lshl_add_u64 v[98:99], v[98:99], 0, v[176:177]
	global_load_dwordx4 v[110:113], v[98:99], off
	global_load_dwordx4 v[102:105], v[122:123], off offset:256
	s_nop 0
	global_load_dwordx4 v[98:101], v[98:99], off offset:256
	v_add_f32_e32 v97, 1.0, v97
	v_rcp_f32_e32 v96, v96
	v_rcp_f32_e32 v97, v97
	v_add_f32_e32 v90, 1.0, v90
	v_add_f32_e32 v91, 1.0, v91
	v_rcp_f32_e32 v90, v90
	v_rcp_f32_e32 v91, v91
	v_exp_f32_e64 v94, -v94
	v_exp_f32_e64 v95, -v95
	v_exp_f32_e64 v86, -v86
	v_exp_f32_e64 v87, -v87
	v_add_f32_e32 v94, 1.0, v94
	v_add_f32_e32 v95, 1.0, v95
	v_exp_f32_e64 v88, -v88
	v_exp_f32_e64 v89, -v89
	v_rcp_f32_e32 v94, v94
	v_rcp_f32_e32 v95, v95
	v_exp_f32_e64 v82, -v82
	v_exp_f32_e64 v83, -v83
	v_add_f32_e32 v86, 1.0, v86
	v_add_f32_e32 v87, 1.0, v87
	v_rcp_f32_e32 v86, v86
	v_rcp_f32_e32 v87, v87
	v_add_f32_e32 v88, 1.0, v88
	v_add_f32_e32 v89, 1.0, v89
	v_rcp_f32_e32 v88, v88
	v_rcp_f32_e32 v89, v89
	v_add_f32_e32 v82, 1.0, v82
	v_add_f32_e32 v83, 1.0, v83
	v_rcp_f32_e32 v82, v82
	v_rcp_f32_e32 v83, v83
	v_exp_f32_e64 v78, -v78
	v_exp_f32_e64 v79, -v79
	v_exp_f32_e64 v80, -v80
	v_exp_f32_e64 v81, -v81
	v_exp_f32_e64 v74, -v74
	v_exp_f32_e64 v75, -v75
	v_add_f32_e32 v78, 1.0, v78
	v_add_f32_e32 v79, 1.0, v79
	v_rcp_f32_e32 v78, v78
	v_rcp_f32_e32 v79, v79
	v_add_f32_e32 v80, 1.0, v80
	v_add_f32_e32 v81, 1.0, v81
	v_rcp_f32_e32 v80, v80
	v_rcp_f32_e32 v81, v81
	v_add_f32_e32 v74, 1.0, v74
	v_add_f32_e32 v75, 1.0, v75
	v_rcp_f32_e32 v74, v74
	v_rcp_f32_e32 v75, v75
	v_exp_f32_e64 v70, -v70
	v_exp_f32_e64 v71, -v71
	v_exp_f32_e64 v72, -v72
	v_exp_f32_e64 v73, -v73
	v_exp_f32_e64 v66, -v66
	v_exp_f32_e64 v67, -v67
	v_add_f32_e32 v70, 1.0, v70
	v_add_f32_e32 v71, 1.0, v71
	v_rcp_f32_e32 v70, v70
	v_rcp_f32_e32 v71, v71
	v_add_f32_e32 v72, 1.0, v72
	v_add_f32_e32 v73, 1.0, v73
	v_rcp_f32_e32 v72, v72
	v_rcp_f32_e32 v73, v73
	v_add_f32_e32 v66, 1.0, v66
	v_add_f32_e32 v67, 1.0, v67
	v_rcp_f32_e32 v66, v66
	s_waitcnt vmcnt(7)
	v_lshlrev_b32_e32 v134, 16, v126
	v_and_b32_e32 v135, 0xffff0000, v126
	s_waitcnt vmcnt(6)
; __device__ __forceinline__ unsigned pk2(float lo, float hi) { f32x2_t v = {lo, hi}; bf16x2_t b = __builtin_convertvector(v, bf16x2_t); return __builtin_bit_cast(unsigned, b); }
; __device__ __forceinline__ float bf_lo(unsigned w) { return __uint_as_float(w << 16); }
; __device__ __forceinline__ float bf_hi(unsigned w) { return __uint_as_float(w & 0xffff0000u); }
;     __device__ __forceinline__ void operator()(const f32x4 (&acc)[2][2][4][2], const pg8::Unit& u, int wr, int wc, int fr, int fq) const {
;     ...
;                 if (MODE != 0) {
; #pragma unroll
;                     for (int i = 0; i < 4; ++i) { const size_t row = (size_t)(row0 + ai * 128 + (2 * mh + (i >> 1)) * 16); const int co = col0 + (i & 1) * 128;
;                         cw[i] = *(const u32x4*)(O + row * ldc + co); if (MODE >= 3) xw[i] = *(const u32x4*)(X + row * ldx + co); }
;                 }
; #pragma unroll
;                 for (int i = 0; i < 4; ++i) {
;                     const int m = 2 * mh + (i >> 1), bj = i & 1;
;                     bf16_t* p = O + (size_t)(row0 + ai * 128 + m * 16) * ldc + col0 + bj * 128;
;                     const f32x4 v0 = acc[ai][bj][m][0], v1 = acc[ai][bj][m][1];
;                     float v[8] = {v0[0], v0[1], v0[2], v0[3], v1[0], v1[1], v1[2], v1[3]};
;                     if (MODE != 0) {
;                         float c[8] = {bf_lo(cw[i].x), bf_hi(cw[i].x), bf_lo(cw[i].y), bf_hi(cw[i].y), bf_lo(cw[i].z), bf_hi(cw[i].z), bf_lo(cw[i].w), bf_hi(cw[i].w)};
;                         if (MODE == 1) {
; #pragma unroll
;                             for (int e = 0; e < 8; ++e) v[e] = v[e] * sigm2(v[e]) * c[e];
;                         } else if (MODE == 2) {
; #pragma unroll
;                             for (int e = 0; e < 8; ++e) v[e] = sigm2(v[e]) * c[e];
;                         } else {
;                             float x[8] = {bf_lo(xw[i].x), bf_hi(xw[i].x), bf_lo(xw[i].y), bf_hi(xw[i].y), bf_lo(xw[i].z), bf_hi(xw[i].z), bf_lo(xw[i].w), bf_hi(xw[i].w)};
; #pragma unroll
;                             for (int e = 0; e < 8; ++e) v[e] = (MODE == 4 ? 0.f : c[e]) + sigm2(v[e]) * x[e];
;                         }
;                     }
;                     u32x4 w; w.x = pk2(v[0], v[1]); w.y = pk2(v[2], v[3]); w.z = pk2(v[4], v[5]); w.w = pk2(v[6], v[7]);
;                     *(u32x4*)p = w;
	v_lshlrev_b32_e32 v136, 16, v130
	v_and_b32_e32 v137, 0xffff0000, v130
	v_lshlrev_b32_e32 v126, 16, v127
	v_and_b32_e32 v127, 0xffff0000, v127
	v_lshlrev_b32_e32 v130, 16, v131
	v_and_b32_e32 v131, 0xffff0000, v131
	v_fma_f32 v96, v96, v130, v126
	v_fma_f32 v97, v97, v131, v127
	v_lshlrev_b32_e32 v126, 16, v128
	v_and_b32_e32 v127, 0xffff0000, v128
	v_lshlrev_b32_e32 v130, 16, v132
	v_and_b32_e32 v131, 0xffff0000, v132
	v_fma_f32 v126, v90, v130, v126
	v_fma_f32 v127, v91, v131, v127
	v_exp_f32_e64 v90, -v92
	v_exp_f32_e64 v91, -v93
	v_lshlrev_b32_e32 v92, 16, v129
	v_and_b32_e32 v93, 0xffff0000, v129
	v_add_f32_e32 v90, 1.0, v90
	v_add_f32_e32 v91, 1.0, v91
	v_rcp_f32_e32 v90, v90
	v_rcp_f32_e32 v91, v91
	v_lshlrev_b32_e32 v128, 16, v133
	v_and_b32_e32 v129, 0xffff0000, v133
	v_fma_f32 v94, v94, v136, v134
	v_fma_f32 v95, v95, v137, v135
	v_fma_f32 v128, v90, v128, v92
	v_fma_f32 v129, v91, v129, v93
	v_cvt_pk_bf16_f32 v90, v94, v95
	v_cvt_pk_bf16_f32 v91, v96, v97
	v_cvt_pk_bf16_f32 v92, v126, v127
	v_cvt_pk_bf16_f32 v93, v128, v129
	global_store_dwordx4 v[124:125], v[90:93], off
	v_rcp_f32_e32 v67, v67
	v_exp_f32_e64 v64, -v64
	s_waitcnt vmcnt(6)
	v_lshlrev_b32_e32 v90, 16, v118
	v_and_b32_e32 v91, 0xffff0000, v118
	s_waitcnt vmcnt(5)
	v_lshlrev_b32_e32 v92, 16, v114
	v_and_b32_e32 v93, 0xffff0000, v114
	v_fma_f32 v86, v86, v92, v90
	v_fma_f32 v87, v87, v93, v91
	v_lshlrev_b32_e32 v90, 16, v119
	v_and_b32_e32 v91, 0xffff0000, v119
	v_lshlrev_b32_e32 v92, 16, v115
	v_and_b32_e32 v93, 0xffff0000, v115
	v_fma_f32 v88, v88, v92, v90
	v_fma_f32 v89, v89, v93, v91
	v_lshlrev_b32_e32 v90, 16, v120
	v_and_b32_e32 v91, 0xffff0000, v120
	v_lshlrev_b32_e32 v92, 16, v116
	v_and_b32_e32 v93, 0xffff0000, v116
	v_fma_f32 v90, v82, v92, v90
	v_fma_f32 v91, v83, v93, v91
	v_exp_f32_e64 v82, -v84
	v_exp_f32_e64 v83, -v85
	v_lshlrev_b32_e32 v84, 16, v121
	v_and_b32_e32 v85, 0xffff0000, v121
	v_add_f32_e32 v82, 1.0, v82
	v_add_f32_e32 v83, 1.0, v83
	v_rcp_f32_e32 v82, v82
	v_rcp_f32_e32 v83, v83
	v_lshlrev_b32_e32 v92, 16, v117
	v_and_b32_e32 v93, 0xffff0000, v117
	v_exp_f32_e64 v65, -v65
	v_fma_f32 v92, v82, v92, v84
	v_fma_f32 v93, v83, v93, v85
	v_cvt_pk_bf16_f32 v82, v86, v87
	v_cvt_pk_bf16_f32 v83, v88, v89
	v_cvt_pk_bf16_f32 v84, v90, v91
	v_cvt_pk_bf16_f32 v85, v92, v93
	global_store_dwordx4 v[124:125], v[82:85], off offset:256
	v_exp_f32_e64 v58, -v58
	v_exp_f32_e64 v59, -v59
	s_waitcnt vmcnt(5)
	v_lshlrev_b32_e32 v82, 16, v106
	v_and_b32_e32 v83, 0xffff0000, v106
	s_waitcnt vmcnt(4)
	v_lshlrev_b32_e32 v84, 16, v110
	v_and_b32_e32 v85, 0xffff0000, v110
	v_fma_f32 v78, v78, v84, v82
	v_fma_f32 v79, v79, v85, v83
	v_lshlrev_b32_e32 v82, 16, v107
	v_and_b32_e32 v83, 0xffff0000, v107
	v_lshlrev_b32_e32 v84, 16, v111
	v_and_b32_e32 v85, 0xffff0000, v111
	v_fma_f32 v80, v80, v84, v82
	v_fma_f32 v81, v81, v85, v83
	v_lshlrev_b32_e32 v82, 16, v108
	v_and_b32_e32 v83, 0xffff0000, v108
	v_lshlrev_b32_e32 v84, 16, v112
	v_and_b32_e32 v85, 0xffff0000, v112
	v_fma_f32 v82, v74, v84, v82
	v_fma_f32 v83, v75, v85, v83
	v_exp_f32_e64 v74, -v76
	v_exp_f32_e64 v75, -v77
	v_lshlrev_b32_e32 v76, 16, v109
	v_and_b32_e32 v77, 0xffff0000, v109
	v_add_f32_e32 v74, 1.0, v74
	v_add_f32_e32 v75, 1.0, v75
	v_rcp_f32_e32 v74, v74
	v_rcp_f32_e32 v75, v75
	v_lshlrev_b32_e32 v84, 16, v113
	v_and_b32_e32 v85, 0xffff0000, v113
	v_add_f32_e32 v64, 1.0, v64
	v_fma_f32 v84, v74, v84, v76
	v_fma_f32 v85, v75, v85, v77
	v_cvt_pk_bf16_f32 v74, v78, v79
	v_cvt_pk_bf16_f32 v75, v80, v81
	v_cvt_pk_bf16_f32 v76, v82, v83
	v_cvt_pk_bf16_f32 v77, v84, v85
	global_store_dwordx4 v[122:123], v[74:77], off
	v_add_f32_e32 v65, 1.0, v65
	v_rcp_f32_e32 v64, v64
	s_waitcnt vmcnt(4)
	v_lshlrev_b32_e32 v74, 16, v102
	v_and_b32_e32 v75, 0xffff0000, v102
	s_waitcnt vmcnt(3)
	v_lshlrev_b32_e32 v76, 16, v98
	v_and_b32_e32 v77, 0xffff0000, v98
	v_fma_f32 v70, v70, v76, v74
	v_fma_f32 v71, v71, v77, v75
	v_lshlrev_b32_e32 v74, 16, v103
	v_and_b32_e32 v75, 0xffff0000, v103
	v_lshlrev_b32_e32 v76, 16, v99
	v_and_b32_e32 v77, 0xffff0000, v99
	v_fma_f32 v72, v72, v76, v74
	v_fma_f32 v73, v73, v77, v75
	v_lshlrev_b32_e32 v74, 16, v104
	v_and_b32_e32 v75, 0xffff0000, v104
	v_lshlrev_b32_e32 v76, 16, v100
	v_and_b32_e32 v77, 0xffff0000, v100
	v_fma_f32 v74, v66, v76, v74
	v_fma_f32 v75, v67, v77, v75
	v_exp_f32_e64 v66, -v68
	v_exp_f32_e64 v67, -v69
	v_lshlrev_b32_e32 v68, 16, v105
	v_and_b32_e32 v69, 0xffff0000, v105
	v_add_f32_e32 v66, 1.0, v66
	v_add_f32_e32 v67, 1.0, v67
	v_rcp_f32_e32 v66, v66
	v_rcp_f32_e32 v67, v67
	v_lshlrev_b32_e32 v76, 16, v101
	v_and_b32_e32 v77, 0xffff0000, v101
	v_rcp_f32_e32 v65, v65
	v_fma_f32 v76, v66, v76, v68
	v_fma_f32 v77, v67, v77, v69
	v_cvt_pk_bf16_f32 v66, v70, v71
	v_cvt_pk_bf16_f32 v67, v72, v73
	v_cvt_pk_bf16_f32 v68, v74, v75
	v_cvt_pk_bf16_f32 v69, v76, v77
	global_store_dwordx4 v[122:123], v[66:69], off offset:256
	v_add_f32_e32 v58, 1.0, v58
	v_add_f32_e32 v59, 1.0, v59
	v_add_u32_e32 v66, 0x80, v174
	v_ashrrev_i32_e32 v67, 31, v66
	v_mad_i64_i32 v[68:69], s[4:5], v66, s16, v[178:179]
	v_lshl_add_u64 v[92:93], v[68:69], 0, v[176:177]
	v_lshlrev_b64 v[66:67], 11, v[66:67]
	global_load_dwordx4 v[94:97], v[92:93], off
	v_lshl_add_u64 v[66:67], s[92:93], 0, v[66:67]
	v_lshl_add_u64 v[66:67], v[66:67], 0, v[176:177]
	global_load_dwordx4 v[98:101], v[66:67], off
	global_load_dwordx4 v[86:89], v[92:93], off offset:256
	global_load_dwordx4 v[82:85], v[66:67], off offset:256
	v_add_u32_e32 v66, 0x90, v174
	v_ashrrev_i32_e32 v67, 31, v66
	v_mad_i64_i32 v[68:69], s[4:5], v66, s16, v[178:179]
	v_lshl_add_u64 v[90:91], v[68:69], 0, v[176:177]
	v_lshlrev_b64 v[66:67], 11, v[66:67]
; __device__ __forceinline__ unsigned pk2(float lo, float hi) { f32x2_t v = {lo, hi}; bf16x2_t b = __builtin_convertvector(v, bf16x2_t); return __builtin_bit_cast(unsigned, b); }
; __device__ __forceinline__ float bf_lo(unsigned w) { return __uint_as_float(w << 16); }
; __device__ __forceinline__ float bf_hi(unsigned w) { return __uint_as_float(w & 0xffff0000u); }
;     __device__ __forceinline__ void operator()(const f32x4 (&acc)[2][2][4][2], const pg8::Unit& u, int wr, int wc, int fr, int fq) const {
;     ...
;                 if (MODE != 0) {
; #pragma unroll
;                     for (int i = 0; i < 4; ++i) { const size_t row = (size_t)(row0 + ai * 128 + (2 * mh + (i >> 1)) * 16); const int co = col0 + (i & 1) * 128;
;                         cw[i] = *(const u32x4*)(O + row * ldc + co); if (MODE >= 3) xw[i] = *(const u32x4*)(X + row * ldx + co); }
;                 }
; #pragma unroll
;                 for (int i = 0; i < 4; ++i) {
;                     const int m = 2 * mh + (i >> 1), bj = i & 1;
;                     bf16_t* p = O + (size_t)(row0 + ai * 128 + m * 16) * ldc + col0 + bj * 128;
;                     const f32x4 v0 = acc[ai][bj][m][0], v1 = acc[ai][bj][m][1];
;                     float v[8] = {v0[0], v0[1], v0[2], v0[3], v1[0], v1[1], v1[2], v1[3]};
;                     if (MODE != 0) {
;                         float c[8] = {bf_lo(cw[i].x), bf_hi(cw[i].x), bf_lo(cw[i].y), bf_hi(cw[i].y), bf_lo(cw[i].z), bf_hi(cw[i].z), bf_lo(cw[i].w), bf_hi(cw[i].w)};
;                         if (MODE == 1) {
; #pragma unroll
;                             for (int e = 0; e < 8; ++e) v[e] = v[e] * sigm2(v[e]) * c[e];
;                         } else if (MODE == 2) {
; #pragma unroll
;                             for (int e = 0; e < 8; ++e) v[e] = sigm2(v[e]) * c[e];
;                         } else {
;                             float x[8] = {bf_lo(xw[i].x), bf_hi(xw[i].x), bf_lo(xw[i].y), bf_hi(xw[i].y), bf_lo(xw[i].z), bf_hi(xw[i].z), bf_lo(xw[i].w), bf_hi(xw[i].w)};
; #pragma unroll
;                             for (int e = 0; e < 8; ++e) v[e] = (MODE == 4 ? 0.f : c[e]) + sigm2(v[e]) * x[e];
;                         }
;                     }
;                     u32x4 w; w.x = pk2(v[0], v[1]); w.y = pk2(v[2], v[3]); w.z = pk2(v[4], v[5]); w.w = pk2(v[6], v[7]);
;                     *(u32x4*)p = w;
	global_load_dwordx4 v[74:77], v[90:91], off
	v_lshl_add_u64 v[66:67], s[92:93], 0, v[66:67]
	v_lshl_add_u64 v[66:67], v[66:67], 0, v[176:177]
	global_load_dwordx4 v[78:81], v[66:67], off
	global_load_dwordx4 v[70:73], v[90:91], off offset:256
	s_nop 0
	global_load_dwordx4 v[66:69], v[66:67], off offset:256
	v_rcp_f32_e32 v58, v58
	v_rcp_f32_e32 v59, v59
	v_exp_f32_e64 v62, -v62
	v_exp_f32_e64 v63, -v63
	v_exp_f32_e64 v54, -v54
	v_exp_f32_e64 v55, -v55
	v_add_f32_e32 v62, 1.0, v62
	v_add_f32_e32 v63, 1.0, v63
	v_exp_f32_e64 v56, -v56
	v_exp_f32_e64 v57, -v57
	v_rcp_f32_e32 v62, v62
	v_rcp_f32_e32 v63, v63
	v_exp_f32_e64 v50, -v50
	v_exp_f32_e64 v51, -v51
	v_add_f32_e32 v54, 1.0, v54
	v_add_f32_e32 v55, 1.0, v55
	v_rcp_f32_e32 v54, v54
	v_rcp_f32_e32 v55, v55
	v_add_f32_e32 v56, 1.0, v56
	v_add_f32_e32 v57, 1.0, v57
	v_rcp_f32_e32 v56, v56
	v_rcp_f32_e32 v57, v57
	v_add_f32_e32 v50, 1.0, v50
	v_add_f32_e32 v51, 1.0, v51
	v_rcp_f32_e32 v50, v50
	v_rcp_f32_e32 v51, v51
	v_exp_f32_e64 v46, -v46
	v_exp_f32_e64 v47, -v47
	v_exp_f32_e64 v48, -v48
	v_exp_f32_e64 v49, -v49
	v_exp_f32_e64 v42, -v42
	v_exp_f32_e64 v43, -v43
	v_add_f32_e32 v46, 1.0, v46
	v_add_f32_e32 v47, 1.0, v47
	v_rcp_f32_e32 v46, v46
	v_rcp_f32_e32 v47, v47
	v_add_f32_e32 v48, 1.0, v48
	v_add_f32_e32 v49, 1.0, v49
	v_rcp_f32_e32 v48, v48
	v_rcp_f32_e32 v49, v49
	v_add_f32_e32 v42, 1.0, v42
	v_add_f32_e32 v43, 1.0, v43
	v_rcp_f32_e32 v42, v42
	v_rcp_f32_e32 v43, v43
	v_exp_f32_e64 v38, -v38
	v_exp_f32_e64 v39, -v39
	v_exp_f32_e64 v40, -v40
	v_exp_f32_e64 v41, -v41
	v_exp_f32_e64 v34, -v34
	v_exp_f32_e64 v35, -v35
	v_add_f32_e32 v38, 1.0, v38
	v_add_f32_e32 v39, 1.0, v39
	v_rcp_f32_e32 v38, v38
	v_rcp_f32_e32 v39, v39
	v_add_f32_e32 v40, 1.0, v40
	v_add_f32_e32 v41, 1.0, v41
	v_rcp_f32_e32 v40, v40
	v_rcp_f32_e32 v41, v41
	v_add_f32_e32 v34, 1.0, v34
	v_add_f32_e32 v35, 1.0, v35
	v_rcp_f32_e32 v34, v34
	v_rcp_f32_e32 v35, v35
	v_exp_f32_e64 v32, -v32
	v_exp_f32_e64 v33, -v33
	v_exp_f32_e64 v26, -v26
	v_exp_f32_e64 v27, -v27
	s_waitcnt vmcnt(7)
	v_lshlrev_b32_e32 v102, 16, v94
	v_and_b32_e32 v103, 0xffff0000, v94
	s_waitcnt vmcnt(6)
	v_lshlrev_b32_e32 v104, 16, v98
	v_and_b32_e32 v105, 0xffff0000, v98
	v_lshlrev_b32_e32 v94, 16, v95
	v_and_b32_e32 v95, 0xffff0000, v95
	v_lshlrev_b32_e32 v98, 16, v99
	v_and_b32_e32 v99, 0xffff0000, v99
	v_fma_f32 v64, v64, v98, v94
	v_fma_f32 v65, v65, v99, v95
	v_lshlrev_b32_e32 v94, 16, v96
	v_and_b32_e32 v95, 0xffff0000, v96
	v_lshlrev_b32_e32 v98, 16, v100
	v_and_b32_e32 v99, 0xffff0000, v100
	v_fma_f32 v94, v58, v98, v94
	v_fma_f32 v95, v59, v99, v95
	v_exp_f32_e64 v58, -v60
	v_exp_f32_e64 v59, -v61
	v_lshlrev_b32_e32 v60, 16, v97
	v_and_b32_e32 v61, 0xffff0000, v97
	v_add_f32_e32 v58, 1.0, v58
	v_add_f32_e32 v59, 1.0, v59
	v_rcp_f32_e32 v58, v58
	v_rcp_f32_e32 v59, v59
	v_lshlrev_b32_e32 v96, 16, v101
	v_and_b32_e32 v97, 0xffff0000, v101
	v_fma_f32 v62, v62, v104, v102
	v_fma_f32 v63, v63, v105, v103
	v_fma_f32 v96, v58, v96, v60
	v_fma_f32 v97, v59, v97, v61
	v_cvt_pk_bf16_f32 v58, v62, v63
	v_cvt_pk_bf16_f32 v59, v64, v65
	v_cvt_pk_bf16_f32 v60, v94, v95
	v_cvt_pk_bf16_f32 v61, v96, v97
	global_store_dwordx4 v[92:93], v[58:61], off
	v_add_f32_e32 v32, 1.0, v32
	v_add_f32_e32 v33, 1.0, v33
	s_waitcnt vmcnt(6)
	v_lshlrev_b32_e32 v58, 16, v86
	v_and_b32_e32 v59, 0xffff0000, v86
	s_waitcnt vmcnt(5)
	v_lshlrev_b32_e32 v60, 16, v82
	v_and_b32_e32 v61, 0xffff0000, v82
	v_fma_f32 v54, v54, v60, v58
	v_fma_f32 v55, v55, v61, v59
	v_lshlrev_b32_e32 v58, 16, v87
	v_and_b32_e32 v59, 0xffff0000, v87
	v_lshlrev_b32_e32 v60, 16, v83
	v_and_b32_e32 v61, 0xffff0000, v83
	v_fma_f32 v56, v56, v60, v58
	v_fma_f32 v57, v57, v61, v59
	v_lshlrev_b32_e32 v58, 16, v88
	v_and_b32_e32 v59, 0xffff0000, v88
	v_lshlrev_b32_e32 v60, 16, v84
	v_and_b32_e32 v61, 0xffff0000, v84
	v_fma_f32 v58, v50, v60, v58
	v_fma_f32 v59, v51, v61, v59
	v_exp_f32_e64 v50, -v52
	v_exp_f32_e64 v51, -v53
	v_lshlrev_b32_e32 v52, 16, v89
	v_and_b32_e32 v53, 0xffff0000, v89
	v_add_f32_e32 v50, 1.0, v50
	v_add_f32_e32 v51, 1.0, v51
	v_rcp_f32_e32 v50, v50
	v_rcp_f32_e32 v51, v51
	v_lshlrev_b32_e32 v60, 16, v85
	v_and_b32_e32 v61, 0xffff0000, v85
	v_rcp_f32_e32 v32, v32
	v_fma_f32 v60, v50, v60, v52
	v_fma_f32 v61, v51, v61, v53
	v_cvt_pk_bf16_f32 v50, v54, v55
	v_cvt_pk_bf16_f32 v51, v56, v57
	v_cvt_pk_bf16_f32 v52, v58, v59
	v_cvt_pk_bf16_f32 v53, v60, v61
	global_store_dwordx4 v[92:93], v[50:53], off offset:256
	v_rcp_f32_e32 v33, v33
	v_add_f32_e32 v26, 1.0, v26
	s_waitcnt vmcnt(5)
	v_lshlrev_b32_e32 v50, 16, v74
	v_and_b32_e32 v51, 0xffff0000, v74
	s_waitcnt vmcnt(4)
	v_lshlrev_b32_e32 v52, 16, v78
	v_and_b32_e32 v53, 0xffff0000, v78
	v_fma_f32 v46, v46, v52, v50
	v_fma_f32 v47, v47, v53, v51
	v_lshlrev_b32_e32 v50, 16, v75
	v_and_b32_e32 v51, 0xffff0000, v75
	v_lshlrev_b32_e32 v52, 16, v79
	v_and_b32_e32 v53, 0xffff0000, v79
	v_fma_f32 v48, v48, v52, v50
	v_fma_f32 v49, v49, v53, v51
	v_lshlrev_b32_e32 v50, 16, v76
	v_and_b32_e32 v51, 0xffff0000, v76
	v_lshlrev_b32_e32 v52, 16, v80
	v_and_b32_e32 v53, 0xffff0000, v80
	v_fma_f32 v50, v42, v52, v50
	v_fma_f32 v51, v43, v53, v51
	v_exp_f32_e64 v42, -v44
	v_exp_f32_e64 v43, -v45
	v_lshlrev_b32_e32 v44, 16, v77
	v_and_b32_e32 v45, 0xffff0000, v77
	v_add_f32_e32 v42, 1.0, v42
	v_add_f32_e32 v43, 1.0, v43
	v_rcp_f32_e32 v42, v42
	v_rcp_f32_e32 v43, v43
	v_lshlrev_b32_e32 v52, 16, v81
	v_and_b32_e32 v53, 0xffff0000, v81
	v_add_f32_e32 v27, 1.0, v27
	v_fma_f32 v52, v42, v52, v44
	v_fma_f32 v53, v43, v53, v45
	v_cvt_pk_bf16_f32 v42, v46, v47
	v_cvt_pk_bf16_f32 v43, v48, v49
	v_cvt_pk_bf16_f32 v44, v50, v51
	v_cvt_pk_bf16_f32 v45, v52, v53
	global_store_dwordx4 v[90:91], v[42:45], off
	v_rcp_f32_e32 v26, v26
	v_rcp_f32_e32 v27, v27
	s_waitcnt vmcnt(4)
; __device__ __forceinline__ unsigned pk2(float lo, float hi) { f32x2_t v = {lo, hi}; bf16x2_t b = __builtin_convertvector(v, bf16x2_t); return __builtin_bit_cast(unsigned, b); }
; __device__ __forceinline__ float bf_lo(unsigned w) { return __uint_as_float(w << 16); }
;     __device__ __forceinline__ void operator()(const f32x4 (&acc)[2][2][4][2], const pg8::Unit& u, int wr, int wc, int fr, int fq) const {
;     ...
;                 if (MODE != 0) {
; #pragma unroll
;                     for (int i = 0; i < 4; ++i) { const size_t row = (size_t)(row0 + ai * 128 + (2 * mh + (i >> 1)) * 16); const int co = col0 + (i & 1) * 128;
;                         cw[i] = *(const u32x4*)(O + row * ldc + co); if (MODE >= 3) xw[i] = *(const u32x4*)(X + row * ldx + co); }
;                 }
; #pragma unroll
;                 for (int i = 0; i < 4; ++i) {
;                     const int m = 2 * mh + (i >> 1), bj = i & 1;
;                     bf16_t* p = O + (size_t)(row0 + ai * 128 + m * 16) * ldc + col0 + bj * 128;
;                     const f32x4 v0 = acc[ai][bj][m][0], v1 = acc[ai][bj][m][1];
;                     float v[8] = {v0[0], v0[1], v0[2], v0[3], v1[0], v1[1], v1[2], v1[3]};
;                     if (MODE != 0) {
;                         float c[8] = {bf_lo(cw[i].x), bf_hi(cw[i].x), bf_lo(cw[i].y), bf_hi(cw[i].y), bf_lo(cw[i].z), bf_hi(cw[i].z), bf_lo(cw[i].w), bf_hi(cw[i].w)};
;                         if (MODE == 1) {
; #pragma unroll
;                             for (int e = 0; e < 8; ++e) v[e] = v[e] * sigm2(v[e]) * c[e];
;                         } else if (MODE == 2) {
; #pragma unroll
;                             for (int e = 0; e < 8; ++e) v[e] = sigm2(v[e]) * c[e];
;                         } else {
;                             float x[8] = {bf_lo(xw[i].x), bf_hi(xw[i].x), bf_lo(xw[i].y), bf_hi(xw[i].y), bf_lo(xw[i].z), bf_hi(xw[i].z), bf_lo(xw[i].w), bf_hi(xw[i].w)};
; #pragma unroll
;                             for (int e = 0; e < 8; ++e) v[e] = (MODE == 4 ? 0.f : c[e]) + sigm2(v[e]) * x[e];
;                         }
;                     }
;                     u32x4 w; w.x = pk2(v[0], v[1]); w.y = pk2(v[2], v[3]); w.z = pk2(v[4], v[5]); w.w = pk2(v[6], v[7]);
;                     *(u32x4*)p = w;
;                 }
;                 asm volatile("" ::: "memory");
;             }
	v_lshlrev_b32_e32 v42, 16, v70
	v_and_b32_e32 v43, 0xffff0000, v70
	s_waitcnt vmcnt(3)
	v_lshlrev_b32_e32 v44, 16, v66
	v_and_b32_e32 v45, 0xffff0000, v66
	v_fma_f32 v38, v38, v44, v42
	v_fma_f32 v39, v39, v45, v43
	v_lshlrev_b32_e32 v42, 16, v71
	v_and_b32_e32 v43, 0xffff0000, v71
	v_lshlrev_b32_e32 v44, 16, v67
	v_and_b32_e32 v45, 0xffff0000, v67
	v_fma_f32 v40, v40, v44, v42
	v_fma_f32 v41, v41, v45, v43
	v_lshlrev_b32_e32 v42, 16, v72
	v_and_b32_e32 v43, 0xffff0000, v72
	v_lshlrev_b32_e32 v44, 16, v68
	v_and_b32_e32 v45, 0xffff0000, v68
	v_fma_f32 v42, v34, v44, v42
	v_fma_f32 v43, v35, v45, v43
	v_exp_f32_e64 v34, -v36
	v_exp_f32_e64 v35, -v37
	v_lshlrev_b32_e32 v36, 16, v73
	v_and_b32_e32 v37, 0xffff0000, v73
	v_add_f32_e32 v34, 1.0, v34
	v_add_f32_e32 v35, 1.0, v35
	v_rcp_f32_e32 v34, v34
	v_rcp_f32_e32 v35, v35
	v_lshlrev_b32_e32 v44, 16, v69
	v_and_b32_e32 v45, 0xffff0000, v69
	v_exp_f32_e64 v30, -v30
	v_fma_f32 v44, v34, v44, v36
	v_fma_f32 v45, v35, v45, v37
	v_cvt_pk_bf16_f32 v34, v38, v39
	v_cvt_pk_bf16_f32 v35, v40, v41
	v_cvt_pk_bf16_f32 v36, v42, v43
	v_cvt_pk_bf16_f32 v37, v44, v45
	global_store_dwordx4 v[90:91], v[34:37], off offset:256
	v_exp_f32_e64 v31, -v31
	v_exp_f32_e64 v22, -v22
	v_add_u32_e32 v34, 0xa0, v174
	v_ashrrev_i32_e32 v35, 31, v34
	v_mad_i64_i32 v[36:37], s[4:5], v34, s16, v[178:179]
	v_lshl_add_u64 v[60:61], v[36:37], 0, v[176:177]
	v_lshlrev_b64 v[34:35], 11, v[34:35]
	global_load_dwordx4 v[62:65], v[60:61], off
	v_lshl_add_u64 v[34:35], s[92:93], 0, v[34:35]
	v_lshl_add_u64 v[34:35], v[34:35], 0, v[176:177]
	global_load_dwordx4 v[66:69], v[34:35], off
	global_load_dwordx4 v[54:57], v[60:61], off offset:256
	global_load_dwordx4 v[50:53], v[34:35], off offset:256
	v_add_u32_e32 v34, 0xb0, v174
	v_ashrrev_i32_e32 v35, 31, v34
	v_mad_i64_i32 v[36:37], s[4:5], v34, s16, v[178:179]
	v_lshl_add_u64 v[58:59], v[36:37], 0, v[176:177]
	v_lshlrev_b64 v[34:35], 11, v[34:35]
	global_load_dwordx4 v[42:45], v[58:59], off
	v_lshl_add_u64 v[34:35], s[92:93], 0, v[34:35]
	v_lshl_add_u64 v[34:35], v[34:35], 0, v[176:177]
	global_load_dwordx4 v[46:49], v[34:35], off
	global_load_dwordx4 v[38:41], v[58:59], off offset:256
	s_nop 0
	global_load_dwordx4 v[34:37], v[34:35], off offset:256
	v_exp_f32_e64 v23, -v23
	v_add_f32_e32 v30, 1.0, v30
	v_add_f32_e32 v31, 1.0, v31
	v_exp_f32_e64 v24, -v24
	v_exp_f32_e64 v25, -v25
	v_rcp_f32_e32 v30, v30
	v_rcp_f32_e32 v31, v31
	v_exp_f32_e64 v18, -v18
	v_exp_f32_e64 v19, -v19
	v_add_f32_e32 v22, 1.0, v22
	v_add_f32_e32 v23, 1.0, v23
	v_rcp_f32_e32 v22, v22
	v_rcp_f32_e32 v23, v23
	v_add_f32_e32 v24, 1.0, v24
	v_add_f32_e32 v25, 1.0, v25
	v_rcp_f32_e32 v24, v24
	v_rcp_f32_e32 v25, v25
	v_add_f32_e32 v18, 1.0, v18
	v_add_f32_e32 v19, 1.0, v19
	v_rcp_f32_e32 v18, v18
	v_rcp_f32_e32 v19, v19
	v_exp_f32_e64 v14, -v14
	v_exp_f32_e64 v15, -v15
	v_exp_f32_e64 v16, -v16
	v_exp_f32_e64 v17, -v17
	v_exp_f32_e64 v10, -v10
	v_exp_f32_e64 v11, -v11
	v_add_f32_e32 v14, 1.0, v14
	v_add_f32_e32 v15, 1.0, v15
	v_rcp_f32_e32 v14, v14
	v_rcp_f32_e32 v15, v15
	v_add_f32_e32 v16, 1.0, v16
	v_add_f32_e32 v17, 1.0, v17
	v_rcp_f32_e32 v16, v16
	v_rcp_f32_e32 v17, v17
	v_add_f32_e32 v10, 1.0, v10
	v_add_f32_e32 v11, 1.0, v11
	v_rcp_f32_e32 v10, v10
	v_rcp_f32_e32 v11, v11
	v_exp_f32_e64 v6, -v6
	v_exp_f32_e64 v7, -v7
	v_exp_f32_e64 v8, -v8
	v_exp_f32_e64 v9, -v9
	v_exp_f32_e64 v2, -v2
	v_exp_f32_e64 v3, -v3
	v_add_f32_e32 v6, 1.0, v6
	v_add_f32_e32 v7, 1.0, v7
	v_rcp_f32_e32 v6, v6
	v_rcp_f32_e32 v7, v7
	v_add_f32_e32 v8, 1.0, v8
	v_add_f32_e32 v9, 1.0, v9
	v_rcp_f32_e32 v8, v8
	v_rcp_f32_e32 v9, v9
	v_add_f32_e32 v2, 1.0, v2
	v_add_f32_e32 v3, 1.0, v3
	v_rcp_f32_e32 v2, v2
	v_rcp_f32_e32 v3, v3
	s_mov_b64 s[4:5], -1
	s_andn2_b64 vcc, exec, s[38:39]
	s_mov_b32 s33, 0x10000
	s_waitcnt vmcnt(7)
	v_lshlrev_b32_e32 v70, 16, v62
	v_and_b32_e32 v71, 0xffff0000, v62
	s_waitcnt vmcnt(6)
; __device__ __forceinline__ unsigned pk2(float lo, float hi) { f32x2_t v = {lo, hi}; bf16x2_t b = __builtin_convertvector(v, bf16x2_t); return __builtin_bit_cast(unsigned, b); }
; __device__ __forceinline__ float bf_lo(unsigned w) { return __uint_as_float(w << 16); }
;     __device__ __forceinline__ void operator()(const f32x4 (&acc)[2][2][4][2], const pg8::Unit& u, int wr, int wc, int fr, int fq) const {
;     ...
;                 if (MODE != 0) {
; #pragma unroll
;                     for (int i = 0; i < 4; ++i) { const size_t row = (size_t)(row0 + ai * 128 + (2 * mh + (i >> 1)) * 16); const int co = col0 + (i & 1) * 128;
;                         cw[i] = *(const u32x4*)(O + row * ldc + co); if (MODE >= 3) xw[i] = *(const u32x4*)(X + row * ldx + co); }
;                 }
; #pragma unroll
;                 for (int i = 0; i < 4; ++i) {
;                     const int m = 2 * mh + (i >> 1), bj = i & 1;
;                     bf16_t* p = O + (size_t)(row0 + ai * 128 + m * 16) * ldc + col0 + bj * 128;
;                     const f32x4 v0 = acc[ai][bj][m][0], v1 = acc[ai][bj][m][1];
;                     float v[8] = {v0[0], v0[1], v0[2], v0[3], v1[0], v1[1], v1[2], v1[3]};
;                     if (MODE != 0) {
;                         float c[8] = {bf_lo(cw[i].x), bf_hi(cw[i].x), bf_lo(cw[i].y), bf_hi(cw[i].y), bf_lo(cw[i].z), bf_hi(cw[i].z), bf_lo(cw[i].w), bf_hi(cw[i].w)};
;                         if (MODE == 1) {
; #pragma unroll
;                             for (int e = 0; e < 8; ++e) v[e] = v[e] * sigm2(v[e]) * c[e];
;                         } else if (MODE == 2) {
; #pragma unroll
;                             for (int e = 0; e < 8; ++e) v[e] = sigm2(v[e]) * c[e];
;                         } else {
;                             float x[8] = {bf_lo(xw[i].x), bf_hi(xw[i].x), bf_lo(xw[i].y), bf_hi(xw[i].y), bf_lo(xw[i].z), bf_hi(xw[i].z), bf_lo(xw[i].w), bf_hi(xw[i].w)};
; #pragma unroll
;                             for (int e = 0; e < 8; ++e) v[e] = (MODE == 4 ? 0.f : c[e]) + sigm2(v[e]) * x[e];
;                         }
;                     }
;                     u32x4 w; w.x = pk2(v[0], v[1]); w.y = pk2(v[2], v[3]); w.z = pk2(v[4], v[5]); w.w = pk2(v[6], v[7]);
;                     *(u32x4*)p = w;
;                 }
;                 asm volatile("" ::: "memory");
;             }
	v_lshlrev_b32_e32 v72, 16, v66
	v_and_b32_e32 v73, 0xffff0000, v66
	v_lshlrev_b32_e32 v62, 16, v63
	v_and_b32_e32 v63, 0xffff0000, v63
	v_lshlrev_b32_e32 v66, 16, v67
	v_and_b32_e32 v67, 0xffff0000, v67
	v_fma_f32 v32, v32, v66, v62
	v_fma_f32 v33, v33, v67, v63
	v_lshlrev_b32_e32 v62, 16, v64
	v_and_b32_e32 v63, 0xffff0000, v64
	v_lshlrev_b32_e32 v66, 16, v68
	v_and_b32_e32 v67, 0xffff0000, v68
	v_fma_f32 v62, v26, v66, v62
	v_fma_f32 v63, v27, v67, v63
	v_exp_f32_e64 v26, -v28
	v_exp_f32_e64 v27, -v29
	v_lshlrev_b32_e32 v28, 16, v65
	v_and_b32_e32 v29, 0xffff0000, v65
	v_add_f32_e32 v26, 1.0, v26
	v_add_f32_e32 v27, 1.0, v27
	v_rcp_f32_e32 v26, v26
	v_rcp_f32_e32 v27, v27
	v_lshlrev_b32_e32 v64, 16, v69
	v_and_b32_e32 v65, 0xffff0000, v69
	v_fma_f32 v30, v30, v72, v70
	v_fma_f32 v31, v31, v73, v71
	v_fma_f32 v64, v26, v64, v28
	v_fma_f32 v65, v27, v65, v29
	v_cvt_pk_bf16_f32 v26, v30, v31
	v_cvt_pk_bf16_f32 v27, v32, v33
	v_cvt_pk_bf16_f32 v28, v62, v63
	v_cvt_pk_bf16_f32 v29, v64, v65
	global_store_dwordx4 v[60:61], v[26:29], off
	s_waitcnt vmcnt(6)
	s_nop 0
	v_lshlrev_b32_e32 v26, 16, v54
	v_and_b32_e32 v27, 0xffff0000, v54
	s_waitcnt vmcnt(5)
	v_lshlrev_b32_e32 v28, 16, v50
	v_and_b32_e32 v29, 0xffff0000, v50
	v_fma_f32 v22, v22, v28, v26
	v_fma_f32 v23, v23, v29, v27
	v_lshlrev_b32_e32 v26, 16, v55
	v_and_b32_e32 v27, 0xffff0000, v55
	v_lshlrev_b32_e32 v28, 16, v51
	v_and_b32_e32 v29, 0xffff0000, v51
	v_fma_f32 v24, v24, v28, v26
	v_fma_f32 v25, v25, v29, v27
	v_lshlrev_b32_e32 v26, 16, v56
	v_and_b32_e32 v27, 0xffff0000, v56
	v_lshlrev_b32_e32 v28, 16, v52
	v_and_b32_e32 v29, 0xffff0000, v52
	v_fma_f32 v26, v18, v28, v26
	v_fma_f32 v27, v19, v29, v27
	v_exp_f32_e64 v18, -v20
	v_exp_f32_e64 v19, -v21
	v_lshlrev_b32_e32 v20, 16, v57
	v_and_b32_e32 v21, 0xffff0000, v57
	v_add_f32_e32 v18, 1.0, v18
	v_add_f32_e32 v19, 1.0, v19
	v_rcp_f32_e32 v18, v18
	v_rcp_f32_e32 v19, v19
	v_lshlrev_b32_e32 v28, 16, v53
	v_and_b32_e32 v29, 0xffff0000, v53
	v_fma_f32 v28, v18, v28, v20
	v_fma_f32 v29, v19, v29, v21
	v_cvt_pk_bf16_f32 v18, v22, v23
	v_cvt_pk_bf16_f32 v19, v24, v25
	v_cvt_pk_bf16_f32 v20, v26, v27
	v_cvt_pk_bf16_f32 v21, v28, v29
	global_store_dwordx4 v[60:61], v[18:21], off offset:256
	s_waitcnt vmcnt(5)
	s_nop 0
	v_lshlrev_b32_e32 v18, 16, v42
	v_and_b32_e32 v19, 0xffff0000, v42
	s_waitcnt vmcnt(4)
	v_lshlrev_b32_e32 v20, 16, v46
	v_and_b32_e32 v21, 0xffff0000, v46
	v_fma_f32 v14, v14, v20, v18
	v_fma_f32 v15, v15, v21, v19
	v_lshlrev_b32_e32 v18, 16, v43
	v_and_b32_e32 v19, 0xffff0000, v43
	v_lshlrev_b32_e32 v20, 16, v47
	v_and_b32_e32 v21, 0xffff0000, v47
	v_fma_f32 v16, v16, v20, v18
	v_fma_f32 v17, v17, v21, v19
	v_lshlrev_b32_e32 v18, 16, v44
	v_and_b32_e32 v19, 0xffff0000, v44
	v_lshlrev_b32_e32 v20, 16, v48
	v_and_b32_e32 v21, 0xffff0000, v48
	v_fma_f32 v18, v10, v20, v18
	v_fma_f32 v19, v11, v21, v19
	v_exp_f32_e64 v10, -v12
	v_exp_f32_e64 v11, -v13
	v_lshlrev_b32_e32 v12, 16, v45
	v_and_b32_e32 v13, 0xffff0000, v45
	v_add_f32_e32 v10, 1.0, v10
	v_add_f32_e32 v11, 1.0, v11
	v_rcp_f32_e32 v10, v10
	v_rcp_f32_e32 v11, v11
	v_lshlrev_b32_e32 v20, 16, v49
	v_and_b32_e32 v21, 0xffff0000, v49
	v_fma_f32 v20, v10, v20, v12
	v_fma_f32 v21, v11, v21, v13
	v_cvt_pk_bf16_f32 v10, v14, v15
	v_cvt_pk_bf16_f32 v11, v16, v17
	v_cvt_pk_bf16_f32 v12, v18, v19
	v_cvt_pk_bf16_f32 v13, v20, v21
	global_store_dwordx4 v[58:59], v[10:13], off
	s_waitcnt vmcnt(4)
	s_nop 0
	v_lshlrev_b32_e32 v10, 16, v38
	v_and_b32_e32 v11, 0xffff0000, v38
	s_waitcnt vmcnt(3)
	v_lshlrev_b32_e32 v12, 16, v34
	v_and_b32_e32 v13, 0xffff0000, v34
	v_fma_f32 v6, v6, v12, v10
	v_fma_f32 v7, v7, v13, v11
	v_lshlrev_b32_e32 v10, 16, v39
	v_and_b32_e32 v11, 0xffff0000, v39
	v_lshlrev_b32_e32 v12, 16, v35
	v_and_b32_e32 v13, 0xffff0000, v35
	v_pk_fma_f32 v[8:9], v[8:9], v[12:13], v[10:11]
	v_lshlrev_b32_e32 v10, 16, v40
	v_and_b32_e32 v11, 0xffff0000, v40
	v_lshlrev_b32_e32 v12, 16, v36
	v_and_b32_e32 v13, 0xffff0000, v36
	v_pk_fma_f32 v[10:11], v[2:3], v[12:13], v[10:11]
	v_exp_f32_e64 v2, -v4
	v_exp_f32_e64 v3, -v5
	v_lshlrev_b32_e32 v4, 16, v41
	v_and_b32_e32 v5, 0xffff0000, v41
	v_add_f32_e32 v2, 1.0, v2
	v_add_f32_e32 v3, 1.0, v3
	v_rcp_f32_e32 v2, v2
	v_rcp_f32_e32 v3, v3
	v_lshlrev_b32_e32 v12, 16, v37
	v_and_b32_e32 v13, 0xffff0000, v37
	v_pk_fma_f32 v[12:13], v[2:3], v[12:13], v[4:5]
	v_cvt_pk_bf16_f32 v2, v6, v7
	v_cvt_pk_bf16_f32 v3, v8, v9
	v_cvt_pk_bf16_f32 v4, v10, v11
	v_cvt_pk_bf16_f32 v5, v12, v13
	global_store_dwordx4 v[58:59], v[2:5], off offset:256
	s_cbranch_vccnz .LBB0_1433
	s_andn2_b64 vcc, exec, s[36:37]
	s_cbranch_vccnz .LBB0_1432
	s_barrier
	s_branch .LBB0_1432

;     __device__ __forceinline__ void operator()(const f32x4 (&acc)[2][2][4][2], const pg8::Unit& u, int wr, int wc, int fr, int fq) const {
;         const bool lat = u.pm < 128; const int ms = lat ? (u.pm >> 5) : 4;
;         const size_t toff = (size_t)(lat ? u.pm : u.pm - 128) * 256 * DM;
;         const float* base = (lat ? bl : bc) + toff; float* out = (lat ? ol : oc) + toff;
;         const float* g = gate + ms * NMOD; const int col0 = u.pn * 256 + wc * 32 + 4 * fq;
; #pragma unroll
;         for (int bj = 0; bj < 2; ++bj)
; #pragma unroll
;             for (int n = 0; n < 2; ++n) {
;                 const f32x4 gv = *(const f32x4*)(g + col0 + bj * 128 + n * 16) * gs;
;                 f32x4 b[8];
; #pragma unroll
;                 for (int i = 0; i < 8; ++i) b[i] = *(const f32x4*)(base + (size_t)((i >> 2) * 128 + wr * 64 + (i & 3) * 16 + fr) * DM + col0 + bj * 128 + n * 16);
; #pragma unroll
;                 for (int i = 0; i < 8; ++i) *(f32x4*)(out + (size_t)((i >> 2) * 128 + wr * 64 + (i & 3) * 16 + fr) * DM + col0 + bj * 128 + n * 16) = b[i] + gv * acc[i >> 2][bj][i & 3][n];
;                 asm volatile("" ::: "memory");
;             }
.LBB0_1532:
	s_cmpk_lt_i32 s68, 0x80
	s_cselect_b32 s18, s85, s87
	s_cselect_b32 s19, s84, s86
	s_add_i32 s4, s68, 0xffffff80
	s_cmpk_lt_i32 s68, 0x80
	s_cselect_b32 s4, s68, s4
	s_lshr_b32 s5, s68, 5
	s_cmpk_lt_i32 s68, 0x80
	s_mulk_i32 s5, 0x2400
	s_cselect_b32 s6, s5, 0x9000
	s_ashr_i32 s5, s4, 31
	s_ashr_i32 s7, s6, 31
	s_lshl_b64 s[4:5], s[4:5], 20
	s_add_u32 s4, s19, s4
	v_lshl_or_b32 v158, s64, 8, v176
	s_addc_u32 s5, s18, s5
	s_lshl_b64 s[6:7], s[6:7], 2
	v_ashrrev_i32_e32 v159, 31, v158
	s_add_u32 s6, s25, s6
	v_lshlrev_b64 v[158:159], 2, v[158:159]
	s_addc_u32 s7, s26, s7
	v_lshl_add_u64 v[166:167], s[4:5], 0, v[158:159]
	v_lshl_add_u64 v[174:175], s[6:7], 0, v[158:159]
	v_lshl_add_u64 v[158:159], v[166:167], 0, v[138:139]
	global_load_dwordx4 v[178:181], v[174:175], off
	global_load_dwordx4 v[182:185], v[158:159], off
	v_lshl_add_u64 v[160:161], v[166:167], 0, v[140:141]
	v_lshl_add_u64 v[162:163], v[166:167], 0, v[142:143]
	v_lshl_add_u64 v[164:165], v[166:167], 0, v[144:145]
	v_lshl_add_u64 v[168:169], v[166:167], 0, v[146:147]
	v_lshl_add_u64 v[170:171], v[166:167], 0, v[148:149]
	v_lshl_add_u64 v[172:173], v[166:167], 0, v[150:151]
	v_lshl_add_u64 v[166:167], v[166:167], 0, v[152:153]
	global_load_dwordx4 v[186:189], v[160:161], off
	global_load_dwordx4 v[194:197], v[162:163], off
	global_load_dwordx4 v[198:201], v[164:165], off
	global_load_dwordx4 v[202:205], v[168:169], off
	global_load_dwordx4 v[224:227], v[166:167], off
	global_load_dwordx4 v[212:215], v[170:171], off
	global_load_dwordx4 v[220:223], v[172:173], off
	s_and_b64 vcc, exec, s[38:39]
	s_mov_b64 s[4:5], -1
	s_mov_b32 s33, 0x10000
	s_waitcnt vmcnt(0)
	v_fma_f32 v128, v128, v180, v184
	v_fma_f32 v129, v129, v181, v185
	v_fma_f32 v126, v126, v178, v182
	v_fma_f32 v127, v127, v179, v183
	v_fma_f32 v124, v124, v180, v188
	v_fma_f32 v125, v125, v181, v189
	v_fma_f32 v122, v122, v178, v186
	v_fma_f32 v123, v123, v179, v187
	v_fma_f32 v120, v120, v180, v196
	v_fma_f32 v121, v121, v181, v197
	v_fma_f32 v118, v118, v178, v194
	v_fma_f32 v119, v119, v179, v195
	v_fma_f32 v116, v116, v180, v200
	v_fma_f32 v117, v117, v181, v201
	v_fma_f32 v114, v114, v178, v198
	v_fma_f32 v115, v115, v179, v199
	v_fma_f32 v112, v112, v180, v204
	v_fma_f32 v113, v113, v181, v205
	v_fma_f32 v110, v110, v178, v202
	v_fma_f32 v111, v111, v179, v203
	v_fma_f32 v104, v104, v180, v214
	v_fma_f32 v105, v105, v181, v215
	v_fma_f32 v102, v102, v178, v212
	v_fma_f32 v103, v103, v179, v213
	v_fma_f32 v96, v96, v180, v222
	v_fma_f32 v97, v97, v181, v223
	v_fma_f32 v94, v94, v178, v220
	v_fma_f32 v95, v95, v179, v221
	v_fma_f32 v88, v88, v180, v226
	v_fma_f32 v89, v89, v181, v227
	v_fma_f32 v86, v86, v178, v224
	v_fma_f32 v87, v87, v179, v225
	global_store_dwordx4 v[158:159], v[126:129], off
	global_store_dwordx4 v[160:161], v[122:125], off
	global_store_dwordx4 v[162:163], v[118:121], off
	global_store_dwordx4 v[164:165], v[114:117], off
	global_store_dwordx4 v[168:169], v[110:113], off
	global_store_dwordx4 v[170:171], v[102:105], off
	global_store_dwordx4 v[172:173], v[94:97], off
	global_store_dwordx4 v[166:167], v[86:89], off
	global_load_dwordx4 v[86:89], v[174:175], off offset:64
	global_load_dwordx4 v[94:97], v[158:159], off offset:64
	global_load_dwordx4 v[102:105], v[160:161], off offset:64
	global_load_dwordx4 v[110:113], v[162:163], off offset:64
	global_load_dwordx4 v[114:117], v[164:165], off offset:64
	global_load_dwordx4 v[118:121], v[168:169], off offset:64
	global_load_dwordx4 v[122:125], v[170:171], off offset:64
	global_load_dwordx4 v[126:129], v[172:173], off offset:64
	global_load_dwordx4 v[178:181], v[166:167], off offset:64
	s_waitcnt vmcnt(7)
	v_fma_f32 v96, v108, v88, v96
	v_fma_f32 v97, v109, v89, v97
	v_fma_f32 v94, v106, v86, v94
	v_fma_f32 v95, v107, v87, v95
	s_waitcnt vmcnt(6)
	v_fma_f32 v100, v100, v88, v104
	v_fma_f32 v101, v101, v89, v105
	v_fma_f32 v98, v98, v86, v102
	v_fma_f32 v99, v99, v87, v103
	s_waitcnt vmcnt(5)
	v_fma_f32 v92, v92, v88, v112
	v_fma_f32 v93, v93, v89, v113
	v_fma_f32 v90, v90, v86, v110
	v_fma_f32 v91, v91, v87, v111
	s_waitcnt vmcnt(4)
	v_fma_f32 v84, v84, v88, v116
	v_fma_f32 v85, v85, v89, v117
	v_fma_f32 v82, v82, v86, v114
	v_fma_f32 v83, v83, v87, v115
	s_waitcnt vmcnt(3)
	v_fma_f32 v80, v80, v88, v120
	v_fma_f32 v81, v81, v89, v121
	v_fma_f32 v78, v78, v86, v118
	v_fma_f32 v79, v79, v87, v119
	s_waitcnt vmcnt(2)
	v_fma_f32 v76, v76, v88, v124
	v_fma_f32 v77, v77, v89, v125
	v_fma_f32 v74, v74, v86, v122
	v_fma_f32 v75, v75, v87, v123
	s_waitcnt vmcnt(1)
	v_fma_f32 v68, v68, v88, v128
	v_fma_f32 v69, v69, v89, v129
	v_fma_f32 v66, v66, v86, v126
	v_fma_f32 v67, v67, v87, v127
	s_waitcnt vmcnt(0)
;     __device__ __forceinline__ void operator()(const f32x4 (&acc)[2][2][4][2], const pg8::Unit& u, int wr, int wc, int fr, int fq) const {
;     ...
;         for (int bj = 0; bj < 2; ++bj)
; #pragma unroll
;             for (int n = 0; n < 2; ++n) {
;                 const f32x4 gv = *(const f32x4*)(g + col0 + bj * 128 + n * 16) * gs;
;                 f32x4 b[8];
; #pragma unroll
;                 for (int i = 0; i < 8; ++i) b[i] = *(const f32x4*)(base + (size_t)((i >> 2) * 128 + wr * 64 + (i & 3) * 16 + fr) * DM + col0 + bj * 128 + n * 16);
; #pragma unroll
;                 for (int i = 0; i < 8; ++i) *(f32x4*)(out + (size_t)((i >> 2) * 128 + wr * 64 + (i & 3) * 16 + fr) * DM + col0 + bj * 128 + n * 16) = b[i] + gv * acc[i >> 2][bj][i & 3][n];
;                 asm volatile("" ::: "memory");
;             }
	v_fma_f32 v60, v60, v88, v180
	v_fma_f32 v61, v61, v89, v181
	v_fma_f32 v58, v58, v86, v178
	v_fma_f32 v59, v59, v87, v179
	global_store_dwordx4 v[158:159], v[94:97], off offset:64
	global_store_dwordx4 v[160:161], v[98:101], off offset:64
	global_store_dwordx4 v[162:163], v[90:93], off offset:64
	global_store_dwordx4 v[164:165], v[82:85], off offset:64
	global_store_dwordx4 v[168:169], v[78:81], off offset:64
	global_store_dwordx4 v[170:171], v[74:77], off offset:64
	global_store_dwordx4 v[172:173], v[66:69], off offset:64
	global_store_dwordx4 v[166:167], v[58:61], off offset:64
	global_load_dwordx4 v[58:61], v[174:175], off offset:512
	global_load_dwordx4 v[66:69], v[158:159], off offset:512
	global_load_dwordx4 v[74:77], v[160:161], off offset:512
	global_load_dwordx4 v[78:81], v[162:163], off offset:512
	global_load_dwordx4 v[82:85], v[164:165], off offset:512
	global_load_dwordx4 v[86:89], v[168:169], off offset:512
	global_load_dwordx4 v[90:93], v[170:171], off offset:512
	global_load_dwordx4 v[94:97], v[172:173], off offset:512
	global_load_dwordx4 v[98:101], v[166:167], off offset:512
	s_waitcnt vmcnt(7)
	v_fma_f32 v68, v72, v60, v68
	v_fma_f32 v69, v73, v61, v69
	v_fma_f32 v66, v70, v58, v66
	v_fma_f32 v67, v71, v59, v67
	s_waitcnt vmcnt(6)
	v_fma_f32 v64, v64, v60, v76
	v_fma_f32 v65, v65, v61, v77
	v_fma_f32 v62, v62, v58, v74
	v_fma_f32 v63, v63, v59, v75
	s_waitcnt vmcnt(5)
	v_fma_f32 v56, v56, v60, v80
	v_fma_f32 v57, v57, v61, v81
	v_fma_f32 v54, v54, v58, v78
	v_fma_f32 v55, v55, v59, v79
	s_waitcnt vmcnt(4)
	v_fma_f32 v52, v52, v60, v84
	v_fma_f32 v53, v53, v61, v85
	v_fma_f32 v50, v50, v58, v82
	v_fma_f32 v51, v51, v59, v83
	s_waitcnt vmcnt(3)
	v_fma_f32 v48, v48, v60, v88
	v_fma_f32 v49, v49, v61, v89
	v_fma_f32 v46, v46, v58, v86
	v_fma_f32 v47, v47, v59, v87
	s_waitcnt vmcnt(2)
	v_fma_f32 v40, v40, v60, v92
	v_fma_f32 v41, v41, v61, v93
	v_fma_f32 v38, v38, v58, v90
	v_fma_f32 v39, v39, v59, v91
	s_waitcnt vmcnt(1)
	v_fma_f32 v32, v32, v60, v96
	v_fma_f32 v33, v33, v61, v97
	v_fma_f32 v30, v30, v58, v94
	v_fma_f32 v31, v31, v59, v95
	s_waitcnt vmcnt(0)
	v_fma_f32 v24, v24, v60, v100
	v_fma_f32 v25, v25, v61, v101
	v_fma_f32 v22, v22, v58, v98
	v_fma_f32 v23, v23, v59, v99
	global_store_dwordx4 v[158:159], v[66:69], off offset:512
	global_store_dwordx4 v[160:161], v[62:65], off offset:512
	global_store_dwordx4 v[162:163], v[54:57], off offset:512
	global_store_dwordx4 v[164:165], v[50:53], off offset:512
	global_store_dwordx4 v[168:169], v[46:49], off offset:512
	global_store_dwordx4 v[170:171], v[38:41], off offset:512
	global_store_dwordx4 v[172:173], v[30:33], off offset:512
	global_store_dwordx4 v[166:167], v[22:25], off offset:512
	global_load_dwordx4 v[22:25], v[174:175], off offset:576
	global_load_dwordx4 v[30:33], v[158:159], off offset:576
	global_load_dwordx4 v[38:41], v[160:161], off offset:576
	global_load_dwordx4 v[46:49], v[162:163], off offset:576
	global_load_dwordx4 v[50:53], v[164:165], off offset:576
	global_load_dwordx4 v[54:57], v[168:169], off offset:576
	global_load_dwordx4 v[58:61], v[170:171], off offset:576
	global_load_dwordx4 v[62:65], v[172:173], off offset:576
	global_load_dwordx4 v[66:69], v[166:167], off offset:576
	s_waitcnt vmcnt(7)
	v_fma_f32 v32, v44, v24, v32
	v_fma_f32 v33, v45, v25, v33
	v_fma_f32 v30, v42, v22, v30
	v_fma_f32 v31, v43, v23, v31
	s_waitcnt vmcnt(6)
	v_fma_f32 v36, v36, v24, v40
	v_fma_f32 v37, v37, v25, v41
	v_fma_f32 v34, v34, v22, v38
	v_fma_f32 v35, v35, v23, v39
	s_waitcnt vmcnt(5)
	v_fma_f32 v28, v28, v24, v48
	v_fma_f32 v29, v29, v25, v49
	v_fma_f32 v26, v26, v22, v46
	v_fma_f32 v27, v27, v23, v47
	s_waitcnt vmcnt(4)
	v_fma_f32 v20, v20, v24, v52
	v_fma_f32 v21, v21, v25, v53
	v_fma_f32 v18, v18, v22, v50
	v_fma_f32 v19, v19, v23, v51
	s_waitcnt vmcnt(3)
	v_fma_f32 v16, v16, v24, v56
	v_fma_f32 v17, v17, v25, v57
	v_fma_f32 v14, v14, v22, v54
	v_fma_f32 v15, v15, v23, v55
	s_waitcnt vmcnt(2)
	v_fma_f32 v12, v12, v24, v60
	v_fma_f32 v13, v13, v25, v61
	v_fma_f32 v10, v10, v22, v58
	v_fma_f32 v11, v11, v23, v59
	s_waitcnt vmcnt(1)
	v_fma_f32 v8, v8, v24, v64
	v_fma_f32 v9, v9, v25, v65
	v_fma_f32 v6, v6, v22, v62
	v_fma_f32 v7, v7, v23, v63
	s_waitcnt vmcnt(0)
	v_fma_f32 v4, v4, v24, v68
	v_fma_f32 v5, v5, v25, v69
	v_fma_f32 v2, v2, v22, v66
	v_fma_f32 v3, v3, v23, v67
	global_store_dwordx4 v[158:159], v[30:33], off offset:576
	global_store_dwordx4 v[160:161], v[34:37], off offset:576
	global_store_dwordx4 v[162:163], v[26:29], off offset:576
	global_store_dwordx4 v[164:165], v[18:21], off offset:576
	global_store_dwordx4 v[168:169], v[14:17], off offset:576
	global_store_dwordx4 v[170:171], v[10:13], off offset:576
	global_store_dwordx4 v[172:173], v[6:9], off offset:576
	global_store_dwordx4 v[166:167], v[2:5], off offset:576
	s_cbranch_vccnz .LBB0_1519
	s_andn2_b64 vcc, exec, s[36:37]
	s_cbranch_vccnz .LBB0_1518
	s_barrier
	s_branch .LBB0_1518

;     __device__ __forceinline__ void operator()(const f32x4 (&acc)[2][2][4][2], const pg8::Unit& u, int wr, int wc, int fr, int fq) const {
;         const bool lat = u.pm < 128; const int ms = lat ? (u.pm >> 5) : 4;
;         const size_t toff = (size_t)(lat ? u.pm : u.pm - 128) * 256 * DM;
;         const float* base = (lat ? bl : bc) + toff; float* out = (lat ? ol : oc) + toff;
;         const float* g = gate + ms * NMOD; const int col0 = u.pn * 256 + wc * 32 + 4 * fq;
; #pragma unroll
;         for (int bj = 0; bj < 2; ++bj)
; #pragma unroll
;             for (int n = 0; n < 2; ++n) {
;                 const f32x4 gv = *(const f32x4*)(g + col0 + bj * 128 + n * 16) * gs;
;                 f32x4 b[8];
; #pragma unroll
;                 for (int i = 0; i < 8; ++i) b[i] = *(const f32x4*)(base + (size_t)((i >> 2) * 128 + wr * 64 + (i & 3) * 16 + fr) * DM + col0 + bj * 128 + n * 16);
; #pragma unroll
;                 for (int i = 0; i < 8; ++i) *(f32x4*)(out + (size_t)((i >> 2) * 128 + wr * 64 + (i & 3) * 16 + fr) * DM + col0 + bj * 128 + n * 16) = b[i] + gv * acc[i >> 2][bj][i & 3][n];
;                 asm volatile("" ::: "memory");
;             }
.LBB0_1880:
	s_cmpk_lt_i32 s59, 0x80
	s_cselect_b32 s18, s85, s87
	s_cselect_b32 s19, s84, s86
	s_add_i32 s4, s59, 0xffffff80
	s_cmpk_lt_i32 s59, 0x80
	s_cselect_b32 s4, s59, s4
	s_lshr_b32 s5, s59, 5
	s_cmpk_lt_i32 s59, 0x80
	s_mulk_i32 s5, 0x2400
	s_cselect_b32 s6, s5, 0x9000
	s_ashr_i32 s5, s4, 31
	s_ashr_i32 s7, s6, 31
	s_lshl_b64 s[4:5], s[4:5], 20
	s_add_u32 s4, s19, s4
	s_addc_u32 s5, s18, s5
	s_lshl_b64 s[6:7], s[6:7], 2
	v_lshl_or_b32 v154, s51, 8, v172
	s_add_u32 s6, s24, s6
	v_ashrrev_i32_e32 v155, 31, v154
	s_addc_u32 s7, s25, s7
	v_lshlrev_b64 v[154:155], 2, v[154:155]
	v_lshl_add_u64 v[170:171], s[6:7], 0, v[154:155]
	v_lshl_add_u64 v[162:163], s[4:5], 0, v[154:155]
	global_load_dwordx4 v[174:177], v[170:171], off
	v_lshl_add_u64 v[154:155], v[162:163], 0, v[134:135]
	global_load_dwordx4 v[178:181], v[154:155], off
	v_lshl_add_u64 v[156:157], v[162:163], 0, v[136:137]
	v_lshl_add_u64 v[158:159], v[162:163], 0, v[138:139]
	v_lshl_add_u64 v[160:161], v[162:163], 0, v[140:141]
	v_lshl_add_u64 v[164:165], v[162:163], 0, v[142:143]
	v_lshl_add_u64 v[166:167], v[162:163], 0, v[144:145]
	v_lshl_add_u64 v[168:169], v[162:163], 0, v[146:147]
	v_lshl_add_u64 v[162:163], v[162:163], 0, v[148:149]
	global_load_dwordx4 v[182:185], v[156:157], off
	global_load_dwordx4 v[186:189], v[158:159], off
	global_load_dwordx4 v[194:197], v[160:161], off
	global_load_dwordx4 v[198:201], v[164:165], off
	global_load_dwordx4 v[220:223], v[162:163], off
	global_load_dwordx4 v[202:205], v[166:167], off
	global_load_dwordx4 v[212:215], v[168:169], off
	s_and_b64 vcc, exec, s[36:37]
	s_mov_b64 s[4:5], -1
	s_mov_b32 s64, s11
	s_mov_b32 s33, 0x10000
	s_waitcnt vmcnt(0)
	v_mul_f32_e32 v176, 0.5, v176
	v_mul_f32_e32 v177, 0.5, v177
	v_mul_f32_e32 v174, 0.5, v174
	v_mul_f32_e32 v175, 0.5, v175
	v_fma_f32 v128, v128, v176, v180
	v_fma_f32 v129, v129, v177, v181
	v_fma_f32 v126, v126, v174, v178
	v_fma_f32 v127, v127, v175, v179
	v_fma_f32 v124, v124, v176, v184
	v_fma_f32 v125, v125, v177, v185
	v_fma_f32 v122, v122, v174, v182
	v_fma_f32 v123, v123, v175, v183
	v_fma_f32 v120, v120, v176, v188
	v_fma_f32 v121, v121, v177, v189
	v_fma_f32 v118, v118, v174, v186
	v_fma_f32 v119, v119, v175, v187
	v_fma_f32 v116, v116, v176, v196
	v_fma_f32 v117, v117, v177, v197
	v_fma_f32 v114, v114, v174, v194
	v_fma_f32 v115, v115, v175, v195
	v_fma_f32 v112, v112, v176, v200
	v_fma_f32 v113, v113, v177, v201
	v_fma_f32 v110, v110, v174, v198
	v_fma_f32 v111, v111, v175, v199
	v_fma_f32 v104, v104, v176, v204
	v_fma_f32 v105, v105, v177, v205
	v_fma_f32 v102, v102, v174, v202
	v_fma_f32 v103, v103, v175, v203
	v_fma_f32 v96, v96, v176, v214
	v_fma_f32 v97, v97, v177, v215
	v_fma_f32 v94, v94, v174, v212
	v_fma_f32 v95, v95, v175, v213
	v_fma_f32 v88, v88, v176, v222
	v_fma_f32 v89, v89, v177, v223
	v_fma_f32 v86, v86, v174, v220
	v_fma_f32 v87, v87, v175, v221
	global_store_dwordx4 v[154:155], v[126:129], off
	global_store_dwordx4 v[156:157], v[122:125], off
	global_store_dwordx4 v[158:159], v[118:121], off
	global_store_dwordx4 v[160:161], v[114:117], off
	global_store_dwordx4 v[164:165], v[110:113], off
	global_store_dwordx4 v[166:167], v[102:105], off
	global_store_dwordx4 v[168:169], v[94:97], off
	global_store_dwordx4 v[162:163], v[86:89], off
	global_load_dwordx4 v[86:89], v[170:171], off offset:64
	global_load_dwordx4 v[94:97], v[154:155], off offset:64
	global_load_dwordx4 v[102:105], v[156:157], off offset:64
	global_load_dwordx4 v[110:113], v[158:159], off offset:64
	global_load_dwordx4 v[114:117], v[160:161], off offset:64
	global_load_dwordx4 v[118:121], v[164:165], off offset:64
	global_load_dwordx4 v[122:125], v[166:167], off offset:64
	global_load_dwordx4 v[126:129], v[168:169], off offset:64
	global_load_dwordx4 v[174:177], v[162:163], off offset:64
	s_waitcnt vmcnt(8)
	v_mul_f32_e32 v178, 0.5, v88
	v_mul_f32_e32 v179, 0.5, v89
	v_mul_f32_e32 v180, 0.5, v86
	v_mul_f32_e32 v181, 0.5, v87
	s_waitcnt vmcnt(7)
	v_fma_f32 v88, v108, v178, v96
	v_fma_f32 v89, v109, v179, v97
	v_fma_f32 v86, v106, v180, v94
	v_fma_f32 v87, v107, v181, v95
	s_waitcnt vmcnt(6)
	v_fma_f32 v96, v100, v178, v104
	v_fma_f32 v97, v101, v179, v105
	v_fma_f32 v94, v98, v180, v102
	v_fma_f32 v95, v99, v181, v103
	s_waitcnt vmcnt(5)
	v_fma_f32 v92, v92, v178, v112
	v_fma_f32 v93, v93, v179, v113
	v_fma_f32 v90, v90, v180, v110
	v_fma_f32 v91, v91, v181, v111
	s_waitcnt vmcnt(4)
	v_fma_f32 v84, v84, v178, v116
	v_fma_f32 v85, v85, v179, v117
	v_fma_f32 v82, v82, v180, v114
	v_fma_f32 v83, v83, v181, v115
	s_waitcnt vmcnt(3)
	v_fma_f32 v80, v80, v178, v120
	v_fma_f32 v81, v81, v179, v121
	v_fma_f32 v78, v78, v180, v118
	v_fma_f32 v79, v79, v181, v119
	s_waitcnt vmcnt(2)
	v_fma_f32 v76, v76, v178, v124
	v_fma_f32 v77, v77, v179, v125
	v_fma_f32 v74, v74, v180, v122
	v_fma_f32 v75, v75, v181, v123
	s_waitcnt vmcnt(1)
	v_fma_f32 v68, v68, v178, v128
	v_fma_f32 v69, v69, v179, v129
	v_fma_f32 v66, v66, v180, v126
	v_fma_f32 v67, v67, v181, v127
	s_waitcnt vmcnt(0)
;     __device__ __forceinline__ void operator()(const f32x4 (&acc)[2][2][4][2], const pg8::Unit& u, int wr, int wc, int fr, int fq) const {
;     ...
;         for (int bj = 0; bj < 2; ++bj)
; #pragma unroll
;             for (int n = 0; n < 2; ++n) {
;                 const f32x4 gv = *(const f32x4*)(g + col0 + bj * 128 + n * 16) * gs;
;                 f32x4 b[8];
; #pragma unroll
;                 for (int i = 0; i < 8; ++i) b[i] = *(const f32x4*)(base + (size_t)((i >> 2) * 128 + wr * 64 + (i & 3) * 16 + fr) * DM + col0 + bj * 128 + n * 16);
; #pragma unroll
;                 for (int i = 0; i < 8; ++i) *(f32x4*)(out + (size_t)((i >> 2) * 128 + wr * 64 + (i & 3) * 16 + fr) * DM + col0 + bj * 128 + n * 16) = b[i] + gv * acc[i >> 2][bj][i & 3][n];
;                 asm volatile("" ::: "memory");
;             }
	v_fma_f32 v60, v60, v178, v176
	v_fma_f32 v61, v61, v179, v177
	v_fma_f32 v58, v58, v180, v174
	v_fma_f32 v59, v59, v181, v175
	global_store_dwordx4 v[154:155], v[86:89], off offset:64
	global_store_dwordx4 v[156:157], v[94:97], off offset:64
	global_store_dwordx4 v[158:159], v[90:93], off offset:64
	global_store_dwordx4 v[160:161], v[82:85], off offset:64
	global_store_dwordx4 v[164:165], v[78:81], off offset:64
	global_store_dwordx4 v[166:167], v[74:77], off offset:64
	global_store_dwordx4 v[168:169], v[66:69], off offset:64
	global_store_dwordx4 v[162:163], v[58:61], off offset:64
	global_load_dwordx4 v[58:61], v[170:171], off offset:512
	global_load_dwordx4 v[66:69], v[154:155], off offset:512
	global_load_dwordx4 v[74:77], v[156:157], off offset:512
	global_load_dwordx4 v[78:81], v[158:159], off offset:512
	global_load_dwordx4 v[82:85], v[160:161], off offset:512
	global_load_dwordx4 v[86:89], v[164:165], off offset:512
	global_load_dwordx4 v[90:93], v[166:167], off offset:512
	global_load_dwordx4 v[94:97], v[168:169], off offset:512
	global_load_dwordx4 v[98:101], v[162:163], off offset:512
	s_waitcnt vmcnt(8)
	v_mul_f32_e32 v102, 0.5, v60
	v_mul_f32_e32 v103, 0.5, v61
	v_mul_f32_e32 v104, 0.5, v58
	v_mul_f32_e32 v105, 0.5, v59
	s_waitcnt vmcnt(7)
	v_fma_f32 v60, v72, v102, v68
	v_fma_f32 v61, v73, v103, v69
	v_fma_f32 v58, v70, v104, v66
	v_fma_f32 v59, v71, v105, v67
	s_waitcnt vmcnt(6)
	v_fma_f32 v64, v64, v102, v76
	v_fma_f32 v65, v65, v103, v77
	v_fma_f32 v62, v62, v104, v74
	v_fma_f32 v63, v63, v105, v75
	s_waitcnt vmcnt(5)
	v_fma_f32 v56, v56, v102, v80
	v_fma_f32 v57, v57, v103, v81
	v_fma_f32 v54, v54, v104, v78
	v_fma_f32 v55, v55, v105, v79
	s_waitcnt vmcnt(4)
	v_fma_f32 v52, v52, v102, v84
	v_fma_f32 v53, v53, v103, v85
	v_fma_f32 v50, v50, v104, v82
	v_fma_f32 v51, v51, v105, v83
	s_waitcnt vmcnt(3)
	v_fma_f32 v48, v48, v102, v88
	v_fma_f32 v49, v49, v103, v89
	v_fma_f32 v46, v46, v104, v86
	v_fma_f32 v47, v47, v105, v87
	s_waitcnt vmcnt(2)
	v_fma_f32 v40, v40, v102, v92
	v_fma_f32 v41, v41, v103, v93
	v_fma_f32 v38, v38, v104, v90
	v_fma_f32 v39, v39, v105, v91
	s_waitcnt vmcnt(1)
	v_fma_f32 v32, v32, v102, v96
	v_fma_f32 v33, v33, v103, v97
	v_fma_f32 v30, v30, v104, v94
	v_fma_f32 v31, v31, v105, v95
	s_waitcnt vmcnt(0)
	v_fma_f32 v24, v24, v102, v100
	v_fma_f32 v25, v25, v103, v101
	v_fma_f32 v22, v22, v104, v98
	v_fma_f32 v23, v23, v105, v99
	global_store_dwordx4 v[154:155], v[58:61], off offset:512
	global_store_dwordx4 v[156:157], v[62:65], off offset:512
	global_store_dwordx4 v[158:159], v[54:57], off offset:512
	global_store_dwordx4 v[160:161], v[50:53], off offset:512
	global_store_dwordx4 v[164:165], v[46:49], off offset:512
	global_store_dwordx4 v[166:167], v[38:41], off offset:512
	global_store_dwordx4 v[168:169], v[30:33], off offset:512
	global_store_dwordx4 v[162:163], v[22:25], off offset:512
	global_load_dwordx4 v[22:25], v[170:171], off offset:576
	global_load_dwordx4 v[30:33], v[154:155], off offset:576
	global_load_dwordx4 v[38:41], v[156:157], off offset:576
	global_load_dwordx4 v[46:49], v[158:159], off offset:576
	global_load_dwordx4 v[50:53], v[160:161], off offset:576
	global_load_dwordx4 v[54:57], v[164:165], off offset:576
	global_load_dwordx4 v[58:61], v[166:167], off offset:576
	global_load_dwordx4 v[62:65], v[168:169], off offset:576
	global_load_dwordx4 v[66:69], v[162:163], off offset:576
	s_waitcnt vmcnt(8)
	v_mul_f32_e32 v70, 0.5, v24
	v_mul_f32_e32 v71, 0.5, v25
	v_mul_f32_e32 v72, 0.5, v22
	v_mul_f32_e32 v73, 0.5, v23
	s_waitcnt vmcnt(7)
	v_fma_f32 v24, v44, v70, v32
	v_fma_f32 v25, v45, v71, v33
	v_fma_f32 v22, v42, v72, v30
	v_fma_f32 v23, v43, v73, v31
	s_waitcnt vmcnt(6)
	v_fma_f32 v32, v36, v70, v40
	v_fma_f32 v33, v37, v71, v41
	v_fma_f32 v30, v34, v72, v38
	v_fma_f32 v31, v35, v73, v39
	s_waitcnt vmcnt(5)
	v_fma_f32 v28, v28, v70, v48
	v_fma_f32 v29, v29, v71, v49
	v_fma_f32 v26, v26, v72, v46
	v_fma_f32 v27, v27, v73, v47
	s_waitcnt vmcnt(4)
	v_fma_f32 v20, v20, v70, v52
	v_fma_f32 v21, v21, v71, v53
	v_fma_f32 v18, v18, v72, v50
	v_fma_f32 v19, v19, v73, v51
	s_waitcnt vmcnt(3)
	v_fma_f32 v16, v16, v70, v56
	v_fma_f32 v17, v17, v71, v57
	v_fma_f32 v14, v14, v72, v54
	v_fma_f32 v15, v15, v73, v55
	s_waitcnt vmcnt(2)
	v_fma_f32 v12, v12, v70, v60
	v_fma_f32 v13, v13, v71, v61
	v_fma_f32 v10, v10, v72, v58
	v_fma_f32 v11, v11, v73, v59
	s_waitcnt vmcnt(1)
	v_fma_f32 v8, v8, v70, v64
	v_fma_f32 v9, v9, v71, v65
	v_fma_f32 v6, v6, v72, v62
	v_fma_f32 v7, v7, v73, v63
	s_waitcnt vmcnt(0)
	v_fma_f32 v4, v4, v70, v68
	v_fma_f32 v5, v5, v71, v69
	v_fma_f32 v2, v2, v72, v66
	v_fma_f32 v3, v3, v73, v67
	global_store_dwordx4 v[154:155], v[22:25], off offset:576
	global_store_dwordx4 v[156:157], v[30:33], off offset:576
	global_store_dwordx4 v[158:159], v[26:29], off offset:576
	global_store_dwordx4 v[160:161], v[18:21], off offset:576
	global_store_dwordx4 v[164:165], v[14:17], off offset:576
	global_store_dwordx4 v[166:167], v[10:13], off offset:576
	global_store_dwordx4 v[168:169], v[6:9], off offset:576
	global_store_dwordx4 v[162:163], v[2:5], off offset:576
	s_cbranch_vccnz .LBB0_1865
	s_andn2_b64 vcc, exec, s[40:41]
	s_cbranch_vccnz .LBB0_1864
	s_barrier
	s_branch .LBB0_1864
